# P1 in-projection epilogue split into three straight-line mode paths with repacked arithmetic (layers 1-3)
# baseline (speedup 1.0000x reference)
.LBB0_1071:
	s_cmp_lg_u32 s40, 2
	s_cselect_b64 s[46:47], -1, 0
	s_cmp_lt_u32 s40, 6
	s_cselect_b64 s[66:67], -1, 0
	s_and_b64 s[46:47], s[46:47], s[66:67]
	s_cmp_gt_u32 s40, 11
	s_cselect_b32 s0, 2, 0
	s_and_b64 s[46:47], s[46:47], exec
	s_cselect_b32 s0, 1, s0
	s_cmp_gt_i32 s40, 1
	s_cselect_b32 s61, s0, 1
	s_cmp_gt_i32 s61, 1
	s_cbranch_scc1 .Le1m2_10
	s_cmp_eq_u32 s61, 1
	s_cbranch_scc1 .Le1m1_10
	s_cmp_eq_u32 s36, s69
	s_movk_i32 s0, 0x200
	s_cselect_b32 s0, s0, 0x300
	s_cmp_lg_u32 s36, s68
	v_mov_b32_e32 v198, v193
	v_mov_b32_e32 v44, v192
	s_cselect_b32 s0, s0, 0x100
	s_cmp_lg_u32 s36, s35
	s_cselect_b32 s0, s0, 0
	v_lshl_add_u32 v45, v198, 5, s79
	v_add_u32_e32 v199, s70, v44
	ds_read_b128 v[68:71], v45
	ds_read_b128 v[60:63], v45 offset:16
	ds_read_b128 v[72:75], v45 offset:256
	ds_read_b128 v[64:67], v45 offset:272
	ds_read_b128 v[40:43], v45 offset:128
	ds_read_b128 v[32:35], v45 offset:144
	v_add_u32_e32 v44, s0, v199
	v_lshl_add_u32 v48, v44, 3, v197
	ds_read2_b64 v[172:175], v48 offset1:16
	ds_read_b128 v[56:59], v45 offset:384
	ds_read_b128 v[44:47], v45 offset:400
	ds_read2_b64 v[136:139], v48 offset0:32 offset1:48
	ds_read2_b64 v[100:103], v48 offset0:128 offset1:144
	ds_read2_b64 v[48:51], v48 offset0:160 offset1:176
	s_waitcnt lgkmcnt(0)
	s_cmp_gt_i32 s61, 1
	s_mov_b64 s[46:47], -1
	s_andn2_b64 vcc, exec, s[46:47]
	s_cmp_eq_u32 s61, 1
	s_add_i32 s0, s74, 0xfffff400
	s_lshl_b64 s[46:47], s[0:1], 1
	s_add_u32 s0, s56, s46
	s_addc_u32 s37, s57, s47
	s_ashr_i32 s75, s74, 31
	s_lshl_b64 s[46:47], s[74:75], 1
	s_add_u32 s46, s42, s46
	s_addc_u32 s47, s43, s47
	s_cmp_lt_i32 s40, 12
	s_cselect_b32 s0, s46, s0
	v_pk_fma_f32 v[200:201], v[68:69], v[172:173], v[72:73] op_sel:[0,1,0]
	v_pk_fma_f32 v[204:205], v[70:71], v[172:173], v[74:75] op_sel:[0,1,0]
	v_pk_fma_f32 v[206:207], v[60:61], v[172:173], v[64:65] op_sel:[0,1,0]
	v_pk_fma_f32 v[208:209], v[62:63], v[172:173], v[66:67] op_sel:[0,1,0]
	v_pk_fma_f32 v[200:201], v[168:169], v[172:173], v[200:201] op_sel_hi:[1,0,1]
	v_pk_fma_f32 v[204:205], v[170:171], v[172:173], v[204:205] op_sel_hi:[1,0,1]
	v_pk_fma_f32 v[206:207], v[164:165], v[172:173], v[206:207] op_sel_hi:[1,0,1]
	v_pk_fma_f32 v[208:209], v[166:167], v[172:173], v[208:209] op_sel_hi:[1,0,1]
	v_cvt_pk_bf16_f32 v216, v200, v201
	v_cvt_pk_bf16_f32 v217, v204, v205
	v_cvt_pk_bf16_f32 v218, v206, v207
	v_cvt_pk_bf16_f32 v219, v208, v209
	v_lshl_add_u32 v164, v198, 3, s71
	s_cselect_b32 s37, s47, s37
	v_mov_b32_e32 v166, s0
	s_movk_i32 s0, 0xc00
	v_mov_b32_e32 v167, s37
	s_cselect_b32 s0, s0, 0x800
	v_ashrrev_i32_e32 v165, 31, v164
	v_lshl_add_u32 v198, s36, 8, v199
	v_lshl_add_u64 v[164:165], v[164:165], 1, v[166:167]
	v_mad_i64_i32 v[166:167], s[36:37], s0, v198, 0
	v_lshl_add_u64 v[166:167], v[166:167], 1, v[164:165]
	s_cmp_gt_i32 s61, 1
	s_mov_b64 s[36:37], -1
	global_store_dwordx4 v[166:167], v[216:219], off
	s_andn2_b64 vcc, exec, s[36:37]
	s_cmp_eq_u32 s61, 1
	v_pk_fma_f32 v[200:201], v[40:41], v[172:173], v[56:57] op_sel:[0,1,0]
	v_pk_fma_f32 v[204:205], v[42:43], v[172:173], v[58:59] op_sel:[0,1,0]
	v_pk_fma_f32 v[206:207], v[32:33], v[172:173], v[44:45] op_sel:[0,1,0]
	v_pk_fma_f32 v[208:209], v[34:35], v[172:173], v[46:47] op_sel:[0,1,0]
	v_pk_fma_f32 v[200:201], v[160:161], v[172:173], v[200:201] op_sel_hi:[1,0,1]
	v_pk_fma_f32 v[204:205], v[162:163], v[172:173], v[204:205] op_sel_hi:[1,0,1]
	v_pk_fma_f32 v[206:207], v[156:157], v[172:173], v[206:207] op_sel_hi:[1,0,1]
	v_pk_fma_f32 v[208:209], v[158:159], v[172:173], v[208:209] op_sel_hi:[1,0,1]
	v_cvt_pk_bf16_f32 v220, v200, v201
	v_cvt_pk_bf16_f32 v221, v204, v205
	v_cvt_pk_bf16_f32 v222, v206, v207
	v_cvt_pk_bf16_f32 v223, v208, v209
	global_store_dwordx4 v[166:167], v[220:223], off offset:256
	s_cmp_gt_i32 s61, 1
	s_mov_b64 s[36:37], -1
	s_andn2_b64 vcc, exec, s[36:37]
	s_cmp_eq_u32 s61, 1
	v_pk_fma_f32 v[200:201], v[68:69], v[174:175], v[72:73] op_sel:[0,1,0]
	v_pk_fma_f32 v[204:205], v[70:71], v[174:175], v[74:75] op_sel:[0,1,0]
	v_pk_fma_f32 v[206:207], v[60:61], v[174:175], v[64:65] op_sel:[0,1,0]
	v_pk_fma_f32 v[208:209], v[62:63], v[174:175], v[66:67] op_sel:[0,1,0]
	v_pk_fma_f32 v[200:201], v[152:153], v[174:175], v[200:201] op_sel_hi:[1,0,1]
	v_pk_fma_f32 v[204:205], v[154:155], v[174:175], v[204:205] op_sel_hi:[1,0,1]
	v_pk_fma_f32 v[206:207], v[148:149], v[174:175], v[206:207] op_sel_hi:[1,0,1]
	v_pk_fma_f32 v[208:209], v[150:151], v[174:175], v[208:209] op_sel_hi:[1,0,1]
	v_cvt_pk_bf16_f32 v224, v200, v201
	v_cvt_pk_bf16_f32 v225, v204, v205
	v_cvt_pk_bf16_f32 v226, v206, v207
	v_cvt_pk_bf16_f32 v227, v208, v209
	v_add_u32_e32 v148, 16, v198
	v_mad_i64_i32 v[148:149], s[36:37], s0, v148, 0
	v_lshl_add_u64 v[148:149], v[148:149], 1, v[164:165]
	global_store_dwordx4 v[148:149], v[224:227], off
	s_cmp_gt_i32 s61, 1
	s_mov_b64 s[36:37], -1
	s_andn2_b64 vcc, exec, s[36:37]
	s_cmp_eq_u32 s61, 1
	v_pk_fma_f32 v[200:201], v[40:41], v[174:175], v[56:57] op_sel:[0,1,0]
	v_pk_fma_f32 v[204:205], v[42:43], v[174:175], v[58:59] op_sel:[0,1,0]
	v_pk_fma_f32 v[206:207], v[32:33], v[174:175], v[44:45] op_sel:[0,1,0]
	v_pk_fma_f32 v[208:209], v[34:35], v[174:175], v[46:47] op_sel:[0,1,0]
	v_pk_fma_f32 v[200:201], v[144:145], v[174:175], v[200:201] op_sel_hi:[1,0,1]
	v_pk_fma_f32 v[204:205], v[146:147], v[174:175], v[204:205] op_sel_hi:[1,0,1]
	v_pk_fma_f32 v[206:207], v[140:141], v[174:175], v[206:207] op_sel_hi:[1,0,1]
	v_pk_fma_f32 v[208:209], v[142:143], v[174:175], v[208:209] op_sel_hi:[1,0,1]
	v_cvt_pk_bf16_f32 v228, v200, v201
	v_cvt_pk_bf16_f32 v229, v204, v205
	v_cvt_pk_bf16_f32 v230, v206, v207
	v_cvt_pk_bf16_f32 v231, v208, v209
	global_store_dwordx4 v[148:149], v[228:231], off offset:256
	s_cmp_gt_i32 s61, 1
	s_mov_b64 s[36:37], -1
	s_andn2_b64 vcc, exec, s[36:37]
	s_cmp_eq_u32 s61, 1
	v_pk_fma_f32 v[200:201], v[68:69], v[136:137], v[72:73] op_sel:[0,1,0]
	v_pk_fma_f32 v[204:205], v[70:71], v[136:137], v[74:75] op_sel:[0,1,0]
	v_pk_fma_f32 v[206:207], v[60:61], v[136:137], v[64:65] op_sel:[0,1,0]
	v_pk_fma_f32 v[208:209], v[62:63], v[136:137], v[66:67] op_sel:[0,1,0]
	v_pk_fma_f32 v[200:201], v[132:133], v[136:137], v[200:201] op_sel_hi:[1,0,1]
	v_pk_fma_f32 v[204:205], v[134:135], v[136:137], v[204:205] op_sel_hi:[1,0,1]
	v_pk_fma_f32 v[206:207], v[128:129], v[136:137], v[206:207] op_sel_hi:[1,0,1]
	v_pk_fma_f32 v[208:209], v[130:131], v[136:137], v[208:209] op_sel_hi:[1,0,1]
	v_cvt_pk_bf16_f32 v232, v200, v201
	v_cvt_pk_bf16_f32 v233, v204, v205
	v_cvt_pk_bf16_f32 v234, v206, v207
	v_cvt_pk_bf16_f32 v235, v208, v209
	v_add_u32_e32 v128, 32, v198
	v_mad_i64_i32 v[128:129], s[36:37], s0, v128, 0
	v_lshl_add_u64 v[128:129], v[128:129], 1, v[164:165]
	s_cmp_gt_i32 s61, 1
	s_mov_b64 s[36:37], -1
	global_store_dwordx4 v[128:129], v[232:235], off
	s_andn2_b64 vcc, exec, s[36:37]
	s_cmp_eq_u32 s61, 1
	v_pk_fma_f32 v[200:201], v[40:41], v[136:137], v[56:57] op_sel:[0,1,0]
	v_pk_fma_f32 v[204:205], v[42:43], v[136:137], v[58:59] op_sel:[0,1,0]
	v_pk_fma_f32 v[206:207], v[32:33], v[136:137], v[44:45] op_sel:[0,1,0]
	v_pk_fma_f32 v[208:209], v[34:35], v[136:137], v[46:47] op_sel:[0,1,0]
	v_pk_fma_f32 v[200:201], v[124:125], v[136:137], v[200:201] op_sel_hi:[1,0,1]
	v_pk_fma_f32 v[204:205], v[126:127], v[136:137], v[204:205] op_sel_hi:[1,0,1]
	v_pk_fma_f32 v[206:207], v[120:121], v[136:137], v[206:207] op_sel_hi:[1,0,1]
	v_pk_fma_f32 v[208:209], v[122:123], v[136:137], v[208:209] op_sel_hi:[1,0,1]
	v_cvt_pk_bf16_f32 v236, v200, v201
	v_cvt_pk_bf16_f32 v237, v204, v205
	v_cvt_pk_bf16_f32 v238, v206, v207
	v_cvt_pk_bf16_f32 v239, v208, v209
	global_store_dwordx4 v[128:129], v[236:239], off offset:256
	s_cmp_gt_i32 s61, 1
	s_mov_b64 s[36:37], -1
	s_andn2_b64 vcc, exec, s[36:37]
	s_cmp_eq_u32 s61, 1
	v_pk_fma_f32 v[200:201], v[68:69], v[138:139], v[72:73] op_sel:[0,1,0]
	v_pk_fma_f32 v[204:205], v[70:71], v[138:139], v[74:75] op_sel:[0,1,0]
	v_pk_fma_f32 v[206:207], v[60:61], v[138:139], v[64:65] op_sel:[0,1,0]
	v_pk_fma_f32 v[208:209], v[62:63], v[138:139], v[66:67] op_sel:[0,1,0]
	v_pk_fma_f32 v[200:201], v[116:117], v[138:139], v[200:201] op_sel_hi:[1,0,1]
	v_pk_fma_f32 v[204:205], v[118:119], v[138:139], v[204:205] op_sel_hi:[1,0,1]
	v_pk_fma_f32 v[206:207], v[112:113], v[138:139], v[206:207] op_sel_hi:[1,0,1]
	v_pk_fma_f32 v[208:209], v[114:115], v[138:139], v[208:209] op_sel_hi:[1,0,1]
	v_cvt_pk_bf16_f32 v240, v200, v201
	v_cvt_pk_bf16_f32 v241, v204, v205
	v_cvt_pk_bf16_f32 v242, v206, v207
	v_cvt_pk_bf16_f32 v243, v208, v209
	v_add_u32_e32 v112, 48, v198
	v_mad_i64_i32 v[112:113], s[36:37], s0, v112, 0
	v_lshl_add_u64 v[112:113], v[112:113], 1, v[164:165]
	global_store_dwordx4 v[112:113], v[240:243], off
	s_cmp_gt_i32 s61, 1
	s_mov_b64 s[36:37], -1
	s_andn2_b64 vcc, exec, s[36:37]
	s_cmp_eq_u32 s61, 1
	v_pk_fma_f32 v[200:201], v[40:41], v[138:139], v[56:57] op_sel:[0,1,0]
	v_pk_fma_f32 v[204:205], v[42:43], v[138:139], v[58:59] op_sel:[0,1,0]
	v_pk_fma_f32 v[206:207], v[32:33], v[138:139], v[44:45] op_sel:[0,1,0]
	v_pk_fma_f32 v[208:209], v[34:35], v[138:139], v[46:47] op_sel:[0,1,0]
	v_pk_fma_f32 v[200:201], v[108:109], v[138:139], v[200:201] op_sel_hi:[1,0,1]
	v_pk_fma_f32 v[204:205], v[110:111], v[138:139], v[204:205] op_sel_hi:[1,0,1]
	v_pk_fma_f32 v[206:207], v[104:105], v[138:139], v[206:207] op_sel_hi:[1,0,1]
	v_pk_fma_f32 v[208:209], v[106:107], v[138:139], v[208:209] op_sel_hi:[1,0,1]
	v_cvt_pk_bf16_f32 v244, v200, v201
	v_cvt_pk_bf16_f32 v245, v204, v205
	v_cvt_pk_bf16_f32 v246, v206, v207
	v_cvt_pk_bf16_f32 v247, v208, v209
	global_store_dwordx4 v[112:113], v[244:247], off offset:256
	s_cmp_gt_i32 s61, 1
	s_mov_b64 s[36:37], -1
	s_andn2_b64 vcc, exec, s[36:37]
	s_cmp_eq_u32 s61, 1
	v_pk_fma_f32 v[200:201], v[68:69], v[100:101], v[72:73] op_sel:[0,1,0]
	v_pk_fma_f32 v[204:205], v[70:71], v[100:101], v[74:75] op_sel:[0,1,0]
	v_pk_fma_f32 v[206:207], v[60:61], v[100:101], v[64:65] op_sel:[0,1,0]
	v_pk_fma_f32 v[208:209], v[62:63], v[100:101], v[66:67] op_sel:[0,1,0]
	v_pk_fma_f32 v[200:201], v[96:97], v[100:101], v[200:201] op_sel_hi:[1,0,1]
	v_pk_fma_f32 v[204:205], v[98:99], v[100:101], v[204:205] op_sel_hi:[1,0,1]
	v_pk_fma_f32 v[206:207], v[92:93], v[100:101], v[206:207] op_sel_hi:[1,0,1]
	v_pk_fma_f32 v[208:209], v[94:95], v[100:101], v[208:209] op_sel_hi:[1,0,1]
	v_cvt_pk_bf16_f32 v248, v200, v201
	v_cvt_pk_bf16_f32 v249, v204, v205
	v_cvt_pk_bf16_f32 v250, v206, v207
	v_cvt_pk_bf16_f32 v251, v208, v209
	v_add_u32_e32 v92, 0x80, v198
	v_mad_i64_i32 v[92:93], s[36:37], s0, v92, 0
	v_lshl_add_u64 v[92:93], v[92:93], 1, v[164:165]
	s_cmp_gt_i32 s61, 1
	s_mov_b64 s[36:37], -1
	global_store_dwordx4 v[92:93], v[248:251], off
	s_andn2_b64 vcc, exec, s[36:37]
	s_cmp_eq_u32 s61, 1
	v_pk_fma_f32 v[200:201], v[40:41], v[100:101], v[56:57] op_sel:[0,1,0]
	v_pk_fma_f32 v[204:205], v[42:43], v[100:101], v[58:59] op_sel:[0,1,0]
	v_pk_fma_f32 v[206:207], v[32:33], v[100:101], v[44:45] op_sel:[0,1,0]
	v_pk_fma_f32 v[208:209], v[34:35], v[100:101], v[46:47] op_sel:[0,1,0]
	v_pk_fma_f32 v[200:201], v[88:89], v[100:101], v[200:201] op_sel_hi:[1,0,1]
	v_pk_fma_f32 v[204:205], v[90:91], v[100:101], v[204:205] op_sel_hi:[1,0,1]
	v_pk_fma_f32 v[206:207], v[84:85], v[100:101], v[206:207] op_sel_hi:[1,0,1]
	v_pk_fma_f32 v[208:209], v[86:87], v[100:101], v[208:209] op_sel_hi:[1,0,1]
	v_cvt_pk_bf16_f32 v216, v200, v201
	v_cvt_pk_bf16_f32 v217, v204, v205
	v_cvt_pk_bf16_f32 v218, v206, v207
	v_cvt_pk_bf16_f32 v219, v208, v209
	global_store_dwordx4 v[92:93], v[216:219], off offset:256
	s_cmp_gt_i32 s61, 1
	s_mov_b64 s[36:37], -1
	s_andn2_b64 vcc, exec, s[36:37]
	s_cmp_eq_u32 s61, 1
	v_pk_fma_f32 v[200:201], v[68:69], v[102:103], v[72:73] op_sel:[0,1,0]
	v_pk_fma_f32 v[204:205], v[70:71], v[102:103], v[74:75] op_sel:[0,1,0]
	v_pk_fma_f32 v[206:207], v[60:61], v[102:103], v[64:65] op_sel:[0,1,0]
	v_pk_fma_f32 v[208:209], v[62:63], v[102:103], v[66:67] op_sel:[0,1,0]
	v_pk_fma_f32 v[200:201], v[80:81], v[102:103], v[200:201] op_sel_hi:[1,0,1]
	v_pk_fma_f32 v[204:205], v[82:83], v[102:103], v[204:205] op_sel_hi:[1,0,1]
	v_pk_fma_f32 v[206:207], v[76:77], v[102:103], v[206:207] op_sel_hi:[1,0,1]
	v_pk_fma_f32 v[208:209], v[78:79], v[102:103], v[208:209] op_sel_hi:[1,0,1]
	v_cvt_pk_bf16_f32 v220, v200, v201
	v_cvt_pk_bf16_f32 v221, v204, v205
	v_cvt_pk_bf16_f32 v222, v206, v207
	v_cvt_pk_bf16_f32 v223, v208, v209
	v_add_u32_e32 v76, 0x90, v198
	v_mad_i64_i32 v[76:77], s[36:37], s0, v76, 0
	v_lshl_add_u64 v[76:77], v[76:77], 1, v[164:165]
	global_store_dwordx4 v[76:77], v[220:223], off
	s_cmp_gt_i32 s61, 1
	s_mov_b64 s[36:37], -1
	s_andn2_b64 vcc, exec, s[36:37]
	s_cmp_eq_u32 s61, 1
	v_pk_fma_f32 v[200:201], v[40:41], v[102:103], v[56:57] op_sel:[0,1,0]
	v_pk_fma_f32 v[204:205], v[42:43], v[102:103], v[58:59] op_sel:[0,1,0]
	v_pk_fma_f32 v[206:207], v[32:33], v[102:103], v[44:45] op_sel:[0,1,0]
	v_pk_fma_f32 v[208:209], v[34:35], v[102:103], v[46:47] op_sel:[0,1,0]
	v_pk_fma_f32 v[200:201], v[52:53], v[102:103], v[200:201] op_sel_hi:[1,0,1]
	v_pk_fma_f32 v[204:205], v[54:55], v[102:103], v[204:205] op_sel_hi:[1,0,1]
	v_pk_fma_f32 v[206:207], v[36:37], v[102:103], v[206:207] op_sel_hi:[1,0,1]
	v_pk_fma_f32 v[208:209], v[38:39], v[102:103], v[208:209] op_sel_hi:[1,0,1]
	v_cvt_pk_bf16_f32 v224, v200, v201
	v_cvt_pk_bf16_f32 v225, v204, v205
	v_cvt_pk_bf16_f32 v226, v206, v207
	v_cvt_pk_bf16_f32 v227, v208, v209
	global_store_dwordx4 v[76:77], v[224:227], off offset:256
	s_cmp_gt_i32 s61, 1
	s_mov_b64 s[36:37], -1
	s_andn2_b64 vcc, exec, s[36:37]
	s_cmp_eq_u32 s61, 1
	v_pk_fma_f32 v[200:201], v[68:69], v[48:49], v[72:73] op_sel:[0,1,0]
	v_pk_fma_f32 v[204:205], v[70:71], v[48:49], v[74:75] op_sel:[0,1,0]
	v_pk_fma_f32 v[206:207], v[60:61], v[48:49], v[64:65] op_sel:[0,1,0]
	v_pk_fma_f32 v[208:209], v[62:63], v[48:49], v[66:67] op_sel:[0,1,0]
	v_pk_fma_f32 v[200:201], v[28:29], v[48:49], v[200:201] op_sel_hi:[1,0,1]
	v_pk_fma_f32 v[204:205], v[30:31], v[48:49], v[204:205] op_sel_hi:[1,0,1]
	v_pk_fma_f32 v[206:207], v[24:25], v[48:49], v[206:207] op_sel_hi:[1,0,1]
	v_pk_fma_f32 v[208:209], v[26:27], v[48:49], v[208:209] op_sel_hi:[1,0,1]
	v_cvt_pk_bf16_f32 v228, v200, v201
	v_cvt_pk_bf16_f32 v229, v204, v205
	v_cvt_pk_bf16_f32 v230, v206, v207
	v_cvt_pk_bf16_f32 v231, v208, v209
	v_add_u32_e32 v24, 0xa0, v198
	v_mad_i64_i32 v[24:25], s[36:37], s0, v24, 0
	v_lshl_add_u64 v[24:25], v[24:25], 1, v[164:165]
	s_cmp_gt_i32 s61, 1
	s_mov_b64 s[36:37], -1
	global_store_dwordx4 v[24:25], v[228:231], off
	s_andn2_b64 vcc, exec, s[36:37]
	s_cmp_eq_u32 s61, 1
	v_pk_fma_f32 v[200:201], v[40:41], v[48:49], v[56:57] op_sel:[0,1,0]
	v_pk_fma_f32 v[204:205], v[42:43], v[48:49], v[58:59] op_sel:[0,1,0]
	v_pk_fma_f32 v[206:207], v[32:33], v[48:49], v[44:45] op_sel:[0,1,0]
	v_pk_fma_f32 v[208:209], v[34:35], v[48:49], v[46:47] op_sel:[0,1,0]
	v_pk_fma_f32 v[200:201], v[20:21], v[48:49], v[200:201] op_sel_hi:[1,0,1]
	v_pk_fma_f32 v[204:205], v[22:23], v[48:49], v[204:205] op_sel_hi:[1,0,1]
	v_pk_fma_f32 v[206:207], v[16:17], v[48:49], v[206:207] op_sel_hi:[1,0,1]
	v_pk_fma_f32 v[208:209], v[18:19], v[48:49], v[208:209] op_sel_hi:[1,0,1]
	v_cvt_pk_bf16_f32 v232, v200, v201
	v_cvt_pk_bf16_f32 v233, v204, v205
	v_cvt_pk_bf16_f32 v234, v206, v207
	v_cvt_pk_bf16_f32 v235, v208, v209
	global_store_dwordx4 v[24:25], v[232:235], off offset:256
	s_cmp_gt_i32 s61, 1
	s_mov_b64 s[36:37], -1
	s_andn2_b64 vcc, exec, s[36:37]
	s_cmp_eq_u32 s61, 1
	v_pk_fma_f32 v[200:201], v[68:69], v[50:51], v[72:73] op_sel:[0,1,0]
	v_pk_fma_f32 v[204:205], v[70:71], v[50:51], v[74:75] op_sel:[0,1,0]
	v_pk_fma_f32 v[206:207], v[60:61], v[50:51], v[64:65] op_sel:[0,1,0]
	v_pk_fma_f32 v[208:209], v[62:63], v[50:51], v[66:67] op_sel:[0,1,0]
	v_pk_fma_f32 v[200:201], v[12:13], v[50:51], v[200:201] op_sel_hi:[1,0,1]
	v_pk_fma_f32 v[204:205], v[14:15], v[50:51], v[204:205] op_sel_hi:[1,0,1]
	v_pk_fma_f32 v[206:207], v[8:9], v[50:51], v[206:207] op_sel_hi:[1,0,1]
	v_pk_fma_f32 v[208:209], v[10:11], v[50:51], v[208:209] op_sel_hi:[1,0,1]
	v_cvt_pk_bf16_f32 v236, v200, v201
	v_cvt_pk_bf16_f32 v237, v204, v205
	v_cvt_pk_bf16_f32 v238, v206, v207
	v_cvt_pk_bf16_f32 v239, v208, v209
	v_add_u32_e32 v8, 0xb0, v198
	v_mad_i64_i32 v[8:9], s[36:37], s0, v8, 0
	v_lshl_add_u64 v[8:9], v[8:9], 1, v[164:165]
	global_store_dwordx4 v[8:9], v[236:239], off
	s_cmp_gt_i32 s61, 1
	s_mov_b64 s[36:37], -1
	s_andn2_b64 vcc, exec, s[36:37]
	s_cmp_eq_u32 s61, 1
	s_andn2_b64 vcc, exec, s[8:9]
	s_mov_b64 s[8:9], -1
	v_pk_fma_f32 v[200:201], v[40:41], v[50:51], v[56:57] op_sel:[0,1,0]
	v_pk_fma_f32 v[204:205], v[42:43], v[50:51], v[58:59] op_sel:[0,1,0]
	v_pk_fma_f32 v[206:207], v[32:33], v[50:51], v[44:45] op_sel:[0,1,0]
	v_pk_fma_f32 v[208:209], v[34:35], v[50:51], v[46:47] op_sel:[0,1,0]
	v_pk_fma_f32 v[200:201], v[4:5], v[50:51], v[200:201] op_sel_hi:[1,0,1]
	v_pk_fma_f32 v[204:205], v[6:7], v[50:51], v[204:205] op_sel_hi:[1,0,1]
	v_pk_fma_f32 v[206:207], v[0:1], v[50:51], v[206:207] op_sel_hi:[1,0,1]
	v_pk_fma_f32 v[208:209], v[2:3], v[50:51], v[208:209] op_sel_hi:[1,0,1]
	v_cvt_pk_bf16_f32 v240, v200, v201
	v_cvt_pk_bf16_f32 v241, v204, v205
	v_cvt_pk_bf16_f32 v242, v206, v207
	v_cvt_pk_bf16_f32 v243, v208, v209
	global_store_dwordx4 v[8:9], v[240:243], off offset:256
	s_branch .Le1end_10
.Le1m1_10:
	s_cmp_eq_u32 s36, s69
	s_movk_i32 s0, 0x200
	s_cselect_b32 s0, s0, 0x300
	s_cmp_lg_u32 s36, s68
	v_mov_b32_e32 v198, v193
	v_mov_b32_e32 v44, v192
	s_cselect_b32 s0, s0, 0x100
	s_cmp_lg_u32 s36, s35
	s_cselect_b32 s0, s0, 0
	v_lshl_add_u32 v45, v198, 5, s79
	v_add_u32_e32 v199, s70, v44
	ds_read_b128 v[68:71], v45
	ds_read_b128 v[60:63], v45 offset:16
	ds_read_b128 v[72:75], v45 offset:256
	ds_read_b128 v[64:67], v45 offset:272
	ds_read_b128 v[40:43], v45 offset:128
	ds_read_b128 v[32:35], v45 offset:144
	v_add_u32_e32 v44, s0, v199
	v_lshl_add_u32 v48, v44, 3, v197
	ds_read2_b64 v[172:175], v48 offset1:16
	ds_read_b128 v[56:59], v45 offset:384
	ds_read_b128 v[44:47], v45 offset:400
	ds_read2_b64 v[136:139], v48 offset0:32 offset1:48
	ds_read2_b64 v[100:103], v48 offset0:128 offset1:144
	ds_read2_b64 v[48:51], v48 offset0:160 offset1:176
	s_waitcnt lgkmcnt(0)
	s_cmp_gt_i32 s61, 1
	s_mov_b64 s[46:47], -1
	s_andn2_b64 vcc, exec, s[46:47]
	s_cmp_eq_u32 s61, 1
	s_add_i32 s0, s74, 0xfffff400
	s_lshl_b64 s[46:47], s[0:1], 1
	s_add_u32 s0, s56, s46
	s_addc_u32 s37, s57, s47
	s_ashr_i32 s75, s74, 31
	s_lshl_b64 s[46:47], s[74:75], 1
	s_add_u32 s46, s42, s46
	s_addc_u32 s47, s43, s47
	s_cmp_lt_i32 s40, 12
	s_cselect_b32 s0, s46, s0
	v_pk_fma_f32 v[200:201], v[68:69], v[172:173], v[72:73] op_sel:[0,1,0]
	v_pk_fma_f32 v[204:205], v[70:71], v[172:173], v[74:75] op_sel:[0,1,0]
	v_pk_fma_f32 v[206:207], v[60:61], v[172:173], v[64:65] op_sel:[0,1,0]
	v_pk_fma_f32 v[208:209], v[62:63], v[172:173], v[66:67] op_sel:[0,1,0]
	v_pk_fma_f32 v[200:201], v[168:169], v[172:173], v[200:201] op_sel_hi:[1,0,1]
	v_pk_fma_f32 v[204:205], v[170:171], v[172:173], v[204:205] op_sel_hi:[1,0,1]
	v_pk_fma_f32 v[206:207], v[164:165], v[172:173], v[206:207] op_sel_hi:[1,0,1]
	v_pk_fma_f32 v[208:209], v[166:167], v[172:173], v[208:209] op_sel_hi:[1,0,1]
	v_pk_mul_f32 v[200:201], v[200:201], s[34:35] op_sel_hi:[1,0]
	v_pk_mul_f32 v[204:205], v[204:205], s[34:35] op_sel_hi:[1,0]
	v_pk_mul_f32 v[206:207], v[206:207], s[34:35] op_sel_hi:[1,0]
	v_pk_mul_f32 v[208:209], v[208:209], s[34:35] op_sel_hi:[1,0]
	v_cvt_pk_bf16_f32 v216, v200, v201
	v_cvt_pk_bf16_f32 v217, v204, v205
	v_cvt_pk_bf16_f32 v218, v206, v207
	v_cvt_pk_bf16_f32 v219, v208, v209
	v_lshl_add_u32 v164, v198, 3, s71
	s_cselect_b32 s37, s47, s37
	v_mov_b32_e32 v166, s0
	s_movk_i32 s0, 0xc00
	v_mov_b32_e32 v167, s37
	s_cselect_b32 s0, s0, 0x800
	v_ashrrev_i32_e32 v165, 31, v164
	v_lshl_add_u32 v198, s36, 8, v199
	v_lshl_add_u64 v[164:165], v[164:165], 1, v[166:167]
	v_mad_i64_i32 v[166:167], s[36:37], s0, v198, 0
	v_lshl_add_u64 v[166:167], v[166:167], 1, v[164:165]
	s_cmp_gt_i32 s61, 1
	s_mov_b64 s[36:37], -1
	global_store_dwordx4 v[166:167], v[216:219], off
	s_andn2_b64 vcc, exec, s[36:37]
	s_cmp_eq_u32 s61, 1
	v_pk_fma_f32 v[200:201], v[40:41], v[172:173], v[56:57] op_sel:[0,1,0]
	v_pk_fma_f32 v[204:205], v[42:43], v[172:173], v[58:59] op_sel:[0,1,0]
	v_pk_fma_f32 v[206:207], v[32:33], v[172:173], v[44:45] op_sel:[0,1,0]
	v_pk_fma_f32 v[208:209], v[34:35], v[172:173], v[46:47] op_sel:[0,1,0]
	v_pk_fma_f32 v[200:201], v[160:161], v[172:173], v[200:201] op_sel_hi:[1,0,1]
	v_pk_fma_f32 v[204:205], v[162:163], v[172:173], v[204:205] op_sel_hi:[1,0,1]
	v_pk_fma_f32 v[206:207], v[156:157], v[172:173], v[206:207] op_sel_hi:[1,0,1]
	v_pk_fma_f32 v[208:209], v[158:159], v[172:173], v[208:209] op_sel_hi:[1,0,1]
	v_pk_mul_f32 v[200:201], v[200:201], s[34:35] op_sel_hi:[1,0]
	v_pk_mul_f32 v[204:205], v[204:205], s[34:35] op_sel_hi:[1,0]
	v_pk_mul_f32 v[206:207], v[206:207], s[34:35] op_sel_hi:[1,0]
	v_pk_mul_f32 v[208:209], v[208:209], s[34:35] op_sel_hi:[1,0]
	v_cvt_pk_bf16_f32 v220, v200, v201
	v_cvt_pk_bf16_f32 v221, v204, v205
	v_cvt_pk_bf16_f32 v222, v206, v207
	v_cvt_pk_bf16_f32 v223, v208, v209
	global_store_dwordx4 v[166:167], v[220:223], off offset:256
	s_cmp_gt_i32 s61, 1
	s_mov_b64 s[36:37], -1
	s_andn2_b64 vcc, exec, s[36:37]
	s_cmp_eq_u32 s61, 1
	v_pk_fma_f32 v[200:201], v[68:69], v[174:175], v[72:73] op_sel:[0,1,0]
	v_pk_fma_f32 v[204:205], v[70:71], v[174:175], v[74:75] op_sel:[0,1,0]
	v_pk_fma_f32 v[206:207], v[60:61], v[174:175], v[64:65] op_sel:[0,1,0]
	v_pk_fma_f32 v[208:209], v[62:63], v[174:175], v[66:67] op_sel:[0,1,0]
	v_pk_fma_f32 v[200:201], v[152:153], v[174:175], v[200:201] op_sel_hi:[1,0,1]
	v_pk_fma_f32 v[204:205], v[154:155], v[174:175], v[204:205] op_sel_hi:[1,0,1]
	v_pk_fma_f32 v[206:207], v[148:149], v[174:175], v[206:207] op_sel_hi:[1,0,1]
	v_pk_fma_f32 v[208:209], v[150:151], v[174:175], v[208:209] op_sel_hi:[1,0,1]
	v_pk_mul_f32 v[200:201], v[200:201], s[34:35] op_sel_hi:[1,0]
	v_pk_mul_f32 v[204:205], v[204:205], s[34:35] op_sel_hi:[1,0]
	v_pk_mul_f32 v[206:207], v[206:207], s[34:35] op_sel_hi:[1,0]
	v_pk_mul_f32 v[208:209], v[208:209], s[34:35] op_sel_hi:[1,0]
	v_cvt_pk_bf16_f32 v224, v200, v201
	v_cvt_pk_bf16_f32 v225, v204, v205
	v_cvt_pk_bf16_f32 v226, v206, v207
	v_cvt_pk_bf16_f32 v227, v208, v209
	v_add_u32_e32 v148, 16, v198
	v_mad_i64_i32 v[148:149], s[36:37], s0, v148, 0
	v_lshl_add_u64 v[148:149], v[148:149], 1, v[164:165]
	global_store_dwordx4 v[148:149], v[224:227], off
	s_cmp_gt_i32 s61, 1
	s_mov_b64 s[36:37], -1
	s_andn2_b64 vcc, exec, s[36:37]
	s_cmp_eq_u32 s61, 1
	v_pk_fma_f32 v[200:201], v[40:41], v[174:175], v[56:57] op_sel:[0,1,0]
	v_pk_fma_f32 v[204:205], v[42:43], v[174:175], v[58:59] op_sel:[0,1,0]
	v_pk_fma_f32 v[206:207], v[32:33], v[174:175], v[44:45] op_sel:[0,1,0]
	v_pk_fma_f32 v[208:209], v[34:35], v[174:175], v[46:47] op_sel:[0,1,0]
	v_pk_fma_f32 v[200:201], v[144:145], v[174:175], v[200:201] op_sel_hi:[1,0,1]
	v_pk_fma_f32 v[204:205], v[146:147], v[174:175], v[204:205] op_sel_hi:[1,0,1]
	v_pk_fma_f32 v[206:207], v[140:141], v[174:175], v[206:207] op_sel_hi:[1,0,1]
	v_pk_fma_f32 v[208:209], v[142:143], v[174:175], v[208:209] op_sel_hi:[1,0,1]
	v_pk_mul_f32 v[200:201], v[200:201], s[34:35] op_sel_hi:[1,0]
	v_pk_mul_f32 v[204:205], v[204:205], s[34:35] op_sel_hi:[1,0]
	v_pk_mul_f32 v[206:207], v[206:207], s[34:35] op_sel_hi:[1,0]
	v_pk_mul_f32 v[208:209], v[208:209], s[34:35] op_sel_hi:[1,0]
	v_cvt_pk_bf16_f32 v228, v200, v201
	v_cvt_pk_bf16_f32 v229, v204, v205
	v_cvt_pk_bf16_f32 v230, v206, v207
	v_cvt_pk_bf16_f32 v231, v208, v209
	global_store_dwordx4 v[148:149], v[228:231], off offset:256
	s_cmp_gt_i32 s61, 1
	s_mov_b64 s[36:37], -1
	s_andn2_b64 vcc, exec, s[36:37]
	s_cmp_eq_u32 s61, 1
	v_pk_fma_f32 v[200:201], v[68:69], v[136:137], v[72:73] op_sel:[0,1,0]
	v_pk_fma_f32 v[204:205], v[70:71], v[136:137], v[74:75] op_sel:[0,1,0]
	v_pk_fma_f32 v[206:207], v[60:61], v[136:137], v[64:65] op_sel:[0,1,0]
	v_pk_fma_f32 v[208:209], v[62:63], v[136:137], v[66:67] op_sel:[0,1,0]
	v_pk_fma_f32 v[200:201], v[132:133], v[136:137], v[200:201] op_sel_hi:[1,0,1]
	v_pk_fma_f32 v[204:205], v[134:135], v[136:137], v[204:205] op_sel_hi:[1,0,1]
	v_pk_fma_f32 v[206:207], v[128:129], v[136:137], v[206:207] op_sel_hi:[1,0,1]
	v_pk_fma_f32 v[208:209], v[130:131], v[136:137], v[208:209] op_sel_hi:[1,0,1]
	v_pk_mul_f32 v[200:201], v[200:201], s[34:35] op_sel_hi:[1,0]
	v_pk_mul_f32 v[204:205], v[204:205], s[34:35] op_sel_hi:[1,0]
	v_pk_mul_f32 v[206:207], v[206:207], s[34:35] op_sel_hi:[1,0]
	v_pk_mul_f32 v[208:209], v[208:209], s[34:35] op_sel_hi:[1,0]
	v_cvt_pk_bf16_f32 v232, v200, v201
	v_cvt_pk_bf16_f32 v233, v204, v205
	v_cvt_pk_bf16_f32 v234, v206, v207
	v_cvt_pk_bf16_f32 v235, v208, v209
	v_add_u32_e32 v128, 32, v198
	v_mad_i64_i32 v[128:129], s[36:37], s0, v128, 0
	v_lshl_add_u64 v[128:129], v[128:129], 1, v[164:165]
	s_cmp_gt_i32 s61, 1
	s_mov_b64 s[36:37], -1
	global_store_dwordx4 v[128:129], v[232:235], off
	s_andn2_b64 vcc, exec, s[36:37]
	s_cmp_eq_u32 s61, 1
	v_pk_fma_f32 v[200:201], v[40:41], v[136:137], v[56:57] op_sel:[0,1,0]
	v_pk_fma_f32 v[204:205], v[42:43], v[136:137], v[58:59] op_sel:[0,1,0]
	v_pk_fma_f32 v[206:207], v[32:33], v[136:137], v[44:45] op_sel:[0,1,0]
	v_pk_fma_f32 v[208:209], v[34:35], v[136:137], v[46:47] op_sel:[0,1,0]
	v_pk_fma_f32 v[200:201], v[124:125], v[136:137], v[200:201] op_sel_hi:[1,0,1]
	v_pk_fma_f32 v[204:205], v[126:127], v[136:137], v[204:205] op_sel_hi:[1,0,1]
	v_pk_fma_f32 v[206:207], v[120:121], v[136:137], v[206:207] op_sel_hi:[1,0,1]
	v_pk_fma_f32 v[208:209], v[122:123], v[136:137], v[208:209] op_sel_hi:[1,0,1]
	v_pk_mul_f32 v[200:201], v[200:201], s[34:35] op_sel_hi:[1,0]
	v_pk_mul_f32 v[204:205], v[204:205], s[34:35] op_sel_hi:[1,0]
	v_pk_mul_f32 v[206:207], v[206:207], s[34:35] op_sel_hi:[1,0]
	v_pk_mul_f32 v[208:209], v[208:209], s[34:35] op_sel_hi:[1,0]
	v_cvt_pk_bf16_f32 v236, v200, v201
	v_cvt_pk_bf16_f32 v237, v204, v205
	v_cvt_pk_bf16_f32 v238, v206, v207
	v_cvt_pk_bf16_f32 v239, v208, v209
	global_store_dwordx4 v[128:129], v[236:239], off offset:256
	s_cmp_gt_i32 s61, 1
	s_mov_b64 s[36:37], -1
	s_andn2_b64 vcc, exec, s[36:37]
	s_cmp_eq_u32 s61, 1
	v_pk_fma_f32 v[200:201], v[68:69], v[138:139], v[72:73] op_sel:[0,1,0]
	v_pk_fma_f32 v[204:205], v[70:71], v[138:139], v[74:75] op_sel:[0,1,0]
	v_pk_fma_f32 v[206:207], v[60:61], v[138:139], v[64:65] op_sel:[0,1,0]
	v_pk_fma_f32 v[208:209], v[62:63], v[138:139], v[66:67] op_sel:[0,1,0]
	v_pk_fma_f32 v[200:201], v[116:117], v[138:139], v[200:201] op_sel_hi:[1,0,1]
	v_pk_fma_f32 v[204:205], v[118:119], v[138:139], v[204:205] op_sel_hi:[1,0,1]
	v_pk_fma_f32 v[206:207], v[112:113], v[138:139], v[206:207] op_sel_hi:[1,0,1]
	v_pk_fma_f32 v[208:209], v[114:115], v[138:139], v[208:209] op_sel_hi:[1,0,1]
	v_pk_mul_f32 v[200:201], v[200:201], s[34:35] op_sel_hi:[1,0]
	v_pk_mul_f32 v[204:205], v[204:205], s[34:35] op_sel_hi:[1,0]
	v_pk_mul_f32 v[206:207], v[206:207], s[34:35] op_sel_hi:[1,0]
	v_pk_mul_f32 v[208:209], v[208:209], s[34:35] op_sel_hi:[1,0]
	v_cvt_pk_bf16_f32 v240, v200, v201
	v_cvt_pk_bf16_f32 v241, v204, v205
	v_cvt_pk_bf16_f32 v242, v206, v207
	v_cvt_pk_bf16_f32 v243, v208, v209
	v_add_u32_e32 v112, 48, v198
	v_mad_i64_i32 v[112:113], s[36:37], s0, v112, 0
	v_lshl_add_u64 v[112:113], v[112:113], 1, v[164:165]
	global_store_dwordx4 v[112:113], v[240:243], off
	s_cmp_gt_i32 s61, 1
	s_mov_b64 s[36:37], -1
	s_andn2_b64 vcc, exec, s[36:37]
	s_cmp_eq_u32 s61, 1
	v_pk_fma_f32 v[200:201], v[40:41], v[138:139], v[56:57] op_sel:[0,1,0]
	v_pk_fma_f32 v[204:205], v[42:43], v[138:139], v[58:59] op_sel:[0,1,0]
	v_pk_fma_f32 v[206:207], v[32:33], v[138:139], v[44:45] op_sel:[0,1,0]
	v_pk_fma_f32 v[208:209], v[34:35], v[138:139], v[46:47] op_sel:[0,1,0]
	v_pk_fma_f32 v[200:201], v[108:109], v[138:139], v[200:201] op_sel_hi:[1,0,1]
	v_pk_fma_f32 v[204:205], v[110:111], v[138:139], v[204:205] op_sel_hi:[1,0,1]
	v_pk_fma_f32 v[206:207], v[104:105], v[138:139], v[206:207] op_sel_hi:[1,0,1]
	v_pk_fma_f32 v[208:209], v[106:107], v[138:139], v[208:209] op_sel_hi:[1,0,1]
	v_pk_mul_f32 v[200:201], v[200:201], s[34:35] op_sel_hi:[1,0]
	v_pk_mul_f32 v[204:205], v[204:205], s[34:35] op_sel_hi:[1,0]
	v_pk_mul_f32 v[206:207], v[206:207], s[34:35] op_sel_hi:[1,0]
	v_pk_mul_f32 v[208:209], v[208:209], s[34:35] op_sel_hi:[1,0]
	v_cvt_pk_bf16_f32 v244, v200, v201
	v_cvt_pk_bf16_f32 v245, v204, v205
	v_cvt_pk_bf16_f32 v246, v206, v207
	v_cvt_pk_bf16_f32 v247, v208, v209
	global_store_dwordx4 v[112:113], v[244:247], off offset:256
	s_cmp_gt_i32 s61, 1
	s_mov_b64 s[36:37], -1
	s_andn2_b64 vcc, exec, s[36:37]
	s_cmp_eq_u32 s61, 1
	v_pk_fma_f32 v[200:201], v[68:69], v[100:101], v[72:73] op_sel:[0,1,0]
	v_pk_fma_f32 v[204:205], v[70:71], v[100:101], v[74:75] op_sel:[0,1,0]
	v_pk_fma_f32 v[206:207], v[60:61], v[100:101], v[64:65] op_sel:[0,1,0]
	v_pk_fma_f32 v[208:209], v[62:63], v[100:101], v[66:67] op_sel:[0,1,0]
	v_pk_fma_f32 v[200:201], v[96:97], v[100:101], v[200:201] op_sel_hi:[1,0,1]
	v_pk_fma_f32 v[204:205], v[98:99], v[100:101], v[204:205] op_sel_hi:[1,0,1]
	v_pk_fma_f32 v[206:207], v[92:93], v[100:101], v[206:207] op_sel_hi:[1,0,1]
	v_pk_fma_f32 v[208:209], v[94:95], v[100:101], v[208:209] op_sel_hi:[1,0,1]
	v_pk_mul_f32 v[200:201], v[200:201], s[34:35] op_sel_hi:[1,0]
	v_pk_mul_f32 v[204:205], v[204:205], s[34:35] op_sel_hi:[1,0]
	v_pk_mul_f32 v[206:207], v[206:207], s[34:35] op_sel_hi:[1,0]
	v_pk_mul_f32 v[208:209], v[208:209], s[34:35] op_sel_hi:[1,0]
	v_cvt_pk_bf16_f32 v248, v200, v201
	v_cvt_pk_bf16_f32 v249, v204, v205
	v_cvt_pk_bf16_f32 v250, v206, v207
	v_cvt_pk_bf16_f32 v251, v208, v209
	v_add_u32_e32 v92, 0x80, v198
	v_mad_i64_i32 v[92:93], s[36:37], s0, v92, 0
	v_lshl_add_u64 v[92:93], v[92:93], 1, v[164:165]
	s_cmp_gt_i32 s61, 1
	s_mov_b64 s[36:37], -1
	global_store_dwordx4 v[92:93], v[248:251], off
	s_andn2_b64 vcc, exec, s[36:37]
	s_cmp_eq_u32 s61, 1
	v_pk_fma_f32 v[200:201], v[40:41], v[100:101], v[56:57] op_sel:[0,1,0]
	v_pk_fma_f32 v[204:205], v[42:43], v[100:101], v[58:59] op_sel:[0,1,0]
	v_pk_fma_f32 v[206:207], v[32:33], v[100:101], v[44:45] op_sel:[0,1,0]
	v_pk_fma_f32 v[208:209], v[34:35], v[100:101], v[46:47] op_sel:[0,1,0]
	v_pk_fma_f32 v[200:201], v[88:89], v[100:101], v[200:201] op_sel_hi:[1,0,1]
	v_pk_fma_f32 v[204:205], v[90:91], v[100:101], v[204:205] op_sel_hi:[1,0,1]
	v_pk_fma_f32 v[206:207], v[84:85], v[100:101], v[206:207] op_sel_hi:[1,0,1]
	v_pk_fma_f32 v[208:209], v[86:87], v[100:101], v[208:209] op_sel_hi:[1,0,1]
	v_pk_mul_f32 v[200:201], v[200:201], s[34:35] op_sel_hi:[1,0]
	v_pk_mul_f32 v[204:205], v[204:205], s[34:35] op_sel_hi:[1,0]
	v_pk_mul_f32 v[206:207], v[206:207], s[34:35] op_sel_hi:[1,0]
	v_pk_mul_f32 v[208:209], v[208:209], s[34:35] op_sel_hi:[1,0]
	v_cvt_pk_bf16_f32 v216, v200, v201
	v_cvt_pk_bf16_f32 v217, v204, v205
	v_cvt_pk_bf16_f32 v218, v206, v207
	v_cvt_pk_bf16_f32 v219, v208, v209
	global_store_dwordx4 v[92:93], v[216:219], off offset:256
	s_cmp_gt_i32 s61, 1
	s_mov_b64 s[36:37], -1
	s_andn2_b64 vcc, exec, s[36:37]
	s_cmp_eq_u32 s61, 1
	v_pk_fma_f32 v[200:201], v[68:69], v[102:103], v[72:73] op_sel:[0,1,0]
	v_pk_fma_f32 v[204:205], v[70:71], v[102:103], v[74:75] op_sel:[0,1,0]
	v_pk_fma_f32 v[206:207], v[60:61], v[102:103], v[64:65] op_sel:[0,1,0]
	v_pk_fma_f32 v[208:209], v[62:63], v[102:103], v[66:67] op_sel:[0,1,0]
	v_pk_fma_f32 v[200:201], v[80:81], v[102:103], v[200:201] op_sel_hi:[1,0,1]
	v_pk_fma_f32 v[204:205], v[82:83], v[102:103], v[204:205] op_sel_hi:[1,0,1]
	v_pk_fma_f32 v[206:207], v[76:77], v[102:103], v[206:207] op_sel_hi:[1,0,1]
	v_pk_fma_f32 v[208:209], v[78:79], v[102:103], v[208:209] op_sel_hi:[1,0,1]
	v_pk_mul_f32 v[200:201], v[200:201], s[34:35] op_sel_hi:[1,0]
	v_pk_mul_f32 v[204:205], v[204:205], s[34:35] op_sel_hi:[1,0]
	v_pk_mul_f32 v[206:207], v[206:207], s[34:35] op_sel_hi:[1,0]
	v_pk_mul_f32 v[208:209], v[208:209], s[34:35] op_sel_hi:[1,0]
	v_cvt_pk_bf16_f32 v220, v200, v201
	v_cvt_pk_bf16_f32 v221, v204, v205
	v_cvt_pk_bf16_f32 v222, v206, v207
	v_cvt_pk_bf16_f32 v223, v208, v209
	v_add_u32_e32 v76, 0x90, v198
	v_mad_i64_i32 v[76:77], s[36:37], s0, v76, 0
	v_lshl_add_u64 v[76:77], v[76:77], 1, v[164:165]
	global_store_dwordx4 v[76:77], v[220:223], off
	s_cmp_gt_i32 s61, 1
	s_mov_b64 s[36:37], -1
	s_andn2_b64 vcc, exec, s[36:37]
	s_cmp_eq_u32 s61, 1
	v_pk_fma_f32 v[200:201], v[40:41], v[102:103], v[56:57] op_sel:[0,1,0]
	v_pk_fma_f32 v[204:205], v[42:43], v[102:103], v[58:59] op_sel:[0,1,0]
	v_pk_fma_f32 v[206:207], v[32:33], v[102:103], v[44:45] op_sel:[0,1,0]
	v_pk_fma_f32 v[208:209], v[34:35], v[102:103], v[46:47] op_sel:[0,1,0]
	v_pk_fma_f32 v[200:201], v[52:53], v[102:103], v[200:201] op_sel_hi:[1,0,1]
	v_pk_fma_f32 v[204:205], v[54:55], v[102:103], v[204:205] op_sel_hi:[1,0,1]
	v_pk_fma_f32 v[206:207], v[36:37], v[102:103], v[206:207] op_sel_hi:[1,0,1]
	v_pk_fma_f32 v[208:209], v[38:39], v[102:103], v[208:209] op_sel_hi:[1,0,1]
	v_pk_mul_f32 v[200:201], v[200:201], s[34:35] op_sel_hi:[1,0]
	v_pk_mul_f32 v[204:205], v[204:205], s[34:35] op_sel_hi:[1,0]
	v_pk_mul_f32 v[206:207], v[206:207], s[34:35] op_sel_hi:[1,0]
	v_pk_mul_f32 v[208:209], v[208:209], s[34:35] op_sel_hi:[1,0]
	v_cvt_pk_bf16_f32 v224, v200, v201
	v_cvt_pk_bf16_f32 v225, v204, v205
	v_cvt_pk_bf16_f32 v226, v206, v207
	v_cvt_pk_bf16_f32 v227, v208, v209
	global_store_dwordx4 v[76:77], v[224:227], off offset:256
	s_cmp_gt_i32 s61, 1
	s_mov_b64 s[36:37], -1
	s_andn2_b64 vcc, exec, s[36:37]
	s_cmp_eq_u32 s61, 1
	v_pk_fma_f32 v[200:201], v[68:69], v[48:49], v[72:73] op_sel:[0,1,0]
	v_pk_fma_f32 v[204:205], v[70:71], v[48:49], v[74:75] op_sel:[0,1,0]
	v_pk_fma_f32 v[206:207], v[60:61], v[48:49], v[64:65] op_sel:[0,1,0]
	v_pk_fma_f32 v[208:209], v[62:63], v[48:49], v[66:67] op_sel:[0,1,0]
	v_pk_fma_f32 v[200:201], v[28:29], v[48:49], v[200:201] op_sel_hi:[1,0,1]
	v_pk_fma_f32 v[204:205], v[30:31], v[48:49], v[204:205] op_sel_hi:[1,0,1]
	v_pk_fma_f32 v[206:207], v[24:25], v[48:49], v[206:207] op_sel_hi:[1,0,1]
	v_pk_fma_f32 v[208:209], v[26:27], v[48:49], v[208:209] op_sel_hi:[1,0,1]
	v_pk_mul_f32 v[200:201], v[200:201], s[34:35] op_sel_hi:[1,0]
	v_pk_mul_f32 v[204:205], v[204:205], s[34:35] op_sel_hi:[1,0]
	v_pk_mul_f32 v[206:207], v[206:207], s[34:35] op_sel_hi:[1,0]
	v_pk_mul_f32 v[208:209], v[208:209], s[34:35] op_sel_hi:[1,0]
	v_cvt_pk_bf16_f32 v228, v200, v201
	v_cvt_pk_bf16_f32 v229, v204, v205
	v_cvt_pk_bf16_f32 v230, v206, v207
	v_cvt_pk_bf16_f32 v231, v208, v209
	v_add_u32_e32 v24, 0xa0, v198
	v_mad_i64_i32 v[24:25], s[36:37], s0, v24, 0
	v_lshl_add_u64 v[24:25], v[24:25], 1, v[164:165]
	s_cmp_gt_i32 s61, 1
	s_mov_b64 s[36:37], -1
	global_store_dwordx4 v[24:25], v[228:231], off
	s_andn2_b64 vcc, exec, s[36:37]
	s_cmp_eq_u32 s61, 1
	v_pk_fma_f32 v[200:201], v[40:41], v[48:49], v[56:57] op_sel:[0,1,0]
	v_pk_fma_f32 v[204:205], v[42:43], v[48:49], v[58:59] op_sel:[0,1,0]
	v_pk_fma_f32 v[206:207], v[32:33], v[48:49], v[44:45] op_sel:[0,1,0]
	v_pk_fma_f32 v[208:209], v[34:35], v[48:49], v[46:47] op_sel:[0,1,0]
	v_pk_fma_f32 v[200:201], v[20:21], v[48:49], v[200:201] op_sel_hi:[1,0,1]
	v_pk_fma_f32 v[204:205], v[22:23], v[48:49], v[204:205] op_sel_hi:[1,0,1]
	v_pk_fma_f32 v[206:207], v[16:17], v[48:49], v[206:207] op_sel_hi:[1,0,1]
	v_pk_fma_f32 v[208:209], v[18:19], v[48:49], v[208:209] op_sel_hi:[1,0,1]
	v_pk_mul_f32 v[200:201], v[200:201], s[34:35] op_sel_hi:[1,0]
	v_pk_mul_f32 v[204:205], v[204:205], s[34:35] op_sel_hi:[1,0]
	v_pk_mul_f32 v[206:207], v[206:207], s[34:35] op_sel_hi:[1,0]
	v_pk_mul_f32 v[208:209], v[208:209], s[34:35] op_sel_hi:[1,0]
	v_cvt_pk_bf16_f32 v232, v200, v201
	v_cvt_pk_bf16_f32 v233, v204, v205
	v_cvt_pk_bf16_f32 v234, v206, v207
	v_cvt_pk_bf16_f32 v235, v208, v209
	global_store_dwordx4 v[24:25], v[232:235], off offset:256
	s_cmp_gt_i32 s61, 1
	s_mov_b64 s[36:37], -1
	s_andn2_b64 vcc, exec, s[36:37]
	s_cmp_eq_u32 s61, 1
	v_pk_fma_f32 v[200:201], v[68:69], v[50:51], v[72:73] op_sel:[0,1,0]
	v_pk_fma_f32 v[204:205], v[70:71], v[50:51], v[74:75] op_sel:[0,1,0]
	v_pk_fma_f32 v[206:207], v[60:61], v[50:51], v[64:65] op_sel:[0,1,0]
	v_pk_fma_f32 v[208:209], v[62:63], v[50:51], v[66:67] op_sel:[0,1,0]
	v_pk_fma_f32 v[200:201], v[12:13], v[50:51], v[200:201] op_sel_hi:[1,0,1]
	v_pk_fma_f32 v[204:205], v[14:15], v[50:51], v[204:205] op_sel_hi:[1,0,1]
	v_pk_fma_f32 v[206:207], v[8:9], v[50:51], v[206:207] op_sel_hi:[1,0,1]
	v_pk_fma_f32 v[208:209], v[10:11], v[50:51], v[208:209] op_sel_hi:[1,0,1]
	v_pk_mul_f32 v[200:201], v[200:201], s[34:35] op_sel_hi:[1,0]
	v_pk_mul_f32 v[204:205], v[204:205], s[34:35] op_sel_hi:[1,0]
	v_pk_mul_f32 v[206:207], v[206:207], s[34:35] op_sel_hi:[1,0]
	v_pk_mul_f32 v[208:209], v[208:209], s[34:35] op_sel_hi:[1,0]
	v_cvt_pk_bf16_f32 v236, v200, v201
	v_cvt_pk_bf16_f32 v237, v204, v205
	v_cvt_pk_bf16_f32 v238, v206, v207
	v_cvt_pk_bf16_f32 v239, v208, v209
	v_add_u32_e32 v8, 0xb0, v198
	v_mad_i64_i32 v[8:9], s[36:37], s0, v8, 0
	v_lshl_add_u64 v[8:9], v[8:9], 1, v[164:165]
	global_store_dwordx4 v[8:9], v[236:239], off
	s_cmp_gt_i32 s61, 1
	s_mov_b64 s[36:37], -1
	s_andn2_b64 vcc, exec, s[36:37]
	s_cmp_eq_u32 s61, 1
	s_andn2_b64 vcc, exec, s[8:9]
	s_mov_b64 s[8:9], -1
	v_pk_fma_f32 v[200:201], v[40:41], v[50:51], v[56:57] op_sel:[0,1,0]
	v_pk_fma_f32 v[204:205], v[42:43], v[50:51], v[58:59] op_sel:[0,1,0]
	v_pk_fma_f32 v[206:207], v[32:33], v[50:51], v[44:45] op_sel:[0,1,0]
	v_pk_fma_f32 v[208:209], v[34:35], v[50:51], v[46:47] op_sel:[0,1,0]
	v_pk_fma_f32 v[200:201], v[4:5], v[50:51], v[200:201] op_sel_hi:[1,0,1]
	v_pk_fma_f32 v[204:205], v[6:7], v[50:51], v[204:205] op_sel_hi:[1,0,1]
	v_pk_fma_f32 v[206:207], v[0:1], v[50:51], v[206:207] op_sel_hi:[1,0,1]
	v_pk_fma_f32 v[208:209], v[2:3], v[50:51], v[208:209] op_sel_hi:[1,0,1]
	v_pk_mul_f32 v[200:201], v[200:201], s[34:35] op_sel_hi:[1,0]
	v_pk_mul_f32 v[204:205], v[204:205], s[34:35] op_sel_hi:[1,0]
	v_pk_mul_f32 v[206:207], v[206:207], s[34:35] op_sel_hi:[1,0]
	v_pk_mul_f32 v[208:209], v[208:209], s[34:35] op_sel_hi:[1,0]
	v_cvt_pk_bf16_f32 v240, v200, v201
	v_cvt_pk_bf16_f32 v241, v204, v205
	v_cvt_pk_bf16_f32 v242, v206, v207
	v_cvt_pk_bf16_f32 v243, v208, v209
	global_store_dwordx4 v[8:9], v[240:243], off offset:256
	s_branch .Le1end_10
.Le1m2_10:
	v_mov_b32_e32 v200, 0xbfb8aa3b
	v_mov_b32_e32 v201, 1.0
	s_cmp_eq_u32 s36, s69
	s_movk_i32 s0, 0x200
	s_cselect_b32 s0, s0, 0x300
	s_cmp_lg_u32 s36, s68
	v_mov_b32_e32 v198, v193
	v_mov_b32_e32 v44, v192
	s_cselect_b32 s0, s0, 0x100
	s_cmp_lg_u32 s36, s35
	s_cselect_b32 s0, s0, 0
	v_lshl_add_u32 v45, v198, 5, s79
	v_add_u32_e32 v199, s70, v44
	ds_read_b128 v[68:71], v45
	ds_read_b128 v[60:63], v45 offset:16
	ds_read_b128 v[72:75], v45 offset:256
	ds_read_b128 v[64:67], v45 offset:272
	ds_read_b128 v[40:43], v45 offset:128
	ds_read_b128 v[32:35], v45 offset:144
	v_add_u32_e32 v44, s0, v199
	v_lshl_add_u32 v48, v44, 3, v197
	ds_read2_b64 v[172:175], v48 offset1:16
	ds_read_b128 v[56:59], v45 offset:384
	ds_read_b128 v[44:47], v45 offset:400
	ds_read2_b64 v[136:139], v48 offset0:32 offset1:48
	ds_read2_b64 v[100:103], v48 offset0:128 offset1:144
	ds_read2_b64 v[48:51], v48 offset0:160 offset1:176
	s_waitcnt lgkmcnt(0)
	s_cmp_gt_i32 s61, 1
	s_mov_b64 s[46:47], -1
	s_mov_b64 s[46:47], 0
	s_andn2_b64 vcc, exec, s[46:47]
	s_add_i32 s0, s74, 0xfffff400
	s_lshl_b64 s[46:47], s[0:1], 1
	s_add_u32 s0, s56, s46
	s_addc_u32 s37, s57, s47
	s_ashr_i32 s75, s74, 31
	s_lshl_b64 s[46:47], s[74:75], 1
	s_add_u32 s46, s42, s46
	s_addc_u32 s47, s43, s47
	s_cmp_lt_i32 s40, 12
	s_cselect_b32 s0, s46, s0
	v_pk_fma_f32 v[204:205], v[68:69], v[172:173], v[72:73] op_sel:[0,1,0]
	v_pk_fma_f32 v[206:207], v[70:71], v[172:173], v[74:75] op_sel:[0,1,0]
	v_pk_fma_f32 v[208:209], v[60:61], v[172:173], v[64:65] op_sel:[0,1,0]
	v_pk_fma_f32 v[210:211], v[62:63], v[172:173], v[66:67] op_sel:[0,1,0]
	v_pk_fma_f32 v[204:205], v[168:169], v[172:173], v[204:205] op_sel_hi:[1,0,1]
	v_pk_fma_f32 v[206:207], v[170:171], v[172:173], v[206:207] op_sel_hi:[1,0,1]
	v_pk_fma_f32 v[208:209], v[164:165], v[172:173], v[208:209] op_sel_hi:[1,0,1]
	v_pk_fma_f32 v[210:211], v[166:167], v[172:173], v[210:211] op_sel_hi:[1,0,1]
	v_pk_mul_f32 v[216:217], v[204:205], v[200:201] op_sel_hi:[1,0]
	v_pk_mul_f32 v[218:219], v[206:207], v[200:201] op_sel_hi:[1,0]
	v_pk_mul_f32 v[220:221], v[208:209], v[200:201] op_sel_hi:[1,0]
	v_pk_mul_f32 v[222:223], v[210:211], v[200:201] op_sel_hi:[1,0]
	v_exp_f32_e32 v216, v216
	v_exp_f32_e32 v217, v217
	v_exp_f32_e32 v218, v218
	v_exp_f32_e32 v219, v219
	v_exp_f32_e32 v220, v220
	v_exp_f32_e32 v221, v221
	v_exp_f32_e32 v222, v222
	v_exp_f32_e32 v223, v223
	v_pk_add_f32 v[216:217], v[216:217], v[200:201] op_sel:[0,1] op_sel_hi:[1,1]
	v_pk_add_f32 v[218:219], v[218:219], v[200:201] op_sel:[0,1] op_sel_hi:[1,1]
	v_pk_add_f32 v[220:221], v[220:221], v[200:201] op_sel:[0,1] op_sel_hi:[1,1]
	v_pk_add_f32 v[222:223], v[222:223], v[200:201] op_sel:[0,1] op_sel_hi:[1,1]
	v_rcp_f32_e32 v216, v216
	v_rcp_f32_e32 v217, v217
	v_rcp_f32_e32 v218, v218
	v_rcp_f32_e32 v219, v219
	v_rcp_f32_e32 v220, v220
	v_rcp_f32_e32 v221, v221
	v_rcp_f32_e32 v222, v222
	v_rcp_f32_e32 v223, v223
	v_cvt_pk_bf16_f32 v224, v216, v217
	v_cvt_pk_bf16_f32 v225, v218, v219
	v_cvt_pk_bf16_f32 v226, v220, v221
	v_cvt_pk_bf16_f32 v227, v222, v223
	v_lshl_add_u32 v164, v198, 3, s71
	s_cselect_b32 s37, s47, s37
	v_mov_b32_e32 v166, s0
	s_movk_i32 s0, 0xc00
	v_mov_b32_e32 v167, s37
	s_cselect_b32 s0, s0, 0x800
	v_ashrrev_i32_e32 v165, 31, v164
	v_lshl_add_u32 v198, s36, 8, v199
	v_lshl_add_u64 v[164:165], v[164:165], 1, v[166:167]
	v_mad_i64_i32 v[166:167], s[36:37], s0, v198, 0
	v_lshl_add_u64 v[166:167], v[166:167], 1, v[164:165]
	s_cmp_gt_i32 s61, 1
	s_mov_b64 s[36:37], -1
	global_store_dwordx4 v[166:167], v[224:227], off
	s_mov_b64 s[36:37], 0
	s_andn2_b64 vcc, exec, s[36:37]
	v_pk_fma_f32 v[204:205], v[40:41], v[172:173], v[56:57] op_sel:[0,1,0]
	v_pk_fma_f32 v[206:207], v[42:43], v[172:173], v[58:59] op_sel:[0,1,0]
	v_pk_fma_f32 v[208:209], v[32:33], v[172:173], v[44:45] op_sel:[0,1,0]
	v_pk_fma_f32 v[210:211], v[34:35], v[172:173], v[46:47] op_sel:[0,1,0]
	v_pk_fma_f32 v[204:205], v[160:161], v[172:173], v[204:205] op_sel_hi:[1,0,1]
	v_pk_fma_f32 v[206:207], v[162:163], v[172:173], v[206:207] op_sel_hi:[1,0,1]
	v_pk_fma_f32 v[208:209], v[156:157], v[172:173], v[208:209] op_sel_hi:[1,0,1]
	v_pk_fma_f32 v[210:211], v[158:159], v[172:173], v[210:211] op_sel_hi:[1,0,1]
	v_pk_mul_f32 v[216:217], v[204:205], v[200:201] op_sel_hi:[1,0]
	v_pk_mul_f32 v[218:219], v[206:207], v[200:201] op_sel_hi:[1,0]
	v_pk_mul_f32 v[220:221], v[208:209], v[200:201] op_sel_hi:[1,0]
	v_pk_mul_f32 v[222:223], v[210:211], v[200:201] op_sel_hi:[1,0]
	v_exp_f32_e32 v216, v216
	v_exp_f32_e32 v217, v217
	v_exp_f32_e32 v218, v218
	v_exp_f32_e32 v219, v219
	v_exp_f32_e32 v220, v220
	v_exp_f32_e32 v221, v221
	v_exp_f32_e32 v222, v222
	v_exp_f32_e32 v223, v223
	v_pk_add_f32 v[216:217], v[216:217], v[200:201] op_sel:[0,1] op_sel_hi:[1,1]
	v_pk_add_f32 v[218:219], v[218:219], v[200:201] op_sel:[0,1] op_sel_hi:[1,1]
	v_pk_add_f32 v[220:221], v[220:221], v[200:201] op_sel:[0,1] op_sel_hi:[1,1]
	v_pk_add_f32 v[222:223], v[222:223], v[200:201] op_sel:[0,1] op_sel_hi:[1,1]
	v_rcp_f32_e32 v216, v216
	v_rcp_f32_e32 v217, v217
	v_rcp_f32_e32 v218, v218
	v_rcp_f32_e32 v219, v219
	v_rcp_f32_e32 v220, v220
	v_rcp_f32_e32 v221, v221
	v_rcp_f32_e32 v222, v222
	v_rcp_f32_e32 v223, v223
	v_cvt_pk_bf16_f32 v228, v216, v217
	v_cvt_pk_bf16_f32 v229, v218, v219
	v_cvt_pk_bf16_f32 v230, v220, v221
	v_cvt_pk_bf16_f32 v231, v222, v223
	global_store_dwordx4 v[166:167], v[228:231], off offset:256
	s_cmp_gt_i32 s61, 1
	s_mov_b64 s[36:37], -1
	s_mov_b64 s[36:37], 0
	s_andn2_b64 vcc, exec, s[36:37]
	v_pk_fma_f32 v[204:205], v[68:69], v[174:175], v[72:73] op_sel:[0,1,0]
	v_pk_fma_f32 v[206:207], v[70:71], v[174:175], v[74:75] op_sel:[0,1,0]
	v_pk_fma_f32 v[208:209], v[60:61], v[174:175], v[64:65] op_sel:[0,1,0]
	v_pk_fma_f32 v[210:211], v[62:63], v[174:175], v[66:67] op_sel:[0,1,0]
	v_pk_fma_f32 v[204:205], v[152:153], v[174:175], v[204:205] op_sel_hi:[1,0,1]
	v_pk_fma_f32 v[206:207], v[154:155], v[174:175], v[206:207] op_sel_hi:[1,0,1]
	v_pk_fma_f32 v[208:209], v[148:149], v[174:175], v[208:209] op_sel_hi:[1,0,1]
	v_pk_fma_f32 v[210:211], v[150:151], v[174:175], v[210:211] op_sel_hi:[1,0,1]
	v_pk_mul_f32 v[216:217], v[204:205], v[200:201] op_sel_hi:[1,0]
	v_pk_mul_f32 v[218:219], v[206:207], v[200:201] op_sel_hi:[1,0]
	v_pk_mul_f32 v[220:221], v[208:209], v[200:201] op_sel_hi:[1,0]
	v_pk_mul_f32 v[222:223], v[210:211], v[200:201] op_sel_hi:[1,0]
	v_exp_f32_e32 v216, v216
	v_exp_f32_e32 v217, v217
	v_exp_f32_e32 v218, v218
	v_exp_f32_e32 v219, v219
	v_exp_f32_e32 v220, v220
	v_exp_f32_e32 v221, v221
	v_exp_f32_e32 v222, v222
	v_exp_f32_e32 v223, v223
	v_pk_add_f32 v[216:217], v[216:217], v[200:201] op_sel:[0,1] op_sel_hi:[1,1]
	v_pk_add_f32 v[218:219], v[218:219], v[200:201] op_sel:[0,1] op_sel_hi:[1,1]
	v_pk_add_f32 v[220:221], v[220:221], v[200:201] op_sel:[0,1] op_sel_hi:[1,1]
	v_pk_add_f32 v[222:223], v[222:223], v[200:201] op_sel:[0,1] op_sel_hi:[1,1]
	v_rcp_f32_e32 v216, v216
	v_rcp_f32_e32 v217, v217
	v_rcp_f32_e32 v218, v218
	v_rcp_f32_e32 v219, v219
	v_rcp_f32_e32 v220, v220
	v_rcp_f32_e32 v221, v221
	v_rcp_f32_e32 v222, v222
	v_rcp_f32_e32 v223, v223
	v_cvt_pk_bf16_f32 v232, v216, v217
	v_cvt_pk_bf16_f32 v233, v218, v219
	v_cvt_pk_bf16_f32 v234, v220, v221
	v_cvt_pk_bf16_f32 v235, v222, v223
	v_add_u32_e32 v148, 16, v198
	v_mad_i64_i32 v[148:149], s[36:37], s0, v148, 0
	v_lshl_add_u64 v[148:149], v[148:149], 1, v[164:165]
	global_store_dwordx4 v[148:149], v[232:235], off
	s_cmp_gt_i32 s61, 1
	s_mov_b64 s[36:37], -1
	s_mov_b64 s[36:37], 0
	s_andn2_b64 vcc, exec, s[36:37]
	v_pk_fma_f32 v[204:205], v[40:41], v[174:175], v[56:57] op_sel:[0,1,0]
	v_pk_fma_f32 v[206:207], v[42:43], v[174:175], v[58:59] op_sel:[0,1,0]
	v_pk_fma_f32 v[208:209], v[32:33], v[174:175], v[44:45] op_sel:[0,1,0]
	v_pk_fma_f32 v[210:211], v[34:35], v[174:175], v[46:47] op_sel:[0,1,0]
	v_pk_fma_f32 v[204:205], v[144:145], v[174:175], v[204:205] op_sel_hi:[1,0,1]
	v_pk_fma_f32 v[206:207], v[146:147], v[174:175], v[206:207] op_sel_hi:[1,0,1]
	v_pk_fma_f32 v[208:209], v[140:141], v[174:175], v[208:209] op_sel_hi:[1,0,1]
	v_pk_fma_f32 v[210:211], v[142:143], v[174:175], v[210:211] op_sel_hi:[1,0,1]
	v_pk_mul_f32 v[216:217], v[204:205], v[200:201] op_sel_hi:[1,0]
	v_pk_mul_f32 v[218:219], v[206:207], v[200:201] op_sel_hi:[1,0]
	v_pk_mul_f32 v[220:221], v[208:209], v[200:201] op_sel_hi:[1,0]
	v_pk_mul_f32 v[222:223], v[210:211], v[200:201] op_sel_hi:[1,0]
	v_exp_f32_e32 v216, v216
	v_exp_f32_e32 v217, v217
	v_exp_f32_e32 v218, v218
	v_exp_f32_e32 v219, v219
	v_exp_f32_e32 v220, v220
	v_exp_f32_e32 v221, v221
	v_exp_f32_e32 v222, v222
	v_exp_f32_e32 v223, v223
	v_pk_add_f32 v[216:217], v[216:217], v[200:201] op_sel:[0,1] op_sel_hi:[1,1]
	v_pk_add_f32 v[218:219], v[218:219], v[200:201] op_sel:[0,1] op_sel_hi:[1,1]
	v_pk_add_f32 v[220:221], v[220:221], v[200:201] op_sel:[0,1] op_sel_hi:[1,1]
	v_pk_add_f32 v[222:223], v[222:223], v[200:201] op_sel:[0,1] op_sel_hi:[1,1]
	v_rcp_f32_e32 v216, v216
	v_rcp_f32_e32 v217, v217
	v_rcp_f32_e32 v218, v218
	v_rcp_f32_e32 v219, v219
	v_rcp_f32_e32 v220, v220
	v_rcp_f32_e32 v221, v221
	v_rcp_f32_e32 v222, v222
	v_rcp_f32_e32 v223, v223
	v_cvt_pk_bf16_f32 v236, v216, v217
	v_cvt_pk_bf16_f32 v237, v218, v219
	v_cvt_pk_bf16_f32 v238, v220, v221
	v_cvt_pk_bf16_f32 v239, v222, v223
	global_store_dwordx4 v[148:149], v[236:239], off offset:256
	s_cmp_gt_i32 s61, 1
	s_mov_b64 s[36:37], -1
	s_mov_b64 s[36:37], 0
	s_andn2_b64 vcc, exec, s[36:37]
	v_pk_fma_f32 v[204:205], v[68:69], v[136:137], v[72:73] op_sel:[0,1,0]
	v_pk_fma_f32 v[206:207], v[70:71], v[136:137], v[74:75] op_sel:[0,1,0]
	v_pk_fma_f32 v[208:209], v[60:61], v[136:137], v[64:65] op_sel:[0,1,0]
	v_pk_fma_f32 v[210:211], v[62:63], v[136:137], v[66:67] op_sel:[0,1,0]
	v_pk_fma_f32 v[204:205], v[132:133], v[136:137], v[204:205] op_sel_hi:[1,0,1]
	v_pk_fma_f32 v[206:207], v[134:135], v[136:137], v[206:207] op_sel_hi:[1,0,1]
	v_pk_fma_f32 v[208:209], v[128:129], v[136:137], v[208:209] op_sel_hi:[1,0,1]
	v_pk_fma_f32 v[210:211], v[130:131], v[136:137], v[210:211] op_sel_hi:[1,0,1]
	v_pk_mul_f32 v[216:217], v[204:205], v[200:201] op_sel_hi:[1,0]
	v_pk_mul_f32 v[218:219], v[206:207], v[200:201] op_sel_hi:[1,0]
	v_pk_mul_f32 v[220:221], v[208:209], v[200:201] op_sel_hi:[1,0]
	v_pk_mul_f32 v[222:223], v[210:211], v[200:201] op_sel_hi:[1,0]
	v_exp_f32_e32 v216, v216
	v_exp_f32_e32 v217, v217
	v_exp_f32_e32 v218, v218
	v_exp_f32_e32 v219, v219
	v_exp_f32_e32 v220, v220
	v_exp_f32_e32 v221, v221
	v_exp_f32_e32 v222, v222
	v_exp_f32_e32 v223, v223
	v_pk_add_f32 v[216:217], v[216:217], v[200:201] op_sel:[0,1] op_sel_hi:[1,1]
	v_pk_add_f32 v[218:219], v[218:219], v[200:201] op_sel:[0,1] op_sel_hi:[1,1]
	v_pk_add_f32 v[220:221], v[220:221], v[200:201] op_sel:[0,1] op_sel_hi:[1,1]
	v_pk_add_f32 v[222:223], v[222:223], v[200:201] op_sel:[0,1] op_sel_hi:[1,1]
	v_rcp_f32_e32 v216, v216
	v_rcp_f32_e32 v217, v217
	v_rcp_f32_e32 v218, v218
	v_rcp_f32_e32 v219, v219
	v_rcp_f32_e32 v220, v220
	v_rcp_f32_e32 v221, v221
	v_rcp_f32_e32 v222, v222
	v_rcp_f32_e32 v223, v223
	v_cvt_pk_bf16_f32 v240, v216, v217
	v_cvt_pk_bf16_f32 v241, v218, v219
	v_cvt_pk_bf16_f32 v242, v220, v221
	v_cvt_pk_bf16_f32 v243, v222, v223
	v_add_u32_e32 v128, 32, v198
	v_mad_i64_i32 v[128:129], s[36:37], s0, v128, 0
	v_lshl_add_u64 v[128:129], v[128:129], 1, v[164:165]
	s_cmp_gt_i32 s61, 1
	s_mov_b64 s[36:37], -1
	global_store_dwordx4 v[128:129], v[240:243], off
	s_mov_b64 s[36:37], 0
	s_andn2_b64 vcc, exec, s[36:37]
	v_pk_fma_f32 v[204:205], v[40:41], v[136:137], v[56:57] op_sel:[0,1,0]
	v_pk_fma_f32 v[206:207], v[42:43], v[136:137], v[58:59] op_sel:[0,1,0]
	v_pk_fma_f32 v[208:209], v[32:33], v[136:137], v[44:45] op_sel:[0,1,0]
	v_pk_fma_f32 v[210:211], v[34:35], v[136:137], v[46:47] op_sel:[0,1,0]
	v_pk_fma_f32 v[204:205], v[124:125], v[136:137], v[204:205] op_sel_hi:[1,0,1]
	v_pk_fma_f32 v[206:207], v[126:127], v[136:137], v[206:207] op_sel_hi:[1,0,1]
	v_pk_fma_f32 v[208:209], v[120:121], v[136:137], v[208:209] op_sel_hi:[1,0,1]
	v_pk_fma_f32 v[210:211], v[122:123], v[136:137], v[210:211] op_sel_hi:[1,0,1]
	v_pk_mul_f32 v[216:217], v[204:205], v[200:201] op_sel_hi:[1,0]
	v_pk_mul_f32 v[218:219], v[206:207], v[200:201] op_sel_hi:[1,0]
	v_pk_mul_f32 v[220:221], v[208:209], v[200:201] op_sel_hi:[1,0]
	v_pk_mul_f32 v[222:223], v[210:211], v[200:201] op_sel_hi:[1,0]
	v_exp_f32_e32 v216, v216
	v_exp_f32_e32 v217, v217
	v_exp_f32_e32 v218, v218
	v_exp_f32_e32 v219, v219
	v_exp_f32_e32 v220, v220
	v_exp_f32_e32 v221, v221
	v_exp_f32_e32 v222, v222
	v_exp_f32_e32 v223, v223
	v_pk_add_f32 v[216:217], v[216:217], v[200:201] op_sel:[0,1] op_sel_hi:[1,1]
	v_pk_add_f32 v[218:219], v[218:219], v[200:201] op_sel:[0,1] op_sel_hi:[1,1]
	v_pk_add_f32 v[220:221], v[220:221], v[200:201] op_sel:[0,1] op_sel_hi:[1,1]
	v_pk_add_f32 v[222:223], v[222:223], v[200:201] op_sel:[0,1] op_sel_hi:[1,1]
	v_rcp_f32_e32 v216, v216
	v_rcp_f32_e32 v217, v217
	v_rcp_f32_e32 v218, v218
	v_rcp_f32_e32 v219, v219
	v_rcp_f32_e32 v220, v220
	v_rcp_f32_e32 v221, v221
	v_rcp_f32_e32 v222, v222
	v_rcp_f32_e32 v223, v223
	v_cvt_pk_bf16_f32 v244, v216, v217
	v_cvt_pk_bf16_f32 v245, v218, v219
	v_cvt_pk_bf16_f32 v246, v220, v221
	v_cvt_pk_bf16_f32 v247, v222, v223
	global_store_dwordx4 v[128:129], v[244:247], off offset:256
	s_cmp_gt_i32 s61, 1
	s_mov_b64 s[36:37], -1
	s_mov_b64 s[36:37], 0
	s_andn2_b64 vcc, exec, s[36:37]
	v_pk_fma_f32 v[204:205], v[68:69], v[138:139], v[72:73] op_sel:[0,1,0]
	v_pk_fma_f32 v[206:207], v[70:71], v[138:139], v[74:75] op_sel:[0,1,0]
	v_pk_fma_f32 v[208:209], v[60:61], v[138:139], v[64:65] op_sel:[0,1,0]
	v_pk_fma_f32 v[210:211], v[62:63], v[138:139], v[66:67] op_sel:[0,1,0]
	v_pk_fma_f32 v[204:205], v[116:117], v[138:139], v[204:205] op_sel_hi:[1,0,1]
	v_pk_fma_f32 v[206:207], v[118:119], v[138:139], v[206:207] op_sel_hi:[1,0,1]
	v_pk_fma_f32 v[208:209], v[112:113], v[138:139], v[208:209] op_sel_hi:[1,0,1]
	v_pk_fma_f32 v[210:211], v[114:115], v[138:139], v[210:211] op_sel_hi:[1,0,1]
	v_pk_mul_f32 v[216:217], v[204:205], v[200:201] op_sel_hi:[1,0]
	v_pk_mul_f32 v[218:219], v[206:207], v[200:201] op_sel_hi:[1,0]
	v_pk_mul_f32 v[220:221], v[208:209], v[200:201] op_sel_hi:[1,0]
	v_pk_mul_f32 v[222:223], v[210:211], v[200:201] op_sel_hi:[1,0]
	v_exp_f32_e32 v216, v216
	v_exp_f32_e32 v217, v217
	v_exp_f32_e32 v218, v218
	v_exp_f32_e32 v219, v219
	v_exp_f32_e32 v220, v220
	v_exp_f32_e32 v221, v221
	v_exp_f32_e32 v222, v222
	v_exp_f32_e32 v223, v223
	v_pk_add_f32 v[216:217], v[216:217], v[200:201] op_sel:[0,1] op_sel_hi:[1,1]
	v_pk_add_f32 v[218:219], v[218:219], v[200:201] op_sel:[0,1] op_sel_hi:[1,1]
	v_pk_add_f32 v[220:221], v[220:221], v[200:201] op_sel:[0,1] op_sel_hi:[1,1]
	v_pk_add_f32 v[222:223], v[222:223], v[200:201] op_sel:[0,1] op_sel_hi:[1,1]
	v_rcp_f32_e32 v216, v216
	v_rcp_f32_e32 v217, v217
	v_rcp_f32_e32 v218, v218
	v_rcp_f32_e32 v219, v219
	v_rcp_f32_e32 v220, v220
	v_rcp_f32_e32 v221, v221
	v_rcp_f32_e32 v222, v222
	v_rcp_f32_e32 v223, v223
	v_cvt_pk_bf16_f32 v248, v216, v217
	v_cvt_pk_bf16_f32 v249, v218, v219
	v_cvt_pk_bf16_f32 v250, v220, v221
	v_cvt_pk_bf16_f32 v251, v222, v223
	v_add_u32_e32 v112, 48, v198
	v_mad_i64_i32 v[112:113], s[36:37], s0, v112, 0
	v_lshl_add_u64 v[112:113], v[112:113], 1, v[164:165]
	global_store_dwordx4 v[112:113], v[248:251], off
	s_cmp_gt_i32 s61, 1
	s_mov_b64 s[36:37], -1
	s_mov_b64 s[36:37], 0
	s_andn2_b64 vcc, exec, s[36:37]
	v_pk_fma_f32 v[204:205], v[40:41], v[138:139], v[56:57] op_sel:[0,1,0]
	v_pk_fma_f32 v[206:207], v[42:43], v[138:139], v[58:59] op_sel:[0,1,0]
	v_pk_fma_f32 v[208:209], v[32:33], v[138:139], v[44:45] op_sel:[0,1,0]
	v_pk_fma_f32 v[210:211], v[34:35], v[138:139], v[46:47] op_sel:[0,1,0]
	v_pk_fma_f32 v[204:205], v[108:109], v[138:139], v[204:205] op_sel_hi:[1,0,1]
	v_pk_fma_f32 v[206:207], v[110:111], v[138:139], v[206:207] op_sel_hi:[1,0,1]
	v_pk_fma_f32 v[208:209], v[104:105], v[138:139], v[208:209] op_sel_hi:[1,0,1]
	v_pk_fma_f32 v[210:211], v[106:107], v[138:139], v[210:211] op_sel_hi:[1,0,1]
	v_pk_mul_f32 v[216:217], v[204:205], v[200:201] op_sel_hi:[1,0]
	v_pk_mul_f32 v[218:219], v[206:207], v[200:201] op_sel_hi:[1,0]
	v_pk_mul_f32 v[220:221], v[208:209], v[200:201] op_sel_hi:[1,0]
	v_pk_mul_f32 v[222:223], v[210:211], v[200:201] op_sel_hi:[1,0]
	v_exp_f32_e32 v216, v216
	v_exp_f32_e32 v217, v217
	v_exp_f32_e32 v218, v218
	v_exp_f32_e32 v219, v219
	v_exp_f32_e32 v220, v220
	v_exp_f32_e32 v221, v221
	v_exp_f32_e32 v222, v222
	v_exp_f32_e32 v223, v223
	v_pk_add_f32 v[216:217], v[216:217], v[200:201] op_sel:[0,1] op_sel_hi:[1,1]
	v_pk_add_f32 v[218:219], v[218:219], v[200:201] op_sel:[0,1] op_sel_hi:[1,1]
	v_pk_add_f32 v[220:221], v[220:221], v[200:201] op_sel:[0,1] op_sel_hi:[1,1]
	v_pk_add_f32 v[222:223], v[222:223], v[200:201] op_sel:[0,1] op_sel_hi:[1,1]
	v_rcp_f32_e32 v216, v216
	v_rcp_f32_e32 v217, v217
	v_rcp_f32_e32 v218, v218
	v_rcp_f32_e32 v219, v219
	v_rcp_f32_e32 v220, v220
	v_rcp_f32_e32 v221, v221
	v_rcp_f32_e32 v222, v222
	v_rcp_f32_e32 v223, v223
	v_cvt_pk_bf16_f32 v224, v216, v217
	v_cvt_pk_bf16_f32 v225, v218, v219
	v_cvt_pk_bf16_f32 v226, v220, v221
	v_cvt_pk_bf16_f32 v227, v222, v223
	global_store_dwordx4 v[112:113], v[224:227], off offset:256
	s_cmp_gt_i32 s61, 1
	s_mov_b64 s[36:37], -1
	s_mov_b64 s[36:37], 0
	s_andn2_b64 vcc, exec, s[36:37]
	v_pk_fma_f32 v[204:205], v[68:69], v[100:101], v[72:73] op_sel:[0,1,0]
	v_pk_fma_f32 v[206:207], v[70:71], v[100:101], v[74:75] op_sel:[0,1,0]
	v_pk_fma_f32 v[208:209], v[60:61], v[100:101], v[64:65] op_sel:[0,1,0]
	v_pk_fma_f32 v[210:211], v[62:63], v[100:101], v[66:67] op_sel:[0,1,0]
	v_pk_fma_f32 v[204:205], v[96:97], v[100:101], v[204:205] op_sel_hi:[1,0,1]
	v_pk_fma_f32 v[206:207], v[98:99], v[100:101], v[206:207] op_sel_hi:[1,0,1]
	v_pk_fma_f32 v[208:209], v[92:93], v[100:101], v[208:209] op_sel_hi:[1,0,1]
	v_pk_fma_f32 v[210:211], v[94:95], v[100:101], v[210:211] op_sel_hi:[1,0,1]
	v_pk_mul_f32 v[216:217], v[204:205], v[200:201] op_sel_hi:[1,0]
	v_pk_mul_f32 v[218:219], v[206:207], v[200:201] op_sel_hi:[1,0]
	v_pk_mul_f32 v[220:221], v[208:209], v[200:201] op_sel_hi:[1,0]
	v_pk_mul_f32 v[222:223], v[210:211], v[200:201] op_sel_hi:[1,0]
	v_exp_f32_e32 v216, v216
	v_exp_f32_e32 v217, v217
	v_exp_f32_e32 v218, v218
	v_exp_f32_e32 v219, v219
	v_exp_f32_e32 v220, v220
	v_exp_f32_e32 v221, v221
	v_exp_f32_e32 v222, v222
	v_exp_f32_e32 v223, v223
	v_pk_add_f32 v[216:217], v[216:217], v[200:201] op_sel:[0,1] op_sel_hi:[1,1]
	v_pk_add_f32 v[218:219], v[218:219], v[200:201] op_sel:[0,1] op_sel_hi:[1,1]
	v_pk_add_f32 v[220:221], v[220:221], v[200:201] op_sel:[0,1] op_sel_hi:[1,1]
	v_pk_add_f32 v[222:223], v[222:223], v[200:201] op_sel:[0,1] op_sel_hi:[1,1]
	v_rcp_f32_e32 v216, v216
	v_rcp_f32_e32 v217, v217
	v_rcp_f32_e32 v218, v218
	v_rcp_f32_e32 v219, v219
	v_rcp_f32_e32 v220, v220
	v_rcp_f32_e32 v221, v221
	v_rcp_f32_e32 v222, v222
	v_rcp_f32_e32 v223, v223
	v_cvt_pk_bf16_f32 v228, v216, v217
	v_cvt_pk_bf16_f32 v229, v218, v219
	v_cvt_pk_bf16_f32 v230, v220, v221
	v_cvt_pk_bf16_f32 v231, v222, v223
	v_add_u32_e32 v92, 0x80, v198
	v_mad_i64_i32 v[92:93], s[36:37], s0, v92, 0
	v_lshl_add_u64 v[92:93], v[92:93], 1, v[164:165]
	s_cmp_gt_i32 s61, 1
	s_mov_b64 s[36:37], -1
	global_store_dwordx4 v[92:93], v[228:231], off
	s_mov_b64 s[36:37], 0
	s_andn2_b64 vcc, exec, s[36:37]
	v_pk_fma_f32 v[204:205], v[40:41], v[100:101], v[56:57] op_sel:[0,1,0]
	v_pk_fma_f32 v[206:207], v[42:43], v[100:101], v[58:59] op_sel:[0,1,0]
	v_pk_fma_f32 v[208:209], v[32:33], v[100:101], v[44:45] op_sel:[0,1,0]
	v_pk_fma_f32 v[210:211], v[34:35], v[100:101], v[46:47] op_sel:[0,1,0]
	v_pk_fma_f32 v[204:205], v[88:89], v[100:101], v[204:205] op_sel_hi:[1,0,1]
	v_pk_fma_f32 v[206:207], v[90:91], v[100:101], v[206:207] op_sel_hi:[1,0,1]
	v_pk_fma_f32 v[208:209], v[84:85], v[100:101], v[208:209] op_sel_hi:[1,0,1]
	v_pk_fma_f32 v[210:211], v[86:87], v[100:101], v[210:211] op_sel_hi:[1,0,1]
	v_pk_mul_f32 v[216:217], v[204:205], v[200:201] op_sel_hi:[1,0]
	v_pk_mul_f32 v[218:219], v[206:207], v[200:201] op_sel_hi:[1,0]
	v_pk_mul_f32 v[220:221], v[208:209], v[200:201] op_sel_hi:[1,0]
	v_pk_mul_f32 v[222:223], v[210:211], v[200:201] op_sel_hi:[1,0]
	v_exp_f32_e32 v216, v216
	v_exp_f32_e32 v217, v217
	v_exp_f32_e32 v218, v218
	v_exp_f32_e32 v219, v219
	v_exp_f32_e32 v220, v220
	v_exp_f32_e32 v221, v221
	v_exp_f32_e32 v222, v222
	v_exp_f32_e32 v223, v223
	v_pk_add_f32 v[216:217], v[216:217], v[200:201] op_sel:[0,1] op_sel_hi:[1,1]
	v_pk_add_f32 v[218:219], v[218:219], v[200:201] op_sel:[0,1] op_sel_hi:[1,1]
	v_pk_add_f32 v[220:221], v[220:221], v[200:201] op_sel:[0,1] op_sel_hi:[1,1]
	v_pk_add_f32 v[222:223], v[222:223], v[200:201] op_sel:[0,1] op_sel_hi:[1,1]
	v_rcp_f32_e32 v216, v216
	v_rcp_f32_e32 v217, v217
	v_rcp_f32_e32 v218, v218
	v_rcp_f32_e32 v219, v219
	v_rcp_f32_e32 v220, v220
	v_rcp_f32_e32 v221, v221
	v_rcp_f32_e32 v222, v222
	v_rcp_f32_e32 v223, v223
	v_cvt_pk_bf16_f32 v232, v216, v217
	v_cvt_pk_bf16_f32 v233, v218, v219
	v_cvt_pk_bf16_f32 v234, v220, v221
	v_cvt_pk_bf16_f32 v235, v222, v223
	global_store_dwordx4 v[92:93], v[232:235], off offset:256
	s_cmp_gt_i32 s61, 1
	s_mov_b64 s[36:37], -1
	s_mov_b64 s[36:37], 0
	s_andn2_b64 vcc, exec, s[36:37]
	v_pk_fma_f32 v[204:205], v[68:69], v[102:103], v[72:73] op_sel:[0,1,0]
	v_pk_fma_f32 v[206:207], v[70:71], v[102:103], v[74:75] op_sel:[0,1,0]
	v_pk_fma_f32 v[208:209], v[60:61], v[102:103], v[64:65] op_sel:[0,1,0]
	v_pk_fma_f32 v[210:211], v[62:63], v[102:103], v[66:67] op_sel:[0,1,0]
	v_pk_fma_f32 v[204:205], v[80:81], v[102:103], v[204:205] op_sel_hi:[1,0,1]
	v_pk_fma_f32 v[206:207], v[82:83], v[102:103], v[206:207] op_sel_hi:[1,0,1]
	v_pk_fma_f32 v[208:209], v[76:77], v[102:103], v[208:209] op_sel_hi:[1,0,1]
	v_pk_fma_f32 v[210:211], v[78:79], v[102:103], v[210:211] op_sel_hi:[1,0,1]
	v_pk_mul_f32 v[216:217], v[204:205], v[200:201] op_sel_hi:[1,0]
	v_pk_mul_f32 v[218:219], v[206:207], v[200:201] op_sel_hi:[1,0]
	v_pk_mul_f32 v[220:221], v[208:209], v[200:201] op_sel_hi:[1,0]
	v_pk_mul_f32 v[222:223], v[210:211], v[200:201] op_sel_hi:[1,0]
	v_exp_f32_e32 v216, v216
	v_exp_f32_e32 v217, v217
	v_exp_f32_e32 v218, v218
	v_exp_f32_e32 v219, v219
	v_exp_f32_e32 v220, v220
	v_exp_f32_e32 v221, v221
	v_exp_f32_e32 v222, v222
	v_exp_f32_e32 v223, v223
	v_pk_add_f32 v[216:217], v[216:217], v[200:201] op_sel:[0,1] op_sel_hi:[1,1]
	v_pk_add_f32 v[218:219], v[218:219], v[200:201] op_sel:[0,1] op_sel_hi:[1,1]
	v_pk_add_f32 v[220:221], v[220:221], v[200:201] op_sel:[0,1] op_sel_hi:[1,1]
	v_pk_add_f32 v[222:223], v[222:223], v[200:201] op_sel:[0,1] op_sel_hi:[1,1]
	v_rcp_f32_e32 v216, v216
	v_rcp_f32_e32 v217, v217
	v_rcp_f32_e32 v218, v218
	v_rcp_f32_e32 v219, v219
	v_rcp_f32_e32 v220, v220
	v_rcp_f32_e32 v221, v221
	v_rcp_f32_e32 v222, v222
	v_rcp_f32_e32 v223, v223
	v_cvt_pk_bf16_f32 v236, v216, v217
	v_cvt_pk_bf16_f32 v237, v218, v219
	v_cvt_pk_bf16_f32 v238, v220, v221
	v_cvt_pk_bf16_f32 v239, v222, v223
	v_add_u32_e32 v76, 0x90, v198
	v_mad_i64_i32 v[76:77], s[36:37], s0, v76, 0
	v_lshl_add_u64 v[76:77], v[76:77], 1, v[164:165]
	global_store_dwordx4 v[76:77], v[236:239], off
	s_cmp_gt_i32 s61, 1
	s_mov_b64 s[36:37], -1
	s_mov_b64 s[36:37], 0
	s_andn2_b64 vcc, exec, s[36:37]
	v_pk_fma_f32 v[204:205], v[40:41], v[102:103], v[56:57] op_sel:[0,1,0]
	v_pk_fma_f32 v[206:207], v[42:43], v[102:103], v[58:59] op_sel:[0,1,0]
	v_pk_fma_f32 v[208:209], v[32:33], v[102:103], v[44:45] op_sel:[0,1,0]
	v_pk_fma_f32 v[210:211], v[34:35], v[102:103], v[46:47] op_sel:[0,1,0]
	v_pk_fma_f32 v[204:205], v[52:53], v[102:103], v[204:205] op_sel_hi:[1,0,1]
	v_pk_fma_f32 v[206:207], v[54:55], v[102:103], v[206:207] op_sel_hi:[1,0,1]
	v_pk_fma_f32 v[208:209], v[36:37], v[102:103], v[208:209] op_sel_hi:[1,0,1]
	v_pk_fma_f32 v[210:211], v[38:39], v[102:103], v[210:211] op_sel_hi:[1,0,1]
	v_pk_mul_f32 v[216:217], v[204:205], v[200:201] op_sel_hi:[1,0]
	v_pk_mul_f32 v[218:219], v[206:207], v[200:201] op_sel_hi:[1,0]
	v_pk_mul_f32 v[220:221], v[208:209], v[200:201] op_sel_hi:[1,0]
	v_pk_mul_f32 v[222:223], v[210:211], v[200:201] op_sel_hi:[1,0]
	v_exp_f32_e32 v216, v216
	v_exp_f32_e32 v217, v217
	v_exp_f32_e32 v218, v218
	v_exp_f32_e32 v219, v219
	v_exp_f32_e32 v220, v220
	v_exp_f32_e32 v221, v221
	v_exp_f32_e32 v222, v222
	v_exp_f32_e32 v223, v223
	v_pk_add_f32 v[216:217], v[216:217], v[200:201] op_sel:[0,1] op_sel_hi:[1,1]
	v_pk_add_f32 v[218:219], v[218:219], v[200:201] op_sel:[0,1] op_sel_hi:[1,1]
	v_pk_add_f32 v[220:221], v[220:221], v[200:201] op_sel:[0,1] op_sel_hi:[1,1]
	v_pk_add_f32 v[222:223], v[222:223], v[200:201] op_sel:[0,1] op_sel_hi:[1,1]
	v_rcp_f32_e32 v216, v216
	v_rcp_f32_e32 v217, v217
	v_rcp_f32_e32 v218, v218
	v_rcp_f32_e32 v219, v219
	v_rcp_f32_e32 v220, v220
	v_rcp_f32_e32 v221, v221
	v_rcp_f32_e32 v222, v222
	v_rcp_f32_e32 v223, v223
	v_cvt_pk_bf16_f32 v240, v216, v217
	v_cvt_pk_bf16_f32 v241, v218, v219
	v_cvt_pk_bf16_f32 v242, v220, v221
	v_cvt_pk_bf16_f32 v243, v222, v223
	global_store_dwordx4 v[76:77], v[240:243], off offset:256
	s_cmp_gt_i32 s61, 1
	s_mov_b64 s[36:37], -1
	s_mov_b64 s[36:37], 0
	s_andn2_b64 vcc, exec, s[36:37]
	v_pk_fma_f32 v[204:205], v[68:69], v[48:49], v[72:73] op_sel:[0,1,0]
	v_pk_fma_f32 v[206:207], v[70:71], v[48:49], v[74:75] op_sel:[0,1,0]
	v_pk_fma_f32 v[208:209], v[60:61], v[48:49], v[64:65] op_sel:[0,1,0]
	v_pk_fma_f32 v[210:211], v[62:63], v[48:49], v[66:67] op_sel:[0,1,0]
	v_pk_fma_f32 v[204:205], v[28:29], v[48:49], v[204:205] op_sel_hi:[1,0,1]
	v_pk_fma_f32 v[206:207], v[30:31], v[48:49], v[206:207] op_sel_hi:[1,0,1]
	v_pk_fma_f32 v[208:209], v[24:25], v[48:49], v[208:209] op_sel_hi:[1,0,1]
	v_pk_fma_f32 v[210:211], v[26:27], v[48:49], v[210:211] op_sel_hi:[1,0,1]
	v_pk_mul_f32 v[216:217], v[204:205], v[200:201] op_sel_hi:[1,0]
	v_pk_mul_f32 v[218:219], v[206:207], v[200:201] op_sel_hi:[1,0]
	v_pk_mul_f32 v[220:221], v[208:209], v[200:201] op_sel_hi:[1,0]
	v_pk_mul_f32 v[222:223], v[210:211], v[200:201] op_sel_hi:[1,0]
	v_exp_f32_e32 v216, v216
	v_exp_f32_e32 v217, v217
	v_exp_f32_e32 v218, v218
	v_exp_f32_e32 v219, v219
	v_exp_f32_e32 v220, v220
	v_exp_f32_e32 v221, v221
	v_exp_f32_e32 v222, v222
	v_exp_f32_e32 v223, v223
	v_pk_add_f32 v[216:217], v[216:217], v[200:201] op_sel:[0,1] op_sel_hi:[1,1]
	v_pk_add_f32 v[218:219], v[218:219], v[200:201] op_sel:[0,1] op_sel_hi:[1,1]
	v_pk_add_f32 v[220:221], v[220:221], v[200:201] op_sel:[0,1] op_sel_hi:[1,1]
	v_pk_add_f32 v[222:223], v[222:223], v[200:201] op_sel:[0,1] op_sel_hi:[1,1]
	v_rcp_f32_e32 v216, v216
	v_rcp_f32_e32 v217, v217
	v_rcp_f32_e32 v218, v218
	v_rcp_f32_e32 v219, v219
	v_rcp_f32_e32 v220, v220
	v_rcp_f32_e32 v221, v221
	v_rcp_f32_e32 v222, v222
	v_rcp_f32_e32 v223, v223
	v_cvt_pk_bf16_f32 v244, v216, v217
	v_cvt_pk_bf16_f32 v245, v218, v219
	v_cvt_pk_bf16_f32 v246, v220, v221
	v_cvt_pk_bf16_f32 v247, v222, v223
	v_add_u32_e32 v24, 0xa0, v198
	v_mad_i64_i32 v[24:25], s[36:37], s0, v24, 0
	v_lshl_add_u64 v[24:25], v[24:25], 1, v[164:165]
	s_cmp_gt_i32 s61, 1
	s_mov_b64 s[36:37], -1
	global_store_dwordx4 v[24:25], v[244:247], off
	s_mov_b64 s[36:37], 0
	s_andn2_b64 vcc, exec, s[36:37]
	v_pk_fma_f32 v[204:205], v[40:41], v[48:49], v[56:57] op_sel:[0,1,0]
	v_pk_fma_f32 v[206:207], v[42:43], v[48:49], v[58:59] op_sel:[0,1,0]
	v_pk_fma_f32 v[208:209], v[32:33], v[48:49], v[44:45] op_sel:[0,1,0]
	v_pk_fma_f32 v[210:211], v[34:35], v[48:49], v[46:47] op_sel:[0,1,0]
	v_pk_fma_f32 v[204:205], v[20:21], v[48:49], v[204:205] op_sel_hi:[1,0,1]
	v_pk_fma_f32 v[206:207], v[22:23], v[48:49], v[206:207] op_sel_hi:[1,0,1]
	v_pk_fma_f32 v[208:209], v[16:17], v[48:49], v[208:209] op_sel_hi:[1,0,1]
	v_pk_fma_f32 v[210:211], v[18:19], v[48:49], v[210:211] op_sel_hi:[1,0,1]
	v_pk_mul_f32 v[216:217], v[204:205], v[200:201] op_sel_hi:[1,0]
	v_pk_mul_f32 v[218:219], v[206:207], v[200:201] op_sel_hi:[1,0]
	v_pk_mul_f32 v[220:221], v[208:209], v[200:201] op_sel_hi:[1,0]
	v_pk_mul_f32 v[222:223], v[210:211], v[200:201] op_sel_hi:[1,0]
	v_exp_f32_e32 v216, v216
	v_exp_f32_e32 v217, v217
	v_exp_f32_e32 v218, v218
	v_exp_f32_e32 v219, v219
	v_exp_f32_e32 v220, v220
	v_exp_f32_e32 v221, v221
	v_exp_f32_e32 v222, v222
	v_exp_f32_e32 v223, v223
	v_pk_add_f32 v[216:217], v[216:217], v[200:201] op_sel:[0,1] op_sel_hi:[1,1]
	v_pk_add_f32 v[218:219], v[218:219], v[200:201] op_sel:[0,1] op_sel_hi:[1,1]
	v_pk_add_f32 v[220:221], v[220:221], v[200:201] op_sel:[0,1] op_sel_hi:[1,1]
	v_pk_add_f32 v[222:223], v[222:223], v[200:201] op_sel:[0,1] op_sel_hi:[1,1]
	v_rcp_f32_e32 v216, v216
	v_rcp_f32_e32 v217, v217
	v_rcp_f32_e32 v218, v218
	v_rcp_f32_e32 v219, v219
	v_rcp_f32_e32 v220, v220
	v_rcp_f32_e32 v221, v221
	v_rcp_f32_e32 v222, v222
	v_rcp_f32_e32 v223, v223
	v_cvt_pk_bf16_f32 v248, v216, v217
	v_cvt_pk_bf16_f32 v249, v218, v219
	v_cvt_pk_bf16_f32 v250, v220, v221
	v_cvt_pk_bf16_f32 v251, v222, v223
	global_store_dwordx4 v[24:25], v[248:251], off offset:256
	s_cmp_gt_i32 s61, 1
	s_mov_b64 s[36:37], -1
	s_mov_b64 s[36:37], 0
	s_andn2_b64 vcc, exec, s[36:37]
	v_pk_fma_f32 v[204:205], v[68:69], v[50:51], v[72:73] op_sel:[0,1,0]
	v_pk_fma_f32 v[206:207], v[70:71], v[50:51], v[74:75] op_sel:[0,1,0]
	v_pk_fma_f32 v[208:209], v[60:61], v[50:51], v[64:65] op_sel:[0,1,0]
	v_pk_fma_f32 v[210:211], v[62:63], v[50:51], v[66:67] op_sel:[0,1,0]
	v_pk_fma_f32 v[204:205], v[12:13], v[50:51], v[204:205] op_sel_hi:[1,0,1]
	v_pk_fma_f32 v[206:207], v[14:15], v[50:51], v[206:207] op_sel_hi:[1,0,1]
	v_pk_fma_f32 v[208:209], v[8:9], v[50:51], v[208:209] op_sel_hi:[1,0,1]
	v_pk_fma_f32 v[210:211], v[10:11], v[50:51], v[210:211] op_sel_hi:[1,0,1]
	v_pk_mul_f32 v[216:217], v[204:205], v[200:201] op_sel_hi:[1,0]
	v_pk_mul_f32 v[218:219], v[206:207], v[200:201] op_sel_hi:[1,0]
	v_pk_mul_f32 v[220:221], v[208:209], v[200:201] op_sel_hi:[1,0]
	v_pk_mul_f32 v[222:223], v[210:211], v[200:201] op_sel_hi:[1,0]
	v_exp_f32_e32 v216, v216
	v_exp_f32_e32 v217, v217
	v_exp_f32_e32 v218, v218
	v_exp_f32_e32 v219, v219
	v_exp_f32_e32 v220, v220
	v_exp_f32_e32 v221, v221
	v_exp_f32_e32 v222, v222
	v_exp_f32_e32 v223, v223
	v_pk_add_f32 v[216:217], v[216:217], v[200:201] op_sel:[0,1] op_sel_hi:[1,1]
	v_pk_add_f32 v[218:219], v[218:219], v[200:201] op_sel:[0,1] op_sel_hi:[1,1]
	v_pk_add_f32 v[220:221], v[220:221], v[200:201] op_sel:[0,1] op_sel_hi:[1,1]
	v_pk_add_f32 v[222:223], v[222:223], v[200:201] op_sel:[0,1] op_sel_hi:[1,1]
	v_rcp_f32_e32 v216, v216
	v_rcp_f32_e32 v217, v217
	v_rcp_f32_e32 v218, v218
	v_rcp_f32_e32 v219, v219
	v_rcp_f32_e32 v220, v220
	v_rcp_f32_e32 v221, v221
	v_rcp_f32_e32 v222, v222
	v_rcp_f32_e32 v223, v223
	v_cvt_pk_bf16_f32 v224, v216, v217
	v_cvt_pk_bf16_f32 v225, v218, v219
	v_cvt_pk_bf16_f32 v226, v220, v221
	v_cvt_pk_bf16_f32 v227, v222, v223
	v_add_u32_e32 v8, 0xb0, v198
	v_mad_i64_i32 v[8:9], s[36:37], s0, v8, 0
	v_lshl_add_u64 v[8:9], v[8:9], 1, v[164:165]
	global_store_dwordx4 v[8:9], v[224:227], off
	s_cmp_gt_i32 s61, 1
	s_mov_b64 s[36:37], -1
	s_mov_b64 s[36:37], 0
	s_andn2_b64 vcc, exec, s[36:37]
	s_andn2_b64 vcc, exec, s[8:9]
	s_mov_b64 s[8:9], -1
	v_pk_fma_f32 v[204:205], v[40:41], v[50:51], v[56:57] op_sel:[0,1,0]
	v_pk_fma_f32 v[206:207], v[42:43], v[50:51], v[58:59] op_sel:[0,1,0]
	v_pk_fma_f32 v[208:209], v[32:33], v[50:51], v[44:45] op_sel:[0,1,0]
	v_pk_fma_f32 v[210:211], v[34:35], v[50:51], v[46:47] op_sel:[0,1,0]
	v_pk_fma_f32 v[204:205], v[4:5], v[50:51], v[204:205] op_sel_hi:[1,0,1]
	v_pk_fma_f32 v[206:207], v[6:7], v[50:51], v[206:207] op_sel_hi:[1,0,1]
	v_pk_fma_f32 v[208:209], v[0:1], v[50:51], v[208:209] op_sel_hi:[1,0,1]
	v_pk_fma_f32 v[210:211], v[2:3], v[50:51], v[210:211] op_sel_hi:[1,0,1]
	v_pk_mul_f32 v[216:217], v[204:205], v[200:201] op_sel_hi:[1,0]
	v_pk_mul_f32 v[218:219], v[206:207], v[200:201] op_sel_hi:[1,0]
	v_pk_mul_f32 v[220:221], v[208:209], v[200:201] op_sel_hi:[1,0]
	v_pk_mul_f32 v[222:223], v[210:211], v[200:201] op_sel_hi:[1,0]
	v_exp_f32_e32 v216, v216
	v_exp_f32_e32 v217, v217
	v_exp_f32_e32 v218, v218
	v_exp_f32_e32 v219, v219
	v_exp_f32_e32 v220, v220
	v_exp_f32_e32 v221, v221
	v_exp_f32_e32 v222, v222
	v_exp_f32_e32 v223, v223
	v_pk_add_f32 v[216:217], v[216:217], v[200:201] op_sel:[0,1] op_sel_hi:[1,1]
	v_pk_add_f32 v[218:219], v[218:219], v[200:201] op_sel:[0,1] op_sel_hi:[1,1]
	v_pk_add_f32 v[220:221], v[220:221], v[200:201] op_sel:[0,1] op_sel_hi:[1,1]
	v_pk_add_f32 v[222:223], v[222:223], v[200:201] op_sel:[0,1] op_sel_hi:[1,1]
	v_rcp_f32_e32 v216, v216
	v_rcp_f32_e32 v217, v217
	v_rcp_f32_e32 v218, v218
	v_rcp_f32_e32 v219, v219
	v_rcp_f32_e32 v220, v220
	v_rcp_f32_e32 v221, v221
	v_rcp_f32_e32 v222, v222
	v_rcp_f32_e32 v223, v223
	v_cvt_pk_bf16_f32 v228, v216, v217
	v_cvt_pk_bf16_f32 v229, v218, v219
	v_cvt_pk_bf16_f32 v230, v220, v221
	v_cvt_pk_bf16_f32 v231, v222, v223
	global_store_dwordx4 v[8:9], v[228:231], off offset:256
.Le1end_10:
	s_mov_b32 s99, 1
	s_cbranch_vccnz .LBB0_1062
	s_andn2_b64 vcc, exec, s[4:5]
	s_cbranch_vccnz .LBB0_1061
	s_barrier
	s_branch .LBB0_1061

.LBB0_1931:
	s_cmp_lg_u32 s40, 2
	s_cselect_b64 s[46:47], -1, 0
	s_cmp_lt_u32 s40, 6
	s_cselect_b64 s[66:67], -1, 0
	s_and_b64 s[46:47], s[46:47], s[66:67]
	s_cmp_gt_u32 s40, 11
	s_cselect_b32 s0, 2, 0
	s_and_b64 s[46:47], s[46:47], exec
	s_cselect_b32 s0, 1, s0
	s_cmp_gt_i32 s40, 1
	s_cselect_b32 s61, s0, 1
	s_cmp_gt_i32 s61, 1
	s_cbranch_scc1 .Le1m2_18
	s_cmp_eq_u32 s61, 1
	s_cbranch_scc1 .Le1m1_18
	s_cmp_eq_u32 s36, s69
	s_movk_i32 s0, 0x200
	s_cselect_b32 s0, s0, 0x300
	s_cmp_lg_u32 s36, s68
	v_mov_b32_e32 v44, v192
	v_mov_b32_e32 v198, v193
	s_cselect_b32 s0, s0, 0x100
	s_cmp_lg_u32 s36, s35
	s_cselect_b32 s0, s0, 0
	v_lshl_add_u32 v45, v198, 5, s79
	v_add_u32_e32 v199, s70, v44
	ds_read_b128 v[68:71], v45
	ds_read_b128 v[60:63], v45 offset:16
	ds_read_b128 v[72:75], v45 offset:256
	ds_read_b128 v[64:67], v45 offset:272
	ds_read_b128 v[40:43], v45 offset:128
	ds_read_b128 v[32:35], v45 offset:144
	v_add_u32_e32 v44, s0, v199
	v_lshl_add_u32 v48, v44, 3, v197
	ds_read2_b64 v[172:175], v48 offset1:16
	ds_read_b128 v[56:59], v45 offset:384
	ds_read_b128 v[44:47], v45 offset:400
	ds_read2_b64 v[136:139], v48 offset0:32 offset1:48
	ds_read2_b64 v[100:103], v48 offset0:128 offset1:144
	ds_read2_b64 v[48:51], v48 offset0:160 offset1:176
	s_waitcnt lgkmcnt(0)
	s_cmp_gt_i32 s61, 1
	s_mov_b64 s[46:47], -1
	s_andn2_b64 vcc, exec, s[46:47]
	s_cmp_eq_u32 s61, 1
	s_add_i32 s0, s74, 0xfffff400
	s_lshl_b64 s[46:47], s[0:1], 1
	s_add_u32 s0, s56, s46
	s_addc_u32 s37, s57, s47
	s_ashr_i32 s75, s74, 31
	s_lshl_b64 s[46:47], s[74:75], 1
	s_add_u32 s46, s42, s46
	s_addc_u32 s47, s43, s47
	s_cmp_lt_i32 s40, 12
	s_cselect_b32 s0, s46, s0
	v_pk_fma_f32 v[200:201], v[68:69], v[172:173], v[72:73] op_sel:[0,1,0]
	v_pk_fma_f32 v[204:205], v[70:71], v[172:173], v[74:75] op_sel:[0,1,0]
	v_pk_fma_f32 v[206:207], v[60:61], v[172:173], v[64:65] op_sel:[0,1,0]
	v_pk_fma_f32 v[208:209], v[62:63], v[172:173], v[66:67] op_sel:[0,1,0]
	v_pk_fma_f32 v[200:201], v[168:169], v[172:173], v[200:201] op_sel_hi:[1,0,1]
	v_pk_fma_f32 v[204:205], v[170:171], v[172:173], v[204:205] op_sel_hi:[1,0,1]
	v_pk_fma_f32 v[206:207], v[164:165], v[172:173], v[206:207] op_sel_hi:[1,0,1]
	v_pk_fma_f32 v[208:209], v[166:167], v[172:173], v[208:209] op_sel_hi:[1,0,1]
	v_cvt_pk_bf16_f32 v216, v200, v201
	v_cvt_pk_bf16_f32 v217, v204, v205
	v_cvt_pk_bf16_f32 v218, v206, v207
	v_cvt_pk_bf16_f32 v219, v208, v209
	v_lshl_add_u32 v164, v198, 3, s71
	s_cselect_b32 s37, s47, s37
	v_mov_b32_e32 v166, s0
	s_movk_i32 s0, 0xc00
	v_mov_b32_e32 v167, s37
	s_cselect_b32 s0, s0, 0x800
	v_ashrrev_i32_e32 v165, 31, v164
	v_lshl_add_u32 v198, s36, 8, v199
	v_lshl_add_u64 v[164:165], v[164:165], 1, v[166:167]
	v_mad_i64_i32 v[166:167], s[36:37], s0, v198, 0
	v_lshl_add_u64 v[166:167], v[166:167], 1, v[164:165]
	s_cmp_gt_i32 s61, 1
	s_mov_b64 s[36:37], -1
	global_store_dwordx4 v[166:167], v[216:219], off
	s_andn2_b64 vcc, exec, s[36:37]
	s_cmp_eq_u32 s61, 1
	v_pk_fma_f32 v[200:201], v[40:41], v[172:173], v[56:57] op_sel:[0,1,0]
	v_pk_fma_f32 v[204:205], v[42:43], v[172:173], v[58:59] op_sel:[0,1,0]
	v_pk_fma_f32 v[206:207], v[32:33], v[172:173], v[44:45] op_sel:[0,1,0]
	v_pk_fma_f32 v[208:209], v[34:35], v[172:173], v[46:47] op_sel:[0,1,0]
	v_pk_fma_f32 v[200:201], v[160:161], v[172:173], v[200:201] op_sel_hi:[1,0,1]
	v_pk_fma_f32 v[204:205], v[162:163], v[172:173], v[204:205] op_sel_hi:[1,0,1]
	v_pk_fma_f32 v[206:207], v[156:157], v[172:173], v[206:207] op_sel_hi:[1,0,1]
	v_pk_fma_f32 v[208:209], v[158:159], v[172:173], v[208:209] op_sel_hi:[1,0,1]
	v_cvt_pk_bf16_f32 v220, v200, v201
	v_cvt_pk_bf16_f32 v221, v204, v205
	v_cvt_pk_bf16_f32 v222, v206, v207
	v_cvt_pk_bf16_f32 v223, v208, v209
	global_store_dwordx4 v[166:167], v[220:223], off offset:256
	s_cmp_gt_i32 s61, 1
	s_mov_b64 s[36:37], -1
	s_andn2_b64 vcc, exec, s[36:37]
	s_cmp_eq_u32 s61, 1
	v_pk_fma_f32 v[200:201], v[68:69], v[174:175], v[72:73] op_sel:[0,1,0]
	v_pk_fma_f32 v[204:205], v[70:71], v[174:175], v[74:75] op_sel:[0,1,0]
	v_pk_fma_f32 v[206:207], v[60:61], v[174:175], v[64:65] op_sel:[0,1,0]
	v_pk_fma_f32 v[208:209], v[62:63], v[174:175], v[66:67] op_sel:[0,1,0]
	v_pk_fma_f32 v[200:201], v[152:153], v[174:175], v[200:201] op_sel_hi:[1,0,1]
	v_pk_fma_f32 v[204:205], v[154:155], v[174:175], v[204:205] op_sel_hi:[1,0,1]
	v_pk_fma_f32 v[206:207], v[148:149], v[174:175], v[206:207] op_sel_hi:[1,0,1]
	v_pk_fma_f32 v[208:209], v[150:151], v[174:175], v[208:209] op_sel_hi:[1,0,1]
	v_cvt_pk_bf16_f32 v224, v200, v201
	v_cvt_pk_bf16_f32 v225, v204, v205
	v_cvt_pk_bf16_f32 v226, v206, v207
	v_cvt_pk_bf16_f32 v227, v208, v209
	v_add_u32_e32 v148, 16, v198
	v_mad_i64_i32 v[148:149], s[36:37], s0, v148, 0
	v_lshl_add_u64 v[148:149], v[148:149], 1, v[164:165]
	global_store_dwordx4 v[148:149], v[224:227], off
	s_cmp_gt_i32 s61, 1
	s_mov_b64 s[36:37], -1
	s_andn2_b64 vcc, exec, s[36:37]
	s_cmp_eq_u32 s61, 1
	v_pk_fma_f32 v[200:201], v[40:41], v[174:175], v[56:57] op_sel:[0,1,0]
	v_pk_fma_f32 v[204:205], v[42:43], v[174:175], v[58:59] op_sel:[0,1,0]
	v_pk_fma_f32 v[206:207], v[32:33], v[174:175], v[44:45] op_sel:[0,1,0]
	v_pk_fma_f32 v[208:209], v[34:35], v[174:175], v[46:47] op_sel:[0,1,0]
	v_pk_fma_f32 v[200:201], v[144:145], v[174:175], v[200:201] op_sel_hi:[1,0,1]
	v_pk_fma_f32 v[204:205], v[146:147], v[174:175], v[204:205] op_sel_hi:[1,0,1]
	v_pk_fma_f32 v[206:207], v[140:141], v[174:175], v[206:207] op_sel_hi:[1,0,1]
	v_pk_fma_f32 v[208:209], v[142:143], v[174:175], v[208:209] op_sel_hi:[1,0,1]
	v_cvt_pk_bf16_f32 v228, v200, v201
	v_cvt_pk_bf16_f32 v229, v204, v205
	v_cvt_pk_bf16_f32 v230, v206, v207
	v_cvt_pk_bf16_f32 v231, v208, v209
	global_store_dwordx4 v[148:149], v[228:231], off offset:256
	s_cmp_gt_i32 s61, 1
	s_mov_b64 s[36:37], -1
	s_andn2_b64 vcc, exec, s[36:37]
	s_cmp_eq_u32 s61, 1
	v_pk_fma_f32 v[200:201], v[68:69], v[136:137], v[72:73] op_sel:[0,1,0]
	v_pk_fma_f32 v[204:205], v[70:71], v[136:137], v[74:75] op_sel:[0,1,0]
	v_pk_fma_f32 v[206:207], v[60:61], v[136:137], v[64:65] op_sel:[0,1,0]
	v_pk_fma_f32 v[208:209], v[62:63], v[136:137], v[66:67] op_sel:[0,1,0]
	v_pk_fma_f32 v[200:201], v[132:133], v[136:137], v[200:201] op_sel_hi:[1,0,1]
	v_pk_fma_f32 v[204:205], v[134:135], v[136:137], v[204:205] op_sel_hi:[1,0,1]
	v_pk_fma_f32 v[206:207], v[128:129], v[136:137], v[206:207] op_sel_hi:[1,0,1]
	v_pk_fma_f32 v[208:209], v[130:131], v[136:137], v[208:209] op_sel_hi:[1,0,1]
	v_cvt_pk_bf16_f32 v232, v200, v201
	v_cvt_pk_bf16_f32 v233, v204, v205
	v_cvt_pk_bf16_f32 v234, v206, v207
	v_cvt_pk_bf16_f32 v235, v208, v209
	v_add_u32_e32 v128, 32, v198
	v_mad_i64_i32 v[128:129], s[36:37], s0, v128, 0
	v_lshl_add_u64 v[128:129], v[128:129], 1, v[164:165]
	s_cmp_gt_i32 s61, 1
	s_mov_b64 s[36:37], -1
	global_store_dwordx4 v[128:129], v[232:235], off
	s_andn2_b64 vcc, exec, s[36:37]
	s_cmp_eq_u32 s61, 1
	v_pk_fma_f32 v[200:201], v[40:41], v[136:137], v[56:57] op_sel:[0,1,0]
	v_pk_fma_f32 v[204:205], v[42:43], v[136:137], v[58:59] op_sel:[0,1,0]
	v_pk_fma_f32 v[206:207], v[32:33], v[136:137], v[44:45] op_sel:[0,1,0]
	v_pk_fma_f32 v[208:209], v[34:35], v[136:137], v[46:47] op_sel:[0,1,0]
	v_pk_fma_f32 v[200:201], v[124:125], v[136:137], v[200:201] op_sel_hi:[1,0,1]
	v_pk_fma_f32 v[204:205], v[126:127], v[136:137], v[204:205] op_sel_hi:[1,0,1]
	v_pk_fma_f32 v[206:207], v[120:121], v[136:137], v[206:207] op_sel_hi:[1,0,1]
	v_pk_fma_f32 v[208:209], v[122:123], v[136:137], v[208:209] op_sel_hi:[1,0,1]
	v_cvt_pk_bf16_f32 v236, v200, v201
	v_cvt_pk_bf16_f32 v237, v204, v205
	v_cvt_pk_bf16_f32 v238, v206, v207
	v_cvt_pk_bf16_f32 v239, v208, v209
	global_store_dwordx4 v[128:129], v[236:239], off offset:256
	s_cmp_gt_i32 s61, 1
	s_mov_b64 s[36:37], -1
	s_andn2_b64 vcc, exec, s[36:37]
	s_cmp_eq_u32 s61, 1
	v_pk_fma_f32 v[200:201], v[68:69], v[138:139], v[72:73] op_sel:[0,1,0]
	v_pk_fma_f32 v[204:205], v[70:71], v[138:139], v[74:75] op_sel:[0,1,0]
	v_pk_fma_f32 v[206:207], v[60:61], v[138:139], v[64:65] op_sel:[0,1,0]
	v_pk_fma_f32 v[208:209], v[62:63], v[138:139], v[66:67] op_sel:[0,1,0]
	v_pk_fma_f32 v[200:201], v[116:117], v[138:139], v[200:201] op_sel_hi:[1,0,1]
	v_pk_fma_f32 v[204:205], v[118:119], v[138:139], v[204:205] op_sel_hi:[1,0,1]
	v_pk_fma_f32 v[206:207], v[112:113], v[138:139], v[206:207] op_sel_hi:[1,0,1]
	v_pk_fma_f32 v[208:209], v[114:115], v[138:139], v[208:209] op_sel_hi:[1,0,1]
	v_cvt_pk_bf16_f32 v240, v200, v201
	v_cvt_pk_bf16_f32 v241, v204, v205
	v_cvt_pk_bf16_f32 v242, v206, v207
	v_cvt_pk_bf16_f32 v243, v208, v209
	v_add_u32_e32 v112, 48, v198
	v_mad_i64_i32 v[112:113], s[36:37], s0, v112, 0
	v_lshl_add_u64 v[112:113], v[112:113], 1, v[164:165]
	global_store_dwordx4 v[112:113], v[240:243], off
	s_cmp_gt_i32 s61, 1
	s_mov_b64 s[36:37], -1
	s_andn2_b64 vcc, exec, s[36:37]
	s_cmp_eq_u32 s61, 1
	v_pk_fma_f32 v[200:201], v[40:41], v[138:139], v[56:57] op_sel:[0,1,0]
	v_pk_fma_f32 v[204:205], v[42:43], v[138:139], v[58:59] op_sel:[0,1,0]
	v_pk_fma_f32 v[206:207], v[32:33], v[138:139], v[44:45] op_sel:[0,1,0]
	v_pk_fma_f32 v[208:209], v[34:35], v[138:139], v[46:47] op_sel:[0,1,0]
	v_pk_fma_f32 v[200:201], v[108:109], v[138:139], v[200:201] op_sel_hi:[1,0,1]
	v_pk_fma_f32 v[204:205], v[110:111], v[138:139], v[204:205] op_sel_hi:[1,0,1]
	v_pk_fma_f32 v[206:207], v[104:105], v[138:139], v[206:207] op_sel_hi:[1,0,1]
	v_pk_fma_f32 v[208:209], v[106:107], v[138:139], v[208:209] op_sel_hi:[1,0,1]
	v_cvt_pk_bf16_f32 v244, v200, v201
	v_cvt_pk_bf16_f32 v245, v204, v205
	v_cvt_pk_bf16_f32 v246, v206, v207
	v_cvt_pk_bf16_f32 v247, v208, v209
	global_store_dwordx4 v[112:113], v[244:247], off offset:256
	s_cmp_gt_i32 s61, 1
	s_mov_b64 s[36:37], -1
	s_andn2_b64 vcc, exec, s[36:37]
	s_cmp_eq_u32 s61, 1
	v_pk_fma_f32 v[200:201], v[68:69], v[100:101], v[72:73] op_sel:[0,1,0]
	v_pk_fma_f32 v[204:205], v[70:71], v[100:101], v[74:75] op_sel:[0,1,0]
	v_pk_fma_f32 v[206:207], v[60:61], v[100:101], v[64:65] op_sel:[0,1,0]
	v_pk_fma_f32 v[208:209], v[62:63], v[100:101], v[66:67] op_sel:[0,1,0]
	v_pk_fma_f32 v[200:201], v[96:97], v[100:101], v[200:201] op_sel_hi:[1,0,1]
	v_pk_fma_f32 v[204:205], v[98:99], v[100:101], v[204:205] op_sel_hi:[1,0,1]
	v_pk_fma_f32 v[206:207], v[92:93], v[100:101], v[206:207] op_sel_hi:[1,0,1]
	v_pk_fma_f32 v[208:209], v[94:95], v[100:101], v[208:209] op_sel_hi:[1,0,1]
	v_cvt_pk_bf16_f32 v248, v200, v201
	v_cvt_pk_bf16_f32 v249, v204, v205
	v_cvt_pk_bf16_f32 v250, v206, v207
	v_cvt_pk_bf16_f32 v251, v208, v209
	v_add_u32_e32 v92, 0x80, v198
	v_mad_i64_i32 v[92:93], s[36:37], s0, v92, 0
	v_lshl_add_u64 v[92:93], v[92:93], 1, v[164:165]
	s_cmp_gt_i32 s61, 1
	s_mov_b64 s[36:37], -1
	global_store_dwordx4 v[92:93], v[248:251], off
	s_andn2_b64 vcc, exec, s[36:37]
	s_cmp_eq_u32 s61, 1
	v_pk_fma_f32 v[200:201], v[40:41], v[100:101], v[56:57] op_sel:[0,1,0]
	v_pk_fma_f32 v[204:205], v[42:43], v[100:101], v[58:59] op_sel:[0,1,0]
	v_pk_fma_f32 v[206:207], v[32:33], v[100:101], v[44:45] op_sel:[0,1,0]
	v_pk_fma_f32 v[208:209], v[34:35], v[100:101], v[46:47] op_sel:[0,1,0]
	v_pk_fma_f32 v[200:201], v[88:89], v[100:101], v[200:201] op_sel_hi:[1,0,1]
	v_pk_fma_f32 v[204:205], v[90:91], v[100:101], v[204:205] op_sel_hi:[1,0,1]
	v_pk_fma_f32 v[206:207], v[84:85], v[100:101], v[206:207] op_sel_hi:[1,0,1]
	v_pk_fma_f32 v[208:209], v[86:87], v[100:101], v[208:209] op_sel_hi:[1,0,1]
	v_cvt_pk_bf16_f32 v216, v200, v201
	v_cvt_pk_bf16_f32 v217, v204, v205
	v_cvt_pk_bf16_f32 v218, v206, v207
	v_cvt_pk_bf16_f32 v219, v208, v209
	global_store_dwordx4 v[92:93], v[216:219], off offset:256
	s_cmp_gt_i32 s61, 1
	s_mov_b64 s[36:37], -1
	s_andn2_b64 vcc, exec, s[36:37]
	s_cmp_eq_u32 s61, 1
	v_pk_fma_f32 v[200:201], v[68:69], v[102:103], v[72:73] op_sel:[0,1,0]
	v_pk_fma_f32 v[204:205], v[70:71], v[102:103], v[74:75] op_sel:[0,1,0]
	v_pk_fma_f32 v[206:207], v[60:61], v[102:103], v[64:65] op_sel:[0,1,0]
	v_pk_fma_f32 v[208:209], v[62:63], v[102:103], v[66:67] op_sel:[0,1,0]
	v_pk_fma_f32 v[200:201], v[80:81], v[102:103], v[200:201] op_sel_hi:[1,0,1]
	v_pk_fma_f32 v[204:205], v[82:83], v[102:103], v[204:205] op_sel_hi:[1,0,1]
	v_pk_fma_f32 v[206:207], v[76:77], v[102:103], v[206:207] op_sel_hi:[1,0,1]
	v_pk_fma_f32 v[208:209], v[78:79], v[102:103], v[208:209] op_sel_hi:[1,0,1]
	v_cvt_pk_bf16_f32 v220, v200, v201
	v_cvt_pk_bf16_f32 v221, v204, v205
	v_cvt_pk_bf16_f32 v222, v206, v207
	v_cvt_pk_bf16_f32 v223, v208, v209
	v_add_u32_e32 v76, 0x90, v198
	v_mad_i64_i32 v[76:77], s[36:37], s0, v76, 0
	v_lshl_add_u64 v[76:77], v[76:77], 1, v[164:165]
	global_store_dwordx4 v[76:77], v[220:223], off
	s_cmp_gt_i32 s61, 1
	s_mov_b64 s[36:37], -1
	s_andn2_b64 vcc, exec, s[36:37]
	s_cmp_eq_u32 s61, 1
	v_pk_fma_f32 v[200:201], v[40:41], v[102:103], v[56:57] op_sel:[0,1,0]
	v_pk_fma_f32 v[204:205], v[42:43], v[102:103], v[58:59] op_sel:[0,1,0]
	v_pk_fma_f32 v[206:207], v[32:33], v[102:103], v[44:45] op_sel:[0,1,0]
	v_pk_fma_f32 v[208:209], v[34:35], v[102:103], v[46:47] op_sel:[0,1,0]
	v_pk_fma_f32 v[200:201], v[52:53], v[102:103], v[200:201] op_sel_hi:[1,0,1]
	v_pk_fma_f32 v[204:205], v[54:55], v[102:103], v[204:205] op_sel_hi:[1,0,1]
	v_pk_fma_f32 v[206:207], v[36:37], v[102:103], v[206:207] op_sel_hi:[1,0,1]
	v_pk_fma_f32 v[208:209], v[38:39], v[102:103], v[208:209] op_sel_hi:[1,0,1]
	v_cvt_pk_bf16_f32 v224, v200, v201
	v_cvt_pk_bf16_f32 v225, v204, v205
	v_cvt_pk_bf16_f32 v226, v206, v207
	v_cvt_pk_bf16_f32 v227, v208, v209
	global_store_dwordx4 v[76:77], v[224:227], off offset:256
	s_cmp_gt_i32 s61, 1
	s_mov_b64 s[36:37], -1
	s_andn2_b64 vcc, exec, s[36:37]
	s_cmp_eq_u32 s61, 1
	v_pk_fma_f32 v[200:201], v[68:69], v[48:49], v[72:73] op_sel:[0,1,0]
	v_pk_fma_f32 v[204:205], v[70:71], v[48:49], v[74:75] op_sel:[0,1,0]
	v_pk_fma_f32 v[206:207], v[60:61], v[48:49], v[64:65] op_sel:[0,1,0]
	v_pk_fma_f32 v[208:209], v[62:63], v[48:49], v[66:67] op_sel:[0,1,0]
	v_pk_fma_f32 v[200:201], v[28:29], v[48:49], v[200:201] op_sel_hi:[1,0,1]
	v_pk_fma_f32 v[204:205], v[30:31], v[48:49], v[204:205] op_sel_hi:[1,0,1]
	v_pk_fma_f32 v[206:207], v[24:25], v[48:49], v[206:207] op_sel_hi:[1,0,1]
	v_pk_fma_f32 v[208:209], v[26:27], v[48:49], v[208:209] op_sel_hi:[1,0,1]
	v_cvt_pk_bf16_f32 v228, v200, v201
	v_cvt_pk_bf16_f32 v229, v204, v205
	v_cvt_pk_bf16_f32 v230, v206, v207
	v_cvt_pk_bf16_f32 v231, v208, v209
	v_add_u32_e32 v24, 0xa0, v198
	v_mad_i64_i32 v[24:25], s[36:37], s0, v24, 0
	v_lshl_add_u64 v[24:25], v[24:25], 1, v[164:165]
	s_cmp_gt_i32 s61, 1
	s_mov_b64 s[36:37], -1
	global_store_dwordx4 v[24:25], v[228:231], off
	s_andn2_b64 vcc, exec, s[36:37]
	s_cmp_eq_u32 s61, 1
	v_pk_fma_f32 v[200:201], v[40:41], v[48:49], v[56:57] op_sel:[0,1,0]
	v_pk_fma_f32 v[204:205], v[42:43], v[48:49], v[58:59] op_sel:[0,1,0]
	v_pk_fma_f32 v[206:207], v[32:33], v[48:49], v[44:45] op_sel:[0,1,0]
	v_pk_fma_f32 v[208:209], v[34:35], v[48:49], v[46:47] op_sel:[0,1,0]
	v_pk_fma_f32 v[200:201], v[20:21], v[48:49], v[200:201] op_sel_hi:[1,0,1]
	v_pk_fma_f32 v[204:205], v[22:23], v[48:49], v[204:205] op_sel_hi:[1,0,1]
	v_pk_fma_f32 v[206:207], v[16:17], v[48:49], v[206:207] op_sel_hi:[1,0,1]
	v_pk_fma_f32 v[208:209], v[18:19], v[48:49], v[208:209] op_sel_hi:[1,0,1]
	v_cvt_pk_bf16_f32 v232, v200, v201
	v_cvt_pk_bf16_f32 v233, v204, v205
	v_cvt_pk_bf16_f32 v234, v206, v207
	v_cvt_pk_bf16_f32 v235, v208, v209
	global_store_dwordx4 v[24:25], v[232:235], off offset:256
	s_cmp_gt_i32 s61, 1
	s_mov_b64 s[36:37], -1
	s_andn2_b64 vcc, exec, s[36:37]
	s_cmp_eq_u32 s61, 1
	v_pk_fma_f32 v[200:201], v[68:69], v[50:51], v[72:73] op_sel:[0,1,0]
	v_pk_fma_f32 v[204:205], v[70:71], v[50:51], v[74:75] op_sel:[0,1,0]
	v_pk_fma_f32 v[206:207], v[60:61], v[50:51], v[64:65] op_sel:[0,1,0]
	v_pk_fma_f32 v[208:209], v[62:63], v[50:51], v[66:67] op_sel:[0,1,0]
	v_pk_fma_f32 v[200:201], v[12:13], v[50:51], v[200:201] op_sel_hi:[1,0,1]
	v_pk_fma_f32 v[204:205], v[14:15], v[50:51], v[204:205] op_sel_hi:[1,0,1]
	v_pk_fma_f32 v[206:207], v[8:9], v[50:51], v[206:207] op_sel_hi:[1,0,1]
	v_pk_fma_f32 v[208:209], v[10:11], v[50:51], v[208:209] op_sel_hi:[1,0,1]
	v_cvt_pk_bf16_f32 v236, v200, v201
	v_cvt_pk_bf16_f32 v237, v204, v205
	v_cvt_pk_bf16_f32 v238, v206, v207
	v_cvt_pk_bf16_f32 v239, v208, v209
	v_add_u32_e32 v8, 0xb0, v198
	v_mad_i64_i32 v[8:9], s[36:37], s0, v8, 0
	v_lshl_add_u64 v[8:9], v[8:9], 1, v[164:165]
	global_store_dwordx4 v[8:9], v[236:239], off
	s_cmp_gt_i32 s61, 1
	s_mov_b64 s[36:37], -1
	s_andn2_b64 vcc, exec, s[36:37]
	s_cmp_eq_u32 s61, 1
	s_andn2_b64 vcc, exec, s[10:11]
	s_mov_b64 s[10:11], -1
	v_pk_fma_f32 v[200:201], v[40:41], v[50:51], v[56:57] op_sel:[0,1,0]
	v_pk_fma_f32 v[204:205], v[42:43], v[50:51], v[58:59] op_sel:[0,1,0]
	v_pk_fma_f32 v[206:207], v[32:33], v[50:51], v[44:45] op_sel:[0,1,0]
	v_pk_fma_f32 v[208:209], v[34:35], v[50:51], v[46:47] op_sel:[0,1,0]
	v_pk_fma_f32 v[200:201], v[4:5], v[50:51], v[200:201] op_sel_hi:[1,0,1]
	v_pk_fma_f32 v[204:205], v[6:7], v[50:51], v[204:205] op_sel_hi:[1,0,1]
	v_pk_fma_f32 v[206:207], v[0:1], v[50:51], v[206:207] op_sel_hi:[1,0,1]
	v_pk_fma_f32 v[208:209], v[2:3], v[50:51], v[208:209] op_sel_hi:[1,0,1]
	v_cvt_pk_bf16_f32 v240, v200, v201
	v_cvt_pk_bf16_f32 v241, v204, v205
	v_cvt_pk_bf16_f32 v242, v206, v207
	v_cvt_pk_bf16_f32 v243, v208, v209
	global_store_dwordx4 v[8:9], v[240:243], off offset:256
	s_branch .Le1end_18
.Le1m1_18:
	s_cmp_eq_u32 s36, s69
	s_movk_i32 s0, 0x200
	s_cselect_b32 s0, s0, 0x300
	s_cmp_lg_u32 s36, s68
	v_mov_b32_e32 v44, v192
	v_mov_b32_e32 v198, v193
	s_cselect_b32 s0, s0, 0x100
	s_cmp_lg_u32 s36, s35
	s_cselect_b32 s0, s0, 0
	v_lshl_add_u32 v45, v198, 5, s79
	v_add_u32_e32 v199, s70, v44
	ds_read_b128 v[68:71], v45
	ds_read_b128 v[60:63], v45 offset:16
	ds_read_b128 v[72:75], v45 offset:256
	ds_read_b128 v[64:67], v45 offset:272
	ds_read_b128 v[40:43], v45 offset:128
	ds_read_b128 v[32:35], v45 offset:144
	v_add_u32_e32 v44, s0, v199
	v_lshl_add_u32 v48, v44, 3, v197
	ds_read2_b64 v[172:175], v48 offset1:16
	ds_read_b128 v[56:59], v45 offset:384
	ds_read_b128 v[44:47], v45 offset:400
	ds_read2_b64 v[136:139], v48 offset0:32 offset1:48
	ds_read2_b64 v[100:103], v48 offset0:128 offset1:144
	ds_read2_b64 v[48:51], v48 offset0:160 offset1:176
	s_waitcnt lgkmcnt(0)
	s_cmp_gt_i32 s61, 1
	s_mov_b64 s[46:47], -1
	s_andn2_b64 vcc, exec, s[46:47]
	s_cmp_eq_u32 s61, 1
	s_add_i32 s0, s74, 0xfffff400
	s_lshl_b64 s[46:47], s[0:1], 1
	s_add_u32 s0, s56, s46
	s_addc_u32 s37, s57, s47
	s_ashr_i32 s75, s74, 31
	s_lshl_b64 s[46:47], s[74:75], 1
	s_add_u32 s46, s42, s46
	s_addc_u32 s47, s43, s47
	s_cmp_lt_i32 s40, 12
	s_cselect_b32 s0, s46, s0
	v_pk_fma_f32 v[200:201], v[68:69], v[172:173], v[72:73] op_sel:[0,1,0]
	v_pk_fma_f32 v[204:205], v[70:71], v[172:173], v[74:75] op_sel:[0,1,0]
	v_pk_fma_f32 v[206:207], v[60:61], v[172:173], v[64:65] op_sel:[0,1,0]
	v_pk_fma_f32 v[208:209], v[62:63], v[172:173], v[66:67] op_sel:[0,1,0]
	v_pk_fma_f32 v[200:201], v[168:169], v[172:173], v[200:201] op_sel_hi:[1,0,1]
	v_pk_fma_f32 v[204:205], v[170:171], v[172:173], v[204:205] op_sel_hi:[1,0,1]
	v_pk_fma_f32 v[206:207], v[164:165], v[172:173], v[206:207] op_sel_hi:[1,0,1]
	v_pk_fma_f32 v[208:209], v[166:167], v[172:173], v[208:209] op_sel_hi:[1,0,1]
	v_pk_mul_f32 v[200:201], v[200:201], s[34:35] op_sel_hi:[1,0]
	v_pk_mul_f32 v[204:205], v[204:205], s[34:35] op_sel_hi:[1,0]
	v_pk_mul_f32 v[206:207], v[206:207], s[34:35] op_sel_hi:[1,0]
	v_pk_mul_f32 v[208:209], v[208:209], s[34:35] op_sel_hi:[1,0]
	v_cvt_pk_bf16_f32 v216, v200, v201
	v_cvt_pk_bf16_f32 v217, v204, v205
	v_cvt_pk_bf16_f32 v218, v206, v207
	v_cvt_pk_bf16_f32 v219, v208, v209
	v_lshl_add_u32 v164, v198, 3, s71
	s_cselect_b32 s37, s47, s37
	v_mov_b32_e32 v166, s0
	s_movk_i32 s0, 0xc00
	v_mov_b32_e32 v167, s37
	s_cselect_b32 s0, s0, 0x800
	v_ashrrev_i32_e32 v165, 31, v164
	v_lshl_add_u32 v198, s36, 8, v199
	v_lshl_add_u64 v[164:165], v[164:165], 1, v[166:167]
	v_mad_i64_i32 v[166:167], s[36:37], s0, v198, 0
	v_lshl_add_u64 v[166:167], v[166:167], 1, v[164:165]
	s_cmp_gt_i32 s61, 1
	s_mov_b64 s[36:37], -1
	global_store_dwordx4 v[166:167], v[216:219], off
	s_andn2_b64 vcc, exec, s[36:37]
	s_cmp_eq_u32 s61, 1
	v_pk_fma_f32 v[200:201], v[40:41], v[172:173], v[56:57] op_sel:[0,1,0]
	v_pk_fma_f32 v[204:205], v[42:43], v[172:173], v[58:59] op_sel:[0,1,0]
	v_pk_fma_f32 v[206:207], v[32:33], v[172:173], v[44:45] op_sel:[0,1,0]
	v_pk_fma_f32 v[208:209], v[34:35], v[172:173], v[46:47] op_sel:[0,1,0]
	v_pk_fma_f32 v[200:201], v[160:161], v[172:173], v[200:201] op_sel_hi:[1,0,1]
	v_pk_fma_f32 v[204:205], v[162:163], v[172:173], v[204:205] op_sel_hi:[1,0,1]
	v_pk_fma_f32 v[206:207], v[156:157], v[172:173], v[206:207] op_sel_hi:[1,0,1]
	v_pk_fma_f32 v[208:209], v[158:159], v[172:173], v[208:209] op_sel_hi:[1,0,1]
	v_pk_mul_f32 v[200:201], v[200:201], s[34:35] op_sel_hi:[1,0]
	v_pk_mul_f32 v[204:205], v[204:205], s[34:35] op_sel_hi:[1,0]
	v_pk_mul_f32 v[206:207], v[206:207], s[34:35] op_sel_hi:[1,0]
	v_pk_mul_f32 v[208:209], v[208:209], s[34:35] op_sel_hi:[1,0]
	v_cvt_pk_bf16_f32 v220, v200, v201
	v_cvt_pk_bf16_f32 v221, v204, v205
	v_cvt_pk_bf16_f32 v222, v206, v207
	v_cvt_pk_bf16_f32 v223, v208, v209
	global_store_dwordx4 v[166:167], v[220:223], off offset:256
	s_cmp_gt_i32 s61, 1
	s_mov_b64 s[36:37], -1
	s_andn2_b64 vcc, exec, s[36:37]
	s_cmp_eq_u32 s61, 1
	v_pk_fma_f32 v[200:201], v[68:69], v[174:175], v[72:73] op_sel:[0,1,0]
	v_pk_fma_f32 v[204:205], v[70:71], v[174:175], v[74:75] op_sel:[0,1,0]
	v_pk_fma_f32 v[206:207], v[60:61], v[174:175], v[64:65] op_sel:[0,1,0]
	v_pk_fma_f32 v[208:209], v[62:63], v[174:175], v[66:67] op_sel:[0,1,0]
	v_pk_fma_f32 v[200:201], v[152:153], v[174:175], v[200:201] op_sel_hi:[1,0,1]
	v_pk_fma_f32 v[204:205], v[154:155], v[174:175], v[204:205] op_sel_hi:[1,0,1]
	v_pk_fma_f32 v[206:207], v[148:149], v[174:175], v[206:207] op_sel_hi:[1,0,1]
	v_pk_fma_f32 v[208:209], v[150:151], v[174:175], v[208:209] op_sel_hi:[1,0,1]
	v_pk_mul_f32 v[200:201], v[200:201], s[34:35] op_sel_hi:[1,0]
	v_pk_mul_f32 v[204:205], v[204:205], s[34:35] op_sel_hi:[1,0]
	v_pk_mul_f32 v[206:207], v[206:207], s[34:35] op_sel_hi:[1,0]
	v_pk_mul_f32 v[208:209], v[208:209], s[34:35] op_sel_hi:[1,0]
	v_cvt_pk_bf16_f32 v224, v200, v201
	v_cvt_pk_bf16_f32 v225, v204, v205
	v_cvt_pk_bf16_f32 v226, v206, v207
	v_cvt_pk_bf16_f32 v227, v208, v209
	v_add_u32_e32 v148, 16, v198
	v_mad_i64_i32 v[148:149], s[36:37], s0, v148, 0
	v_lshl_add_u64 v[148:149], v[148:149], 1, v[164:165]
	global_store_dwordx4 v[148:149], v[224:227], off
	s_cmp_gt_i32 s61, 1
	s_mov_b64 s[36:37], -1
	s_andn2_b64 vcc, exec, s[36:37]
	s_cmp_eq_u32 s61, 1
	v_pk_fma_f32 v[200:201], v[40:41], v[174:175], v[56:57] op_sel:[0,1,0]
	v_pk_fma_f32 v[204:205], v[42:43], v[174:175], v[58:59] op_sel:[0,1,0]
	v_pk_fma_f32 v[206:207], v[32:33], v[174:175], v[44:45] op_sel:[0,1,0]
	v_pk_fma_f32 v[208:209], v[34:35], v[174:175], v[46:47] op_sel:[0,1,0]
	v_pk_fma_f32 v[200:201], v[144:145], v[174:175], v[200:201] op_sel_hi:[1,0,1]
	v_pk_fma_f32 v[204:205], v[146:147], v[174:175], v[204:205] op_sel_hi:[1,0,1]
	v_pk_fma_f32 v[206:207], v[140:141], v[174:175], v[206:207] op_sel_hi:[1,0,1]
	v_pk_fma_f32 v[208:209], v[142:143], v[174:175], v[208:209] op_sel_hi:[1,0,1]
	v_pk_mul_f32 v[200:201], v[200:201], s[34:35] op_sel_hi:[1,0]
	v_pk_mul_f32 v[204:205], v[204:205], s[34:35] op_sel_hi:[1,0]
	v_pk_mul_f32 v[206:207], v[206:207], s[34:35] op_sel_hi:[1,0]
	v_pk_mul_f32 v[208:209], v[208:209], s[34:35] op_sel_hi:[1,0]
	v_cvt_pk_bf16_f32 v228, v200, v201
	v_cvt_pk_bf16_f32 v229, v204, v205
	v_cvt_pk_bf16_f32 v230, v206, v207
	v_cvt_pk_bf16_f32 v231, v208, v209
	global_store_dwordx4 v[148:149], v[228:231], off offset:256
	s_cmp_gt_i32 s61, 1
	s_mov_b64 s[36:37], -1
	s_andn2_b64 vcc, exec, s[36:37]
	s_cmp_eq_u32 s61, 1
	v_pk_fma_f32 v[200:201], v[68:69], v[136:137], v[72:73] op_sel:[0,1,0]
	v_pk_fma_f32 v[204:205], v[70:71], v[136:137], v[74:75] op_sel:[0,1,0]
	v_pk_fma_f32 v[206:207], v[60:61], v[136:137], v[64:65] op_sel:[0,1,0]
	v_pk_fma_f32 v[208:209], v[62:63], v[136:137], v[66:67] op_sel:[0,1,0]
	v_pk_fma_f32 v[200:201], v[132:133], v[136:137], v[200:201] op_sel_hi:[1,0,1]
	v_pk_fma_f32 v[204:205], v[134:135], v[136:137], v[204:205] op_sel_hi:[1,0,1]
	v_pk_fma_f32 v[206:207], v[128:129], v[136:137], v[206:207] op_sel_hi:[1,0,1]
	v_pk_fma_f32 v[208:209], v[130:131], v[136:137], v[208:209] op_sel_hi:[1,0,1]
	v_pk_mul_f32 v[200:201], v[200:201], s[34:35] op_sel_hi:[1,0]
	v_pk_mul_f32 v[204:205], v[204:205], s[34:35] op_sel_hi:[1,0]
	v_pk_mul_f32 v[206:207], v[206:207], s[34:35] op_sel_hi:[1,0]
	v_pk_mul_f32 v[208:209], v[208:209], s[34:35] op_sel_hi:[1,0]
	v_cvt_pk_bf16_f32 v232, v200, v201
	v_cvt_pk_bf16_f32 v233, v204, v205
	v_cvt_pk_bf16_f32 v234, v206, v207
	v_cvt_pk_bf16_f32 v235, v208, v209
	v_add_u32_e32 v128, 32, v198
	v_mad_i64_i32 v[128:129], s[36:37], s0, v128, 0
	v_lshl_add_u64 v[128:129], v[128:129], 1, v[164:165]
	s_cmp_gt_i32 s61, 1
	s_mov_b64 s[36:37], -1
	global_store_dwordx4 v[128:129], v[232:235], off
	s_andn2_b64 vcc, exec, s[36:37]
	s_cmp_eq_u32 s61, 1
	v_pk_fma_f32 v[200:201], v[40:41], v[136:137], v[56:57] op_sel:[0,1,0]
	v_pk_fma_f32 v[204:205], v[42:43], v[136:137], v[58:59] op_sel:[0,1,0]
	v_pk_fma_f32 v[206:207], v[32:33], v[136:137], v[44:45] op_sel:[0,1,0]
	v_pk_fma_f32 v[208:209], v[34:35], v[136:137], v[46:47] op_sel:[0,1,0]
	v_pk_fma_f32 v[200:201], v[124:125], v[136:137], v[200:201] op_sel_hi:[1,0,1]
	v_pk_fma_f32 v[204:205], v[126:127], v[136:137], v[204:205] op_sel_hi:[1,0,1]
	v_pk_fma_f32 v[206:207], v[120:121], v[136:137], v[206:207] op_sel_hi:[1,0,1]
	v_pk_fma_f32 v[208:209], v[122:123], v[136:137], v[208:209] op_sel_hi:[1,0,1]
	v_pk_mul_f32 v[200:201], v[200:201], s[34:35] op_sel_hi:[1,0]
	v_pk_mul_f32 v[204:205], v[204:205], s[34:35] op_sel_hi:[1,0]
	v_pk_mul_f32 v[206:207], v[206:207], s[34:35] op_sel_hi:[1,0]
	v_pk_mul_f32 v[208:209], v[208:209], s[34:35] op_sel_hi:[1,0]
	v_cvt_pk_bf16_f32 v236, v200, v201
	v_cvt_pk_bf16_f32 v237, v204, v205
	v_cvt_pk_bf16_f32 v238, v206, v207
	v_cvt_pk_bf16_f32 v239, v208, v209
	global_store_dwordx4 v[128:129], v[236:239], off offset:256
	s_cmp_gt_i32 s61, 1
	s_mov_b64 s[36:37], -1
	s_andn2_b64 vcc, exec, s[36:37]
	s_cmp_eq_u32 s61, 1
	v_pk_fma_f32 v[200:201], v[68:69], v[138:139], v[72:73] op_sel:[0,1,0]
	v_pk_fma_f32 v[204:205], v[70:71], v[138:139], v[74:75] op_sel:[0,1,0]
	v_pk_fma_f32 v[206:207], v[60:61], v[138:139], v[64:65] op_sel:[0,1,0]
	v_pk_fma_f32 v[208:209], v[62:63], v[138:139], v[66:67] op_sel:[0,1,0]
	v_pk_fma_f32 v[200:201], v[116:117], v[138:139], v[200:201] op_sel_hi:[1,0,1]
	v_pk_fma_f32 v[204:205], v[118:119], v[138:139], v[204:205] op_sel_hi:[1,0,1]
	v_pk_fma_f32 v[206:207], v[112:113], v[138:139], v[206:207] op_sel_hi:[1,0,1]
	v_pk_fma_f32 v[208:209], v[114:115], v[138:139], v[208:209] op_sel_hi:[1,0,1]
	v_pk_mul_f32 v[200:201], v[200:201], s[34:35] op_sel_hi:[1,0]
	v_pk_mul_f32 v[204:205], v[204:205], s[34:35] op_sel_hi:[1,0]
	v_pk_mul_f32 v[206:207], v[206:207], s[34:35] op_sel_hi:[1,0]
	v_pk_mul_f32 v[208:209], v[208:209], s[34:35] op_sel_hi:[1,0]
	v_cvt_pk_bf16_f32 v240, v200, v201
	v_cvt_pk_bf16_f32 v241, v204, v205
	v_cvt_pk_bf16_f32 v242, v206, v207
	v_cvt_pk_bf16_f32 v243, v208, v209
	v_add_u32_e32 v112, 48, v198
	v_mad_i64_i32 v[112:113], s[36:37], s0, v112, 0
	v_lshl_add_u64 v[112:113], v[112:113], 1, v[164:165]
	global_store_dwordx4 v[112:113], v[240:243], off
	s_cmp_gt_i32 s61, 1
	s_mov_b64 s[36:37], -1
	s_andn2_b64 vcc, exec, s[36:37]
	s_cmp_eq_u32 s61, 1
	v_pk_fma_f32 v[200:201], v[40:41], v[138:139], v[56:57] op_sel:[0,1,0]
	v_pk_fma_f32 v[204:205], v[42:43], v[138:139], v[58:59] op_sel:[0,1,0]
	v_pk_fma_f32 v[206:207], v[32:33], v[138:139], v[44:45] op_sel:[0,1,0]
	v_pk_fma_f32 v[208:209], v[34:35], v[138:139], v[46:47] op_sel:[0,1,0]
	v_pk_fma_f32 v[200:201], v[108:109], v[138:139], v[200:201] op_sel_hi:[1,0,1]
	v_pk_fma_f32 v[204:205], v[110:111], v[138:139], v[204:205] op_sel_hi:[1,0,1]
	v_pk_fma_f32 v[206:207], v[104:105], v[138:139], v[206:207] op_sel_hi:[1,0,1]
	v_pk_fma_f32 v[208:209], v[106:107], v[138:139], v[208:209] op_sel_hi:[1,0,1]
	v_pk_mul_f32 v[200:201], v[200:201], s[34:35] op_sel_hi:[1,0]
	v_pk_mul_f32 v[204:205], v[204:205], s[34:35] op_sel_hi:[1,0]
	v_pk_mul_f32 v[206:207], v[206:207], s[34:35] op_sel_hi:[1,0]
	v_pk_mul_f32 v[208:209], v[208:209], s[34:35] op_sel_hi:[1,0]
	v_cvt_pk_bf16_f32 v244, v200, v201
	v_cvt_pk_bf16_f32 v245, v204, v205
	v_cvt_pk_bf16_f32 v246, v206, v207
	v_cvt_pk_bf16_f32 v247, v208, v209
	global_store_dwordx4 v[112:113], v[244:247], off offset:256
	s_cmp_gt_i32 s61, 1
	s_mov_b64 s[36:37], -1
	s_andn2_b64 vcc, exec, s[36:37]
	s_cmp_eq_u32 s61, 1
	v_pk_fma_f32 v[200:201], v[68:69], v[100:101], v[72:73] op_sel:[0,1,0]
	v_pk_fma_f32 v[204:205], v[70:71], v[100:101], v[74:75] op_sel:[0,1,0]
	v_pk_fma_f32 v[206:207], v[60:61], v[100:101], v[64:65] op_sel:[0,1,0]
	v_pk_fma_f32 v[208:209], v[62:63], v[100:101], v[66:67] op_sel:[0,1,0]
	v_pk_fma_f32 v[200:201], v[96:97], v[100:101], v[200:201] op_sel_hi:[1,0,1]
	v_pk_fma_f32 v[204:205], v[98:99], v[100:101], v[204:205] op_sel_hi:[1,0,1]
	v_pk_fma_f32 v[206:207], v[92:93], v[100:101], v[206:207] op_sel_hi:[1,0,1]
	v_pk_fma_f32 v[208:209], v[94:95], v[100:101], v[208:209] op_sel_hi:[1,0,1]
	v_pk_mul_f32 v[200:201], v[200:201], s[34:35] op_sel_hi:[1,0]
	v_pk_mul_f32 v[204:205], v[204:205], s[34:35] op_sel_hi:[1,0]
	v_pk_mul_f32 v[206:207], v[206:207], s[34:35] op_sel_hi:[1,0]
	v_pk_mul_f32 v[208:209], v[208:209], s[34:35] op_sel_hi:[1,0]
	v_cvt_pk_bf16_f32 v248, v200, v201
	v_cvt_pk_bf16_f32 v249, v204, v205
	v_cvt_pk_bf16_f32 v250, v206, v207
	v_cvt_pk_bf16_f32 v251, v208, v209
	v_add_u32_e32 v92, 0x80, v198
	v_mad_i64_i32 v[92:93], s[36:37], s0, v92, 0
	v_lshl_add_u64 v[92:93], v[92:93], 1, v[164:165]
	s_cmp_gt_i32 s61, 1
	s_mov_b64 s[36:37], -1
	global_store_dwordx4 v[92:93], v[248:251], off
	s_andn2_b64 vcc, exec, s[36:37]
	s_cmp_eq_u32 s61, 1
	v_pk_fma_f32 v[200:201], v[40:41], v[100:101], v[56:57] op_sel:[0,1,0]
	v_pk_fma_f32 v[204:205], v[42:43], v[100:101], v[58:59] op_sel:[0,1,0]
	v_pk_fma_f32 v[206:207], v[32:33], v[100:101], v[44:45] op_sel:[0,1,0]
	v_pk_fma_f32 v[208:209], v[34:35], v[100:101], v[46:47] op_sel:[0,1,0]
	v_pk_fma_f32 v[200:201], v[88:89], v[100:101], v[200:201] op_sel_hi:[1,0,1]
	v_pk_fma_f32 v[204:205], v[90:91], v[100:101], v[204:205] op_sel_hi:[1,0,1]
	v_pk_fma_f32 v[206:207], v[84:85], v[100:101], v[206:207] op_sel_hi:[1,0,1]
	v_pk_fma_f32 v[208:209], v[86:87], v[100:101], v[208:209] op_sel_hi:[1,0,1]
	v_pk_mul_f32 v[200:201], v[200:201], s[34:35] op_sel_hi:[1,0]
	v_pk_mul_f32 v[204:205], v[204:205], s[34:35] op_sel_hi:[1,0]
	v_pk_mul_f32 v[206:207], v[206:207], s[34:35] op_sel_hi:[1,0]
	v_pk_mul_f32 v[208:209], v[208:209], s[34:35] op_sel_hi:[1,0]
	v_cvt_pk_bf16_f32 v216, v200, v201
	v_cvt_pk_bf16_f32 v217, v204, v205
	v_cvt_pk_bf16_f32 v218, v206, v207
	v_cvt_pk_bf16_f32 v219, v208, v209
	global_store_dwordx4 v[92:93], v[216:219], off offset:256
	s_cmp_gt_i32 s61, 1
	s_mov_b64 s[36:37], -1
	s_andn2_b64 vcc, exec, s[36:37]
	s_cmp_eq_u32 s61, 1
	v_pk_fma_f32 v[200:201], v[68:69], v[102:103], v[72:73] op_sel:[0,1,0]
	v_pk_fma_f32 v[204:205], v[70:71], v[102:103], v[74:75] op_sel:[0,1,0]
	v_pk_fma_f32 v[206:207], v[60:61], v[102:103], v[64:65] op_sel:[0,1,0]
	v_pk_fma_f32 v[208:209], v[62:63], v[102:103], v[66:67] op_sel:[0,1,0]
	v_pk_fma_f32 v[200:201], v[80:81], v[102:103], v[200:201] op_sel_hi:[1,0,1]
	v_pk_fma_f32 v[204:205], v[82:83], v[102:103], v[204:205] op_sel_hi:[1,0,1]
	v_pk_fma_f32 v[206:207], v[76:77], v[102:103], v[206:207] op_sel_hi:[1,0,1]
	v_pk_fma_f32 v[208:209], v[78:79], v[102:103], v[208:209] op_sel_hi:[1,0,1]
	v_pk_mul_f32 v[200:201], v[200:201], s[34:35] op_sel_hi:[1,0]
	v_pk_mul_f32 v[204:205], v[204:205], s[34:35] op_sel_hi:[1,0]
	v_pk_mul_f32 v[206:207], v[206:207], s[34:35] op_sel_hi:[1,0]
	v_pk_mul_f32 v[208:209], v[208:209], s[34:35] op_sel_hi:[1,0]
	v_cvt_pk_bf16_f32 v220, v200, v201
	v_cvt_pk_bf16_f32 v221, v204, v205
	v_cvt_pk_bf16_f32 v222, v206, v207
	v_cvt_pk_bf16_f32 v223, v208, v209
	v_add_u32_e32 v76, 0x90, v198
	v_mad_i64_i32 v[76:77], s[36:37], s0, v76, 0
	v_lshl_add_u64 v[76:77], v[76:77], 1, v[164:165]
	global_store_dwordx4 v[76:77], v[220:223], off
	s_cmp_gt_i32 s61, 1
	s_mov_b64 s[36:37], -1
	s_andn2_b64 vcc, exec, s[36:37]
	s_cmp_eq_u32 s61, 1
	v_pk_fma_f32 v[200:201], v[40:41], v[102:103], v[56:57] op_sel:[0,1,0]
	v_pk_fma_f32 v[204:205], v[42:43], v[102:103], v[58:59] op_sel:[0,1,0]
	v_pk_fma_f32 v[206:207], v[32:33], v[102:103], v[44:45] op_sel:[0,1,0]
	v_pk_fma_f32 v[208:209], v[34:35], v[102:103], v[46:47] op_sel:[0,1,0]
	v_pk_fma_f32 v[200:201], v[52:53], v[102:103], v[200:201] op_sel_hi:[1,0,1]
	v_pk_fma_f32 v[204:205], v[54:55], v[102:103], v[204:205] op_sel_hi:[1,0,1]
	v_pk_fma_f32 v[206:207], v[36:37], v[102:103], v[206:207] op_sel_hi:[1,0,1]
	v_pk_fma_f32 v[208:209], v[38:39], v[102:103], v[208:209] op_sel_hi:[1,0,1]
	v_pk_mul_f32 v[200:201], v[200:201], s[34:35] op_sel_hi:[1,0]
	v_pk_mul_f32 v[204:205], v[204:205], s[34:35] op_sel_hi:[1,0]
	v_pk_mul_f32 v[206:207], v[206:207], s[34:35] op_sel_hi:[1,0]
	v_pk_mul_f32 v[208:209], v[208:209], s[34:35] op_sel_hi:[1,0]
	v_cvt_pk_bf16_f32 v224, v200, v201
	v_cvt_pk_bf16_f32 v225, v204, v205
	v_cvt_pk_bf16_f32 v226, v206, v207
	v_cvt_pk_bf16_f32 v227, v208, v209
	global_store_dwordx4 v[76:77], v[224:227], off offset:256
	s_cmp_gt_i32 s61, 1
	s_mov_b64 s[36:37], -1
	s_andn2_b64 vcc, exec, s[36:37]
	s_cmp_eq_u32 s61, 1
	v_pk_fma_f32 v[200:201], v[68:69], v[48:49], v[72:73] op_sel:[0,1,0]
	v_pk_fma_f32 v[204:205], v[70:71], v[48:49], v[74:75] op_sel:[0,1,0]
	v_pk_fma_f32 v[206:207], v[60:61], v[48:49], v[64:65] op_sel:[0,1,0]
	v_pk_fma_f32 v[208:209], v[62:63], v[48:49], v[66:67] op_sel:[0,1,0]
	v_pk_fma_f32 v[200:201], v[28:29], v[48:49], v[200:201] op_sel_hi:[1,0,1]
	v_pk_fma_f32 v[204:205], v[30:31], v[48:49], v[204:205] op_sel_hi:[1,0,1]
	v_pk_fma_f32 v[206:207], v[24:25], v[48:49], v[206:207] op_sel_hi:[1,0,1]
	v_pk_fma_f32 v[208:209], v[26:27], v[48:49], v[208:209] op_sel_hi:[1,0,1]
	v_pk_mul_f32 v[200:201], v[200:201], s[34:35] op_sel_hi:[1,0]
	v_pk_mul_f32 v[204:205], v[204:205], s[34:35] op_sel_hi:[1,0]
	v_pk_mul_f32 v[206:207], v[206:207], s[34:35] op_sel_hi:[1,0]
	v_pk_mul_f32 v[208:209], v[208:209], s[34:35] op_sel_hi:[1,0]
	v_cvt_pk_bf16_f32 v228, v200, v201
	v_cvt_pk_bf16_f32 v229, v204, v205
	v_cvt_pk_bf16_f32 v230, v206, v207
	v_cvt_pk_bf16_f32 v231, v208, v209
	v_add_u32_e32 v24, 0xa0, v198
	v_mad_i64_i32 v[24:25], s[36:37], s0, v24, 0
	v_lshl_add_u64 v[24:25], v[24:25], 1, v[164:165]
	s_cmp_gt_i32 s61, 1
	s_mov_b64 s[36:37], -1
	global_store_dwordx4 v[24:25], v[228:231], off
	s_andn2_b64 vcc, exec, s[36:37]
	s_cmp_eq_u32 s61, 1
	v_pk_fma_f32 v[200:201], v[40:41], v[48:49], v[56:57] op_sel:[0,1,0]
	v_pk_fma_f32 v[204:205], v[42:43], v[48:49], v[58:59] op_sel:[0,1,0]
	v_pk_fma_f32 v[206:207], v[32:33], v[48:49], v[44:45] op_sel:[0,1,0]
	v_pk_fma_f32 v[208:209], v[34:35], v[48:49], v[46:47] op_sel:[0,1,0]
	v_pk_fma_f32 v[200:201], v[20:21], v[48:49], v[200:201] op_sel_hi:[1,0,1]
	v_pk_fma_f32 v[204:205], v[22:23], v[48:49], v[204:205] op_sel_hi:[1,0,1]
	v_pk_fma_f32 v[206:207], v[16:17], v[48:49], v[206:207] op_sel_hi:[1,0,1]
	v_pk_fma_f32 v[208:209], v[18:19], v[48:49], v[208:209] op_sel_hi:[1,0,1]
	v_pk_mul_f32 v[200:201], v[200:201], s[34:35] op_sel_hi:[1,0]
	v_pk_mul_f32 v[204:205], v[204:205], s[34:35] op_sel_hi:[1,0]
	v_pk_mul_f32 v[206:207], v[206:207], s[34:35] op_sel_hi:[1,0]
	v_pk_mul_f32 v[208:209], v[208:209], s[34:35] op_sel_hi:[1,0]
	v_cvt_pk_bf16_f32 v232, v200, v201
	v_cvt_pk_bf16_f32 v233, v204, v205
	v_cvt_pk_bf16_f32 v234, v206, v207
	v_cvt_pk_bf16_f32 v235, v208, v209
	global_store_dwordx4 v[24:25], v[232:235], off offset:256
	s_cmp_gt_i32 s61, 1
	s_mov_b64 s[36:37], -1
	s_andn2_b64 vcc, exec, s[36:37]
	s_cmp_eq_u32 s61, 1
	v_pk_fma_f32 v[200:201], v[68:69], v[50:51], v[72:73] op_sel:[0,1,0]
	v_pk_fma_f32 v[204:205], v[70:71], v[50:51], v[74:75] op_sel:[0,1,0]
	v_pk_fma_f32 v[206:207], v[60:61], v[50:51], v[64:65] op_sel:[0,1,0]
	v_pk_fma_f32 v[208:209], v[62:63], v[50:51], v[66:67] op_sel:[0,1,0]
	v_pk_fma_f32 v[200:201], v[12:13], v[50:51], v[200:201] op_sel_hi:[1,0,1]
	v_pk_fma_f32 v[204:205], v[14:15], v[50:51], v[204:205] op_sel_hi:[1,0,1]
	v_pk_fma_f32 v[206:207], v[8:9], v[50:51], v[206:207] op_sel_hi:[1,0,1]
	v_pk_fma_f32 v[208:209], v[10:11], v[50:51], v[208:209] op_sel_hi:[1,0,1]
	v_pk_mul_f32 v[200:201], v[200:201], s[34:35] op_sel_hi:[1,0]
	v_pk_mul_f32 v[204:205], v[204:205], s[34:35] op_sel_hi:[1,0]
	v_pk_mul_f32 v[206:207], v[206:207], s[34:35] op_sel_hi:[1,0]
	v_pk_mul_f32 v[208:209], v[208:209], s[34:35] op_sel_hi:[1,0]
	v_cvt_pk_bf16_f32 v236, v200, v201
	v_cvt_pk_bf16_f32 v237, v204, v205
	v_cvt_pk_bf16_f32 v238, v206, v207
	v_cvt_pk_bf16_f32 v239, v208, v209
	v_add_u32_e32 v8, 0xb0, v198
	v_mad_i64_i32 v[8:9], s[36:37], s0, v8, 0
	v_lshl_add_u64 v[8:9], v[8:9], 1, v[164:165]
	global_store_dwordx4 v[8:9], v[236:239], off
	s_cmp_gt_i32 s61, 1
	s_mov_b64 s[36:37], -1
	s_andn2_b64 vcc, exec, s[36:37]
	s_cmp_eq_u32 s61, 1
	s_andn2_b64 vcc, exec, s[10:11]
	s_mov_b64 s[10:11], -1
	v_pk_fma_f32 v[200:201], v[40:41], v[50:51], v[56:57] op_sel:[0,1,0]
	v_pk_fma_f32 v[204:205], v[42:43], v[50:51], v[58:59] op_sel:[0,1,0]
	v_pk_fma_f32 v[206:207], v[32:33], v[50:51], v[44:45] op_sel:[0,1,0]
	v_pk_fma_f32 v[208:209], v[34:35], v[50:51], v[46:47] op_sel:[0,1,0]
	v_pk_fma_f32 v[200:201], v[4:5], v[50:51], v[200:201] op_sel_hi:[1,0,1]
	v_pk_fma_f32 v[204:205], v[6:7], v[50:51], v[204:205] op_sel_hi:[1,0,1]
	v_pk_fma_f32 v[206:207], v[0:1], v[50:51], v[206:207] op_sel_hi:[1,0,1]
	v_pk_fma_f32 v[208:209], v[2:3], v[50:51], v[208:209] op_sel_hi:[1,0,1]
	v_pk_mul_f32 v[200:201], v[200:201], s[34:35] op_sel_hi:[1,0]
	v_pk_mul_f32 v[204:205], v[204:205], s[34:35] op_sel_hi:[1,0]
	v_pk_mul_f32 v[206:207], v[206:207], s[34:35] op_sel_hi:[1,0]
	v_pk_mul_f32 v[208:209], v[208:209], s[34:35] op_sel_hi:[1,0]
	v_cvt_pk_bf16_f32 v240, v200, v201
	v_cvt_pk_bf16_f32 v241, v204, v205
	v_cvt_pk_bf16_f32 v242, v206, v207
	v_cvt_pk_bf16_f32 v243, v208, v209
	global_store_dwordx4 v[8:9], v[240:243], off offset:256
	s_branch .Le1end_18
.Le1m2_18:
	v_mov_b32_e32 v200, 0xbfb8aa3b
	v_mov_b32_e32 v201, 1.0
	s_cmp_eq_u32 s36, s69
	s_movk_i32 s0, 0x200
	s_cselect_b32 s0, s0, 0x300
	s_cmp_lg_u32 s36, s68
	v_mov_b32_e32 v44, v192
	v_mov_b32_e32 v198, v193
	s_cselect_b32 s0, s0, 0x100
	s_cmp_lg_u32 s36, s35
	s_cselect_b32 s0, s0, 0
	v_lshl_add_u32 v45, v198, 5, s79
	v_add_u32_e32 v199, s70, v44
	ds_read_b128 v[68:71], v45
	ds_read_b128 v[60:63], v45 offset:16
	ds_read_b128 v[72:75], v45 offset:256
	ds_read_b128 v[64:67], v45 offset:272
	ds_read_b128 v[40:43], v45 offset:128
	ds_read_b128 v[32:35], v45 offset:144
	v_add_u32_e32 v44, s0, v199
	v_lshl_add_u32 v48, v44, 3, v197
	ds_read2_b64 v[172:175], v48 offset1:16
	ds_read_b128 v[56:59], v45 offset:384
	ds_read_b128 v[44:47], v45 offset:400
	ds_read2_b64 v[136:139], v48 offset0:32 offset1:48
	ds_read2_b64 v[100:103], v48 offset0:128 offset1:144
	ds_read2_b64 v[48:51], v48 offset0:160 offset1:176
	s_waitcnt lgkmcnt(0)
	s_cmp_gt_i32 s61, 1
	s_mov_b64 s[46:47], -1
	s_mov_b64 s[46:47], 0
	s_andn2_b64 vcc, exec, s[46:47]
	s_add_i32 s0, s74, 0xfffff400
	s_lshl_b64 s[46:47], s[0:1], 1
	s_add_u32 s0, s56, s46
	s_addc_u32 s37, s57, s47
	s_ashr_i32 s75, s74, 31
	s_lshl_b64 s[46:47], s[74:75], 1
	s_add_u32 s46, s42, s46
	s_addc_u32 s47, s43, s47
	s_cmp_lt_i32 s40, 12
	s_cselect_b32 s0, s46, s0
	v_pk_fma_f32 v[204:205], v[68:69], v[172:173], v[72:73] op_sel:[0,1,0]
	v_pk_fma_f32 v[206:207], v[70:71], v[172:173], v[74:75] op_sel:[0,1,0]
	v_pk_fma_f32 v[208:209], v[60:61], v[172:173], v[64:65] op_sel:[0,1,0]
	v_pk_fma_f32 v[210:211], v[62:63], v[172:173], v[66:67] op_sel:[0,1,0]
	v_pk_fma_f32 v[204:205], v[168:169], v[172:173], v[204:205] op_sel_hi:[1,0,1]
	v_pk_fma_f32 v[206:207], v[170:171], v[172:173], v[206:207] op_sel_hi:[1,0,1]
	v_pk_fma_f32 v[208:209], v[164:165], v[172:173], v[208:209] op_sel_hi:[1,0,1]
	v_pk_fma_f32 v[210:211], v[166:167], v[172:173], v[210:211] op_sel_hi:[1,0,1]
	v_pk_mul_f32 v[216:217], v[204:205], v[200:201] op_sel_hi:[1,0]
	v_pk_mul_f32 v[218:219], v[206:207], v[200:201] op_sel_hi:[1,0]
	v_pk_mul_f32 v[220:221], v[208:209], v[200:201] op_sel_hi:[1,0]
	v_pk_mul_f32 v[222:223], v[210:211], v[200:201] op_sel_hi:[1,0]
	v_exp_f32_e32 v216, v216
	v_exp_f32_e32 v217, v217
	v_exp_f32_e32 v218, v218
	v_exp_f32_e32 v219, v219
	v_exp_f32_e32 v220, v220
	v_exp_f32_e32 v221, v221
	v_exp_f32_e32 v222, v222
	v_exp_f32_e32 v223, v223
	v_pk_add_f32 v[216:217], v[216:217], v[200:201] op_sel:[0,1] op_sel_hi:[1,1]
	v_pk_add_f32 v[218:219], v[218:219], v[200:201] op_sel:[0,1] op_sel_hi:[1,1]
	v_pk_add_f32 v[220:221], v[220:221], v[200:201] op_sel:[0,1] op_sel_hi:[1,1]
	v_pk_add_f32 v[222:223], v[222:223], v[200:201] op_sel:[0,1] op_sel_hi:[1,1]
	v_rcp_f32_e32 v216, v216
	v_rcp_f32_e32 v217, v217
	v_rcp_f32_e32 v218, v218
	v_rcp_f32_e32 v219, v219
	v_rcp_f32_e32 v220, v220
	v_rcp_f32_e32 v221, v221
	v_rcp_f32_e32 v222, v222
	v_rcp_f32_e32 v223, v223
	v_cvt_pk_bf16_f32 v224, v216, v217
	v_cvt_pk_bf16_f32 v225, v218, v219
	v_cvt_pk_bf16_f32 v226, v220, v221
	v_cvt_pk_bf16_f32 v227, v222, v223
	v_lshl_add_u32 v164, v198, 3, s71
	s_cselect_b32 s37, s47, s37
	v_mov_b32_e32 v166, s0
	s_movk_i32 s0, 0xc00
	v_mov_b32_e32 v167, s37
	s_cselect_b32 s0, s0, 0x800
	v_ashrrev_i32_e32 v165, 31, v164
	v_lshl_add_u32 v198, s36, 8, v199
	v_lshl_add_u64 v[164:165], v[164:165], 1, v[166:167]
	v_mad_i64_i32 v[166:167], s[36:37], s0, v198, 0
	v_lshl_add_u64 v[166:167], v[166:167], 1, v[164:165]
	s_cmp_gt_i32 s61, 1
	s_mov_b64 s[36:37], -1
	global_store_dwordx4 v[166:167], v[224:227], off
	s_mov_b64 s[36:37], 0
	s_andn2_b64 vcc, exec, s[36:37]
	v_pk_fma_f32 v[204:205], v[40:41], v[172:173], v[56:57] op_sel:[0,1,0]
	v_pk_fma_f32 v[206:207], v[42:43], v[172:173], v[58:59] op_sel:[0,1,0]
	v_pk_fma_f32 v[208:209], v[32:33], v[172:173], v[44:45] op_sel:[0,1,0]
	v_pk_fma_f32 v[210:211], v[34:35], v[172:173], v[46:47] op_sel:[0,1,0]
	v_pk_fma_f32 v[204:205], v[160:161], v[172:173], v[204:205] op_sel_hi:[1,0,1]
	v_pk_fma_f32 v[206:207], v[162:163], v[172:173], v[206:207] op_sel_hi:[1,0,1]
	v_pk_fma_f32 v[208:209], v[156:157], v[172:173], v[208:209] op_sel_hi:[1,0,1]
	v_pk_fma_f32 v[210:211], v[158:159], v[172:173], v[210:211] op_sel_hi:[1,0,1]
	v_pk_mul_f32 v[216:217], v[204:205], v[200:201] op_sel_hi:[1,0]
	v_pk_mul_f32 v[218:219], v[206:207], v[200:201] op_sel_hi:[1,0]
	v_pk_mul_f32 v[220:221], v[208:209], v[200:201] op_sel_hi:[1,0]
	v_pk_mul_f32 v[222:223], v[210:211], v[200:201] op_sel_hi:[1,0]
	v_exp_f32_e32 v216, v216
	v_exp_f32_e32 v217, v217
	v_exp_f32_e32 v218, v218
	v_exp_f32_e32 v219, v219
	v_exp_f32_e32 v220, v220
	v_exp_f32_e32 v221, v221
	v_exp_f32_e32 v222, v222
	v_exp_f32_e32 v223, v223
	v_pk_add_f32 v[216:217], v[216:217], v[200:201] op_sel:[0,1] op_sel_hi:[1,1]
	v_pk_add_f32 v[218:219], v[218:219], v[200:201] op_sel:[0,1] op_sel_hi:[1,1]
	v_pk_add_f32 v[220:221], v[220:221], v[200:201] op_sel:[0,1] op_sel_hi:[1,1]
	v_pk_add_f32 v[222:223], v[222:223], v[200:201] op_sel:[0,1] op_sel_hi:[1,1]
	v_rcp_f32_e32 v216, v216
	v_rcp_f32_e32 v217, v217
	v_rcp_f32_e32 v218, v218
	v_rcp_f32_e32 v219, v219
	v_rcp_f32_e32 v220, v220
	v_rcp_f32_e32 v221, v221
	v_rcp_f32_e32 v222, v222
	v_rcp_f32_e32 v223, v223
	v_cvt_pk_bf16_f32 v228, v216, v217
	v_cvt_pk_bf16_f32 v229, v218, v219
	v_cvt_pk_bf16_f32 v230, v220, v221
	v_cvt_pk_bf16_f32 v231, v222, v223
	global_store_dwordx4 v[166:167], v[228:231], off offset:256
	s_cmp_gt_i32 s61, 1
	s_mov_b64 s[36:37], -1
	s_mov_b64 s[36:37], 0
	s_andn2_b64 vcc, exec, s[36:37]
	v_pk_fma_f32 v[204:205], v[68:69], v[174:175], v[72:73] op_sel:[0,1,0]
	v_pk_fma_f32 v[206:207], v[70:71], v[174:175], v[74:75] op_sel:[0,1,0]
	v_pk_fma_f32 v[208:209], v[60:61], v[174:175], v[64:65] op_sel:[0,1,0]
	v_pk_fma_f32 v[210:211], v[62:63], v[174:175], v[66:67] op_sel:[0,1,0]
	v_pk_fma_f32 v[204:205], v[152:153], v[174:175], v[204:205] op_sel_hi:[1,0,1]
	v_pk_fma_f32 v[206:207], v[154:155], v[174:175], v[206:207] op_sel_hi:[1,0,1]
	v_pk_fma_f32 v[208:209], v[148:149], v[174:175], v[208:209] op_sel_hi:[1,0,1]
	v_pk_fma_f32 v[210:211], v[150:151], v[174:175], v[210:211] op_sel_hi:[1,0,1]
	v_pk_mul_f32 v[216:217], v[204:205], v[200:201] op_sel_hi:[1,0]
	v_pk_mul_f32 v[218:219], v[206:207], v[200:201] op_sel_hi:[1,0]
	v_pk_mul_f32 v[220:221], v[208:209], v[200:201] op_sel_hi:[1,0]
	v_pk_mul_f32 v[222:223], v[210:211], v[200:201] op_sel_hi:[1,0]
	v_exp_f32_e32 v216, v216
	v_exp_f32_e32 v217, v217
	v_exp_f32_e32 v218, v218
	v_exp_f32_e32 v219, v219
	v_exp_f32_e32 v220, v220
	v_exp_f32_e32 v221, v221
	v_exp_f32_e32 v222, v222
	v_exp_f32_e32 v223, v223
	v_pk_add_f32 v[216:217], v[216:217], v[200:201] op_sel:[0,1] op_sel_hi:[1,1]
	v_pk_add_f32 v[218:219], v[218:219], v[200:201] op_sel:[0,1] op_sel_hi:[1,1]
	v_pk_add_f32 v[220:221], v[220:221], v[200:201] op_sel:[0,1] op_sel_hi:[1,1]
	v_pk_add_f32 v[222:223], v[222:223], v[200:201] op_sel:[0,1] op_sel_hi:[1,1]
	v_rcp_f32_e32 v216, v216
	v_rcp_f32_e32 v217, v217
	v_rcp_f32_e32 v218, v218
	v_rcp_f32_e32 v219, v219
	v_rcp_f32_e32 v220, v220
	v_rcp_f32_e32 v221, v221
	v_rcp_f32_e32 v222, v222
	v_rcp_f32_e32 v223, v223
	v_cvt_pk_bf16_f32 v232, v216, v217
	v_cvt_pk_bf16_f32 v233, v218, v219
	v_cvt_pk_bf16_f32 v234, v220, v221
	v_cvt_pk_bf16_f32 v235, v222, v223
	v_add_u32_e32 v148, 16, v198
	v_mad_i64_i32 v[148:149], s[36:37], s0, v148, 0
	v_lshl_add_u64 v[148:149], v[148:149], 1, v[164:165]
	global_store_dwordx4 v[148:149], v[232:235], off
	s_cmp_gt_i32 s61, 1
	s_mov_b64 s[36:37], -1
	s_mov_b64 s[36:37], 0
	s_andn2_b64 vcc, exec, s[36:37]
	v_pk_fma_f32 v[204:205], v[40:41], v[174:175], v[56:57] op_sel:[0,1,0]
	v_pk_fma_f32 v[206:207], v[42:43], v[174:175], v[58:59] op_sel:[0,1,0]
	v_pk_fma_f32 v[208:209], v[32:33], v[174:175], v[44:45] op_sel:[0,1,0]
	v_pk_fma_f32 v[210:211], v[34:35], v[174:175], v[46:47] op_sel:[0,1,0]
	v_pk_fma_f32 v[204:205], v[144:145], v[174:175], v[204:205] op_sel_hi:[1,0,1]
	v_pk_fma_f32 v[206:207], v[146:147], v[174:175], v[206:207] op_sel_hi:[1,0,1]
	v_pk_fma_f32 v[208:209], v[140:141], v[174:175], v[208:209] op_sel_hi:[1,0,1]
	v_pk_fma_f32 v[210:211], v[142:143], v[174:175], v[210:211] op_sel_hi:[1,0,1]
	v_pk_mul_f32 v[216:217], v[204:205], v[200:201] op_sel_hi:[1,0]
	v_pk_mul_f32 v[218:219], v[206:207], v[200:201] op_sel_hi:[1,0]
	v_pk_mul_f32 v[220:221], v[208:209], v[200:201] op_sel_hi:[1,0]
	v_pk_mul_f32 v[222:223], v[210:211], v[200:201] op_sel_hi:[1,0]
	v_exp_f32_e32 v216, v216
	v_exp_f32_e32 v217, v217
	v_exp_f32_e32 v218, v218
	v_exp_f32_e32 v219, v219
	v_exp_f32_e32 v220, v220
	v_exp_f32_e32 v221, v221
	v_exp_f32_e32 v222, v222
	v_exp_f32_e32 v223, v223
	v_pk_add_f32 v[216:217], v[216:217], v[200:201] op_sel:[0,1] op_sel_hi:[1,1]
	v_pk_add_f32 v[218:219], v[218:219], v[200:201] op_sel:[0,1] op_sel_hi:[1,1]
	v_pk_add_f32 v[220:221], v[220:221], v[200:201] op_sel:[0,1] op_sel_hi:[1,1]
	v_pk_add_f32 v[222:223], v[222:223], v[200:201] op_sel:[0,1] op_sel_hi:[1,1]
	v_rcp_f32_e32 v216, v216
	v_rcp_f32_e32 v217, v217
	v_rcp_f32_e32 v218, v218
	v_rcp_f32_e32 v219, v219
	v_rcp_f32_e32 v220, v220
	v_rcp_f32_e32 v221, v221
	v_rcp_f32_e32 v222, v222
	v_rcp_f32_e32 v223, v223
	v_cvt_pk_bf16_f32 v236, v216, v217
	v_cvt_pk_bf16_f32 v237, v218, v219
	v_cvt_pk_bf16_f32 v238, v220, v221
	v_cvt_pk_bf16_f32 v239, v222, v223
	global_store_dwordx4 v[148:149], v[236:239], off offset:256
	s_cmp_gt_i32 s61, 1
	s_mov_b64 s[36:37], -1
	s_mov_b64 s[36:37], 0
	s_andn2_b64 vcc, exec, s[36:37]
	v_pk_fma_f32 v[204:205], v[68:69], v[136:137], v[72:73] op_sel:[0,1,0]
	v_pk_fma_f32 v[206:207], v[70:71], v[136:137], v[74:75] op_sel:[0,1,0]
	v_pk_fma_f32 v[208:209], v[60:61], v[136:137], v[64:65] op_sel:[0,1,0]
	v_pk_fma_f32 v[210:211], v[62:63], v[136:137], v[66:67] op_sel:[0,1,0]
	v_pk_fma_f32 v[204:205], v[132:133], v[136:137], v[204:205] op_sel_hi:[1,0,1]
	v_pk_fma_f32 v[206:207], v[134:135], v[136:137], v[206:207] op_sel_hi:[1,0,1]
	v_pk_fma_f32 v[208:209], v[128:129], v[136:137], v[208:209] op_sel_hi:[1,0,1]
	v_pk_fma_f32 v[210:211], v[130:131], v[136:137], v[210:211] op_sel_hi:[1,0,1]
	v_pk_mul_f32 v[216:217], v[204:205], v[200:201] op_sel_hi:[1,0]
	v_pk_mul_f32 v[218:219], v[206:207], v[200:201] op_sel_hi:[1,0]
	v_pk_mul_f32 v[220:221], v[208:209], v[200:201] op_sel_hi:[1,0]
	v_pk_mul_f32 v[222:223], v[210:211], v[200:201] op_sel_hi:[1,0]
	v_exp_f32_e32 v216, v216
	v_exp_f32_e32 v217, v217
	v_exp_f32_e32 v218, v218
	v_exp_f32_e32 v219, v219
	v_exp_f32_e32 v220, v220
	v_exp_f32_e32 v221, v221
	v_exp_f32_e32 v222, v222
	v_exp_f32_e32 v223, v223
	v_pk_add_f32 v[216:217], v[216:217], v[200:201] op_sel:[0,1] op_sel_hi:[1,1]
	v_pk_add_f32 v[218:219], v[218:219], v[200:201] op_sel:[0,1] op_sel_hi:[1,1]
	v_pk_add_f32 v[220:221], v[220:221], v[200:201] op_sel:[0,1] op_sel_hi:[1,1]
	v_pk_add_f32 v[222:223], v[222:223], v[200:201] op_sel:[0,1] op_sel_hi:[1,1]
	v_rcp_f32_e32 v216, v216
	v_rcp_f32_e32 v217, v217
	v_rcp_f32_e32 v218, v218
	v_rcp_f32_e32 v219, v219
	v_rcp_f32_e32 v220, v220
	v_rcp_f32_e32 v221, v221
	v_rcp_f32_e32 v222, v222
	v_rcp_f32_e32 v223, v223
	v_cvt_pk_bf16_f32 v240, v216, v217
	v_cvt_pk_bf16_f32 v241, v218, v219
	v_cvt_pk_bf16_f32 v242, v220, v221
	v_cvt_pk_bf16_f32 v243, v222, v223
	v_add_u32_e32 v128, 32, v198
	v_mad_i64_i32 v[128:129], s[36:37], s0, v128, 0
	v_lshl_add_u64 v[128:129], v[128:129], 1, v[164:165]
	s_cmp_gt_i32 s61, 1
	s_mov_b64 s[36:37], -1
	global_store_dwordx4 v[128:129], v[240:243], off
	s_mov_b64 s[36:37], 0
	s_andn2_b64 vcc, exec, s[36:37]
	v_pk_fma_f32 v[204:205], v[40:41], v[136:137], v[56:57] op_sel:[0,1,0]
	v_pk_fma_f32 v[206:207], v[42:43], v[136:137], v[58:59] op_sel:[0,1,0]
	v_pk_fma_f32 v[208:209], v[32:33], v[136:137], v[44:45] op_sel:[0,1,0]
	v_pk_fma_f32 v[210:211], v[34:35], v[136:137], v[46:47] op_sel:[0,1,0]
	v_pk_fma_f32 v[204:205], v[124:125], v[136:137], v[204:205] op_sel_hi:[1,0,1]
	v_pk_fma_f32 v[206:207], v[126:127], v[136:137], v[206:207] op_sel_hi:[1,0,1]
	v_pk_fma_f32 v[208:209], v[120:121], v[136:137], v[208:209] op_sel_hi:[1,0,1]
	v_pk_fma_f32 v[210:211], v[122:123], v[136:137], v[210:211] op_sel_hi:[1,0,1]
	v_pk_mul_f32 v[216:217], v[204:205], v[200:201] op_sel_hi:[1,0]
	v_pk_mul_f32 v[218:219], v[206:207], v[200:201] op_sel_hi:[1,0]
	v_pk_mul_f32 v[220:221], v[208:209], v[200:201] op_sel_hi:[1,0]
	v_pk_mul_f32 v[222:223], v[210:211], v[200:201] op_sel_hi:[1,0]
	v_exp_f32_e32 v216, v216
	v_exp_f32_e32 v217, v217
	v_exp_f32_e32 v218, v218
	v_exp_f32_e32 v219, v219
	v_exp_f32_e32 v220, v220
	v_exp_f32_e32 v221, v221
	v_exp_f32_e32 v222, v222
	v_exp_f32_e32 v223, v223
	v_pk_add_f32 v[216:217], v[216:217], v[200:201] op_sel:[0,1] op_sel_hi:[1,1]
	v_pk_add_f32 v[218:219], v[218:219], v[200:201] op_sel:[0,1] op_sel_hi:[1,1]
	v_pk_add_f32 v[220:221], v[220:221], v[200:201] op_sel:[0,1] op_sel_hi:[1,1]
	v_pk_add_f32 v[222:223], v[222:223], v[200:201] op_sel:[0,1] op_sel_hi:[1,1]
	v_rcp_f32_e32 v216, v216
	v_rcp_f32_e32 v217, v217
	v_rcp_f32_e32 v218, v218
	v_rcp_f32_e32 v219, v219
	v_rcp_f32_e32 v220, v220
	v_rcp_f32_e32 v221, v221
	v_rcp_f32_e32 v222, v222
	v_rcp_f32_e32 v223, v223
	v_cvt_pk_bf16_f32 v244, v216, v217
	v_cvt_pk_bf16_f32 v245, v218, v219
	v_cvt_pk_bf16_f32 v246, v220, v221
	v_cvt_pk_bf16_f32 v247, v222, v223
	global_store_dwordx4 v[128:129], v[244:247], off offset:256
	s_cmp_gt_i32 s61, 1
	s_mov_b64 s[36:37], -1
	s_mov_b64 s[36:37], 0
	s_andn2_b64 vcc, exec, s[36:37]
	v_pk_fma_f32 v[204:205], v[68:69], v[138:139], v[72:73] op_sel:[0,1,0]
	v_pk_fma_f32 v[206:207], v[70:71], v[138:139], v[74:75] op_sel:[0,1,0]
	v_pk_fma_f32 v[208:209], v[60:61], v[138:139], v[64:65] op_sel:[0,1,0]
	v_pk_fma_f32 v[210:211], v[62:63], v[138:139], v[66:67] op_sel:[0,1,0]
	v_pk_fma_f32 v[204:205], v[116:117], v[138:139], v[204:205] op_sel_hi:[1,0,1]
	v_pk_fma_f32 v[206:207], v[118:119], v[138:139], v[206:207] op_sel_hi:[1,0,1]
	v_pk_fma_f32 v[208:209], v[112:113], v[138:139], v[208:209] op_sel_hi:[1,0,1]
	v_pk_fma_f32 v[210:211], v[114:115], v[138:139], v[210:211] op_sel_hi:[1,0,1]
	v_pk_mul_f32 v[216:217], v[204:205], v[200:201] op_sel_hi:[1,0]
	v_pk_mul_f32 v[218:219], v[206:207], v[200:201] op_sel_hi:[1,0]
	v_pk_mul_f32 v[220:221], v[208:209], v[200:201] op_sel_hi:[1,0]
	v_pk_mul_f32 v[222:223], v[210:211], v[200:201] op_sel_hi:[1,0]
	v_exp_f32_e32 v216, v216
	v_exp_f32_e32 v217, v217
	v_exp_f32_e32 v218, v218
	v_exp_f32_e32 v219, v219
	v_exp_f32_e32 v220, v220
	v_exp_f32_e32 v221, v221
	v_exp_f32_e32 v222, v222
	v_exp_f32_e32 v223, v223
	v_pk_add_f32 v[216:217], v[216:217], v[200:201] op_sel:[0,1] op_sel_hi:[1,1]
	v_pk_add_f32 v[218:219], v[218:219], v[200:201] op_sel:[0,1] op_sel_hi:[1,1]
	v_pk_add_f32 v[220:221], v[220:221], v[200:201] op_sel:[0,1] op_sel_hi:[1,1]
	v_pk_add_f32 v[222:223], v[222:223], v[200:201] op_sel:[0,1] op_sel_hi:[1,1]
	v_rcp_f32_e32 v216, v216
	v_rcp_f32_e32 v217, v217
	v_rcp_f32_e32 v218, v218
	v_rcp_f32_e32 v219, v219
	v_rcp_f32_e32 v220, v220
	v_rcp_f32_e32 v221, v221
	v_rcp_f32_e32 v222, v222
	v_rcp_f32_e32 v223, v223
	v_cvt_pk_bf16_f32 v248, v216, v217
	v_cvt_pk_bf16_f32 v249, v218, v219
	v_cvt_pk_bf16_f32 v250, v220, v221
	v_cvt_pk_bf16_f32 v251, v222, v223
	v_add_u32_e32 v112, 48, v198
	v_mad_i64_i32 v[112:113], s[36:37], s0, v112, 0
	v_lshl_add_u64 v[112:113], v[112:113], 1, v[164:165]
	global_store_dwordx4 v[112:113], v[248:251], off
	s_cmp_gt_i32 s61, 1
	s_mov_b64 s[36:37], -1
	s_mov_b64 s[36:37], 0
	s_andn2_b64 vcc, exec, s[36:37]
	v_pk_fma_f32 v[204:205], v[40:41], v[138:139], v[56:57] op_sel:[0,1,0]
	v_pk_fma_f32 v[206:207], v[42:43], v[138:139], v[58:59] op_sel:[0,1,0]
	v_pk_fma_f32 v[208:209], v[32:33], v[138:139], v[44:45] op_sel:[0,1,0]
	v_pk_fma_f32 v[210:211], v[34:35], v[138:139], v[46:47] op_sel:[0,1,0]
	v_pk_fma_f32 v[204:205], v[108:109], v[138:139], v[204:205] op_sel_hi:[1,0,1]
	v_pk_fma_f32 v[206:207], v[110:111], v[138:139], v[206:207] op_sel_hi:[1,0,1]
	v_pk_fma_f32 v[208:209], v[104:105], v[138:139], v[208:209] op_sel_hi:[1,0,1]
	v_pk_fma_f32 v[210:211], v[106:107], v[138:139], v[210:211] op_sel_hi:[1,0,1]
	v_pk_mul_f32 v[216:217], v[204:205], v[200:201] op_sel_hi:[1,0]
	v_pk_mul_f32 v[218:219], v[206:207], v[200:201] op_sel_hi:[1,0]
	v_pk_mul_f32 v[220:221], v[208:209], v[200:201] op_sel_hi:[1,0]
	v_pk_mul_f32 v[222:223], v[210:211], v[200:201] op_sel_hi:[1,0]
	v_exp_f32_e32 v216, v216
	v_exp_f32_e32 v217, v217
	v_exp_f32_e32 v218, v218
	v_exp_f32_e32 v219, v219
	v_exp_f32_e32 v220, v220
	v_exp_f32_e32 v221, v221
	v_exp_f32_e32 v222, v222
	v_exp_f32_e32 v223, v223
	v_pk_add_f32 v[216:217], v[216:217], v[200:201] op_sel:[0,1] op_sel_hi:[1,1]
	v_pk_add_f32 v[218:219], v[218:219], v[200:201] op_sel:[0,1] op_sel_hi:[1,1]
	v_pk_add_f32 v[220:221], v[220:221], v[200:201] op_sel:[0,1] op_sel_hi:[1,1]
	v_pk_add_f32 v[222:223], v[222:223], v[200:201] op_sel:[0,1] op_sel_hi:[1,1]
	v_rcp_f32_e32 v216, v216
	v_rcp_f32_e32 v217, v217
	v_rcp_f32_e32 v218, v218
	v_rcp_f32_e32 v219, v219
	v_rcp_f32_e32 v220, v220
	v_rcp_f32_e32 v221, v221
	v_rcp_f32_e32 v222, v222
	v_rcp_f32_e32 v223, v223
	v_cvt_pk_bf16_f32 v224, v216, v217
	v_cvt_pk_bf16_f32 v225, v218, v219
	v_cvt_pk_bf16_f32 v226, v220, v221
	v_cvt_pk_bf16_f32 v227, v222, v223
	global_store_dwordx4 v[112:113], v[224:227], off offset:256
	s_cmp_gt_i32 s61, 1
	s_mov_b64 s[36:37], -1
	s_mov_b64 s[36:37], 0
	s_andn2_b64 vcc, exec, s[36:37]
	v_pk_fma_f32 v[204:205], v[68:69], v[100:101], v[72:73] op_sel:[0,1,0]
	v_pk_fma_f32 v[206:207], v[70:71], v[100:101], v[74:75] op_sel:[0,1,0]
	v_pk_fma_f32 v[208:209], v[60:61], v[100:101], v[64:65] op_sel:[0,1,0]
	v_pk_fma_f32 v[210:211], v[62:63], v[100:101], v[66:67] op_sel:[0,1,0]
	v_pk_fma_f32 v[204:205], v[96:97], v[100:101], v[204:205] op_sel_hi:[1,0,1]
	v_pk_fma_f32 v[206:207], v[98:99], v[100:101], v[206:207] op_sel_hi:[1,0,1]
	v_pk_fma_f32 v[208:209], v[92:93], v[100:101], v[208:209] op_sel_hi:[1,0,1]
	v_pk_fma_f32 v[210:211], v[94:95], v[100:101], v[210:211] op_sel_hi:[1,0,1]
	v_pk_mul_f32 v[216:217], v[204:205], v[200:201] op_sel_hi:[1,0]
	v_pk_mul_f32 v[218:219], v[206:207], v[200:201] op_sel_hi:[1,0]
	v_pk_mul_f32 v[220:221], v[208:209], v[200:201] op_sel_hi:[1,0]
	v_pk_mul_f32 v[222:223], v[210:211], v[200:201] op_sel_hi:[1,0]
	v_exp_f32_e32 v216, v216
	v_exp_f32_e32 v217, v217
	v_exp_f32_e32 v218, v218
	v_exp_f32_e32 v219, v219
	v_exp_f32_e32 v220, v220
	v_exp_f32_e32 v221, v221
	v_exp_f32_e32 v222, v222
	v_exp_f32_e32 v223, v223
	v_pk_add_f32 v[216:217], v[216:217], v[200:201] op_sel:[0,1] op_sel_hi:[1,1]
	v_pk_add_f32 v[218:219], v[218:219], v[200:201] op_sel:[0,1] op_sel_hi:[1,1]
	v_pk_add_f32 v[220:221], v[220:221], v[200:201] op_sel:[0,1] op_sel_hi:[1,1]
	v_pk_add_f32 v[222:223], v[222:223], v[200:201] op_sel:[0,1] op_sel_hi:[1,1]
	v_rcp_f32_e32 v216, v216
	v_rcp_f32_e32 v217, v217
	v_rcp_f32_e32 v218, v218
	v_rcp_f32_e32 v219, v219
	v_rcp_f32_e32 v220, v220
	v_rcp_f32_e32 v221, v221
	v_rcp_f32_e32 v222, v222
	v_rcp_f32_e32 v223, v223
	v_cvt_pk_bf16_f32 v228, v216, v217
	v_cvt_pk_bf16_f32 v229, v218, v219
	v_cvt_pk_bf16_f32 v230, v220, v221
	v_cvt_pk_bf16_f32 v231, v222, v223
	v_add_u32_e32 v92, 0x80, v198
	v_mad_i64_i32 v[92:93], s[36:37], s0, v92, 0
	v_lshl_add_u64 v[92:93], v[92:93], 1, v[164:165]
	s_cmp_gt_i32 s61, 1
	s_mov_b64 s[36:37], -1
	global_store_dwordx4 v[92:93], v[228:231], off
	s_mov_b64 s[36:37], 0
	s_andn2_b64 vcc, exec, s[36:37]
	v_pk_fma_f32 v[204:205], v[40:41], v[100:101], v[56:57] op_sel:[0,1,0]
	v_pk_fma_f32 v[206:207], v[42:43], v[100:101], v[58:59] op_sel:[0,1,0]
	v_pk_fma_f32 v[208:209], v[32:33], v[100:101], v[44:45] op_sel:[0,1,0]
	v_pk_fma_f32 v[210:211], v[34:35], v[100:101], v[46:47] op_sel:[0,1,0]
	v_pk_fma_f32 v[204:205], v[88:89], v[100:101], v[204:205] op_sel_hi:[1,0,1]
	v_pk_fma_f32 v[206:207], v[90:91], v[100:101], v[206:207] op_sel_hi:[1,0,1]
	v_pk_fma_f32 v[208:209], v[84:85], v[100:101], v[208:209] op_sel_hi:[1,0,1]
	v_pk_fma_f32 v[210:211], v[86:87], v[100:101], v[210:211] op_sel_hi:[1,0,1]
	v_pk_mul_f32 v[216:217], v[204:205], v[200:201] op_sel_hi:[1,0]
	v_pk_mul_f32 v[218:219], v[206:207], v[200:201] op_sel_hi:[1,0]
	v_pk_mul_f32 v[220:221], v[208:209], v[200:201] op_sel_hi:[1,0]
	v_pk_mul_f32 v[222:223], v[210:211], v[200:201] op_sel_hi:[1,0]
	v_exp_f32_e32 v216, v216
	v_exp_f32_e32 v217, v217
	v_exp_f32_e32 v218, v218
	v_exp_f32_e32 v219, v219
	v_exp_f32_e32 v220, v220
	v_exp_f32_e32 v221, v221
	v_exp_f32_e32 v222, v222
	v_exp_f32_e32 v223, v223
	v_pk_add_f32 v[216:217], v[216:217], v[200:201] op_sel:[0,1] op_sel_hi:[1,1]
	v_pk_add_f32 v[218:219], v[218:219], v[200:201] op_sel:[0,1] op_sel_hi:[1,1]
	v_pk_add_f32 v[220:221], v[220:221], v[200:201] op_sel:[0,1] op_sel_hi:[1,1]
	v_pk_add_f32 v[222:223], v[222:223], v[200:201] op_sel:[0,1] op_sel_hi:[1,1]
	v_rcp_f32_e32 v216, v216
	v_rcp_f32_e32 v217, v217
	v_rcp_f32_e32 v218, v218
	v_rcp_f32_e32 v219, v219
	v_rcp_f32_e32 v220, v220
	v_rcp_f32_e32 v221, v221
	v_rcp_f32_e32 v222, v222
	v_rcp_f32_e32 v223, v223
	v_cvt_pk_bf16_f32 v232, v216, v217
	v_cvt_pk_bf16_f32 v233, v218, v219
	v_cvt_pk_bf16_f32 v234, v220, v221
	v_cvt_pk_bf16_f32 v235, v222, v223
	global_store_dwordx4 v[92:93], v[232:235], off offset:256
	s_cmp_gt_i32 s61, 1
	s_mov_b64 s[36:37], -1
	s_mov_b64 s[36:37], 0
	s_andn2_b64 vcc, exec, s[36:37]
	v_pk_fma_f32 v[204:205], v[68:69], v[102:103], v[72:73] op_sel:[0,1,0]
	v_pk_fma_f32 v[206:207], v[70:71], v[102:103], v[74:75] op_sel:[0,1,0]
	v_pk_fma_f32 v[208:209], v[60:61], v[102:103], v[64:65] op_sel:[0,1,0]
	v_pk_fma_f32 v[210:211], v[62:63], v[102:103], v[66:67] op_sel:[0,1,0]
	v_pk_fma_f32 v[204:205], v[80:81], v[102:103], v[204:205] op_sel_hi:[1,0,1]
	v_pk_fma_f32 v[206:207], v[82:83], v[102:103], v[206:207] op_sel_hi:[1,0,1]
	v_pk_fma_f32 v[208:209], v[76:77], v[102:103], v[208:209] op_sel_hi:[1,0,1]
	v_pk_fma_f32 v[210:211], v[78:79], v[102:103], v[210:211] op_sel_hi:[1,0,1]
	v_pk_mul_f32 v[216:217], v[204:205], v[200:201] op_sel_hi:[1,0]
	v_pk_mul_f32 v[218:219], v[206:207], v[200:201] op_sel_hi:[1,0]
	v_pk_mul_f32 v[220:221], v[208:209], v[200:201] op_sel_hi:[1,0]
	v_pk_mul_f32 v[222:223], v[210:211], v[200:201] op_sel_hi:[1,0]
	v_exp_f32_e32 v216, v216
	v_exp_f32_e32 v217, v217
	v_exp_f32_e32 v218, v218
	v_exp_f32_e32 v219, v219
	v_exp_f32_e32 v220, v220
	v_exp_f32_e32 v221, v221
	v_exp_f32_e32 v222, v222
	v_exp_f32_e32 v223, v223
	v_pk_add_f32 v[216:217], v[216:217], v[200:201] op_sel:[0,1] op_sel_hi:[1,1]
	v_pk_add_f32 v[218:219], v[218:219], v[200:201] op_sel:[0,1] op_sel_hi:[1,1]
	v_pk_add_f32 v[220:221], v[220:221], v[200:201] op_sel:[0,1] op_sel_hi:[1,1]
	v_pk_add_f32 v[222:223], v[222:223], v[200:201] op_sel:[0,1] op_sel_hi:[1,1]
	v_rcp_f32_e32 v216, v216
	v_rcp_f32_e32 v217, v217
	v_rcp_f32_e32 v218, v218
	v_rcp_f32_e32 v219, v219
	v_rcp_f32_e32 v220, v220
	v_rcp_f32_e32 v221, v221
	v_rcp_f32_e32 v222, v222
	v_rcp_f32_e32 v223, v223
	v_cvt_pk_bf16_f32 v236, v216, v217
	v_cvt_pk_bf16_f32 v237, v218, v219
	v_cvt_pk_bf16_f32 v238, v220, v221
	v_cvt_pk_bf16_f32 v239, v222, v223
	v_add_u32_e32 v76, 0x90, v198
	v_mad_i64_i32 v[76:77], s[36:37], s0, v76, 0
	v_lshl_add_u64 v[76:77], v[76:77], 1, v[164:165]
	global_store_dwordx4 v[76:77], v[236:239], off
	s_cmp_gt_i32 s61, 1
	s_mov_b64 s[36:37], -1
	s_mov_b64 s[36:37], 0
	s_andn2_b64 vcc, exec, s[36:37]
	v_pk_fma_f32 v[204:205], v[40:41], v[102:103], v[56:57] op_sel:[0,1,0]
	v_pk_fma_f32 v[206:207], v[42:43], v[102:103], v[58:59] op_sel:[0,1,0]
	v_pk_fma_f32 v[208:209], v[32:33], v[102:103], v[44:45] op_sel:[0,1,0]
	v_pk_fma_f32 v[210:211], v[34:35], v[102:103], v[46:47] op_sel:[0,1,0]
	v_pk_fma_f32 v[204:205], v[52:53], v[102:103], v[204:205] op_sel_hi:[1,0,1]
	v_pk_fma_f32 v[206:207], v[54:55], v[102:103], v[206:207] op_sel_hi:[1,0,1]
	v_pk_fma_f32 v[208:209], v[36:37], v[102:103], v[208:209] op_sel_hi:[1,0,1]
	v_pk_fma_f32 v[210:211], v[38:39], v[102:103], v[210:211] op_sel_hi:[1,0,1]
	v_pk_mul_f32 v[216:217], v[204:205], v[200:201] op_sel_hi:[1,0]
	v_pk_mul_f32 v[218:219], v[206:207], v[200:201] op_sel_hi:[1,0]
	v_pk_mul_f32 v[220:221], v[208:209], v[200:201] op_sel_hi:[1,0]
	v_pk_mul_f32 v[222:223], v[210:211], v[200:201] op_sel_hi:[1,0]
	v_exp_f32_e32 v216, v216
	v_exp_f32_e32 v217, v217
	v_exp_f32_e32 v218, v218
	v_exp_f32_e32 v219, v219
	v_exp_f32_e32 v220, v220
	v_exp_f32_e32 v221, v221
	v_exp_f32_e32 v222, v222
	v_exp_f32_e32 v223, v223
	v_pk_add_f32 v[216:217], v[216:217], v[200:201] op_sel:[0,1] op_sel_hi:[1,1]
	v_pk_add_f32 v[218:219], v[218:219], v[200:201] op_sel:[0,1] op_sel_hi:[1,1]
	v_pk_add_f32 v[220:221], v[220:221], v[200:201] op_sel:[0,1] op_sel_hi:[1,1]
	v_pk_add_f32 v[222:223], v[222:223], v[200:201] op_sel:[0,1] op_sel_hi:[1,1]
	v_rcp_f32_e32 v216, v216
	v_rcp_f32_e32 v217, v217
	v_rcp_f32_e32 v218, v218
	v_rcp_f32_e32 v219, v219
	v_rcp_f32_e32 v220, v220
	v_rcp_f32_e32 v221, v221
	v_rcp_f32_e32 v222, v222
	v_rcp_f32_e32 v223, v223
	v_cvt_pk_bf16_f32 v240, v216, v217
	v_cvt_pk_bf16_f32 v241, v218, v219
	v_cvt_pk_bf16_f32 v242, v220, v221
	v_cvt_pk_bf16_f32 v243, v222, v223
	global_store_dwordx4 v[76:77], v[240:243], off offset:256
	s_cmp_gt_i32 s61, 1
	s_mov_b64 s[36:37], -1
	s_mov_b64 s[36:37], 0
	s_andn2_b64 vcc, exec, s[36:37]
	v_pk_fma_f32 v[204:205], v[68:69], v[48:49], v[72:73] op_sel:[0,1,0]
	v_pk_fma_f32 v[206:207], v[70:71], v[48:49], v[74:75] op_sel:[0,1,0]
	v_pk_fma_f32 v[208:209], v[60:61], v[48:49], v[64:65] op_sel:[0,1,0]
	v_pk_fma_f32 v[210:211], v[62:63], v[48:49], v[66:67] op_sel:[0,1,0]
	v_pk_fma_f32 v[204:205], v[28:29], v[48:49], v[204:205] op_sel_hi:[1,0,1]
	v_pk_fma_f32 v[206:207], v[30:31], v[48:49], v[206:207] op_sel_hi:[1,0,1]
	v_pk_fma_f32 v[208:209], v[24:25], v[48:49], v[208:209] op_sel_hi:[1,0,1]
	v_pk_fma_f32 v[210:211], v[26:27], v[48:49], v[210:211] op_sel_hi:[1,0,1]
	v_pk_mul_f32 v[216:217], v[204:205], v[200:201] op_sel_hi:[1,0]
	v_pk_mul_f32 v[218:219], v[206:207], v[200:201] op_sel_hi:[1,0]
	v_pk_mul_f32 v[220:221], v[208:209], v[200:201] op_sel_hi:[1,0]
	v_pk_mul_f32 v[222:223], v[210:211], v[200:201] op_sel_hi:[1,0]
	v_exp_f32_e32 v216, v216
	v_exp_f32_e32 v217, v217
	v_exp_f32_e32 v218, v218
	v_exp_f32_e32 v219, v219
	v_exp_f32_e32 v220, v220
	v_exp_f32_e32 v221, v221
	v_exp_f32_e32 v222, v222
	v_exp_f32_e32 v223, v223
	v_pk_add_f32 v[216:217], v[216:217], v[200:201] op_sel:[0,1] op_sel_hi:[1,1]
	v_pk_add_f32 v[218:219], v[218:219], v[200:201] op_sel:[0,1] op_sel_hi:[1,1]
	v_pk_add_f32 v[220:221], v[220:221], v[200:201] op_sel:[0,1] op_sel_hi:[1,1]
	v_pk_add_f32 v[222:223], v[222:223], v[200:201] op_sel:[0,1] op_sel_hi:[1,1]
	v_rcp_f32_e32 v216, v216
	v_rcp_f32_e32 v217, v217
	v_rcp_f32_e32 v218, v218
	v_rcp_f32_e32 v219, v219
	v_rcp_f32_e32 v220, v220
	v_rcp_f32_e32 v221, v221
	v_rcp_f32_e32 v222, v222
	v_rcp_f32_e32 v223, v223
	v_cvt_pk_bf16_f32 v244, v216, v217
	v_cvt_pk_bf16_f32 v245, v218, v219
	v_cvt_pk_bf16_f32 v246, v220, v221
	v_cvt_pk_bf16_f32 v247, v222, v223
	v_add_u32_e32 v24, 0xa0, v198
	v_mad_i64_i32 v[24:25], s[36:37], s0, v24, 0
	v_lshl_add_u64 v[24:25], v[24:25], 1, v[164:165]
	s_cmp_gt_i32 s61, 1
	s_mov_b64 s[36:37], -1
	global_store_dwordx4 v[24:25], v[244:247], off
	s_mov_b64 s[36:37], 0
	s_andn2_b64 vcc, exec, s[36:37]
	v_pk_fma_f32 v[204:205], v[40:41], v[48:49], v[56:57] op_sel:[0,1,0]
	v_pk_fma_f32 v[206:207], v[42:43], v[48:49], v[58:59] op_sel:[0,1,0]
	v_pk_fma_f32 v[208:209], v[32:33], v[48:49], v[44:45] op_sel:[0,1,0]
	v_pk_fma_f32 v[210:211], v[34:35], v[48:49], v[46:47] op_sel:[0,1,0]
	v_pk_fma_f32 v[204:205], v[20:21], v[48:49], v[204:205] op_sel_hi:[1,0,1]
	v_pk_fma_f32 v[206:207], v[22:23], v[48:49], v[206:207] op_sel_hi:[1,0,1]
	v_pk_fma_f32 v[208:209], v[16:17], v[48:49], v[208:209] op_sel_hi:[1,0,1]
	v_pk_fma_f32 v[210:211], v[18:19], v[48:49], v[210:211] op_sel_hi:[1,0,1]
	v_pk_mul_f32 v[216:217], v[204:205], v[200:201] op_sel_hi:[1,0]
	v_pk_mul_f32 v[218:219], v[206:207], v[200:201] op_sel_hi:[1,0]
	v_pk_mul_f32 v[220:221], v[208:209], v[200:201] op_sel_hi:[1,0]
	v_pk_mul_f32 v[222:223], v[210:211], v[200:201] op_sel_hi:[1,0]
	v_exp_f32_e32 v216, v216
	v_exp_f32_e32 v217, v217
	v_exp_f32_e32 v218, v218
	v_exp_f32_e32 v219, v219
	v_exp_f32_e32 v220, v220
	v_exp_f32_e32 v221, v221
	v_exp_f32_e32 v222, v222
	v_exp_f32_e32 v223, v223
	v_pk_add_f32 v[216:217], v[216:217], v[200:201] op_sel:[0,1] op_sel_hi:[1,1]
	v_pk_add_f32 v[218:219], v[218:219], v[200:201] op_sel:[0,1] op_sel_hi:[1,1]
	v_pk_add_f32 v[220:221], v[220:221], v[200:201] op_sel:[0,1] op_sel_hi:[1,1]
	v_pk_add_f32 v[222:223], v[222:223], v[200:201] op_sel:[0,1] op_sel_hi:[1,1]
	v_rcp_f32_e32 v216, v216
	v_rcp_f32_e32 v217, v217
	v_rcp_f32_e32 v218, v218
	v_rcp_f32_e32 v219, v219
	v_rcp_f32_e32 v220, v220
	v_rcp_f32_e32 v221, v221
	v_rcp_f32_e32 v222, v222
	v_rcp_f32_e32 v223, v223
	v_cvt_pk_bf16_f32 v248, v216, v217
	v_cvt_pk_bf16_f32 v249, v218, v219
	v_cvt_pk_bf16_f32 v250, v220, v221
	v_cvt_pk_bf16_f32 v251, v222, v223
	global_store_dwordx4 v[24:25], v[248:251], off offset:256
	s_cmp_gt_i32 s61, 1
	s_mov_b64 s[36:37], -1
	s_mov_b64 s[36:37], 0
	s_andn2_b64 vcc, exec, s[36:37]
	v_pk_fma_f32 v[204:205], v[68:69], v[50:51], v[72:73] op_sel:[0,1,0]
	v_pk_fma_f32 v[206:207], v[70:71], v[50:51], v[74:75] op_sel:[0,1,0]
	v_pk_fma_f32 v[208:209], v[60:61], v[50:51], v[64:65] op_sel:[0,1,0]
	v_pk_fma_f32 v[210:211], v[62:63], v[50:51], v[66:67] op_sel:[0,1,0]
	v_pk_fma_f32 v[204:205], v[12:13], v[50:51], v[204:205] op_sel_hi:[1,0,1]
	v_pk_fma_f32 v[206:207], v[14:15], v[50:51], v[206:207] op_sel_hi:[1,0,1]
	v_pk_fma_f32 v[208:209], v[8:9], v[50:51], v[208:209] op_sel_hi:[1,0,1]
	v_pk_fma_f32 v[210:211], v[10:11], v[50:51], v[210:211] op_sel_hi:[1,0,1]
	v_pk_mul_f32 v[216:217], v[204:205], v[200:201] op_sel_hi:[1,0]
	v_pk_mul_f32 v[218:219], v[206:207], v[200:201] op_sel_hi:[1,0]
	v_pk_mul_f32 v[220:221], v[208:209], v[200:201] op_sel_hi:[1,0]
	v_pk_mul_f32 v[222:223], v[210:211], v[200:201] op_sel_hi:[1,0]
	v_exp_f32_e32 v216, v216
	v_exp_f32_e32 v217, v217
	v_exp_f32_e32 v218, v218
	v_exp_f32_e32 v219, v219
	v_exp_f32_e32 v220, v220
	v_exp_f32_e32 v221, v221
	v_exp_f32_e32 v222, v222
	v_exp_f32_e32 v223, v223
	v_pk_add_f32 v[216:217], v[216:217], v[200:201] op_sel:[0,1] op_sel_hi:[1,1]
	v_pk_add_f32 v[218:219], v[218:219], v[200:201] op_sel:[0,1] op_sel_hi:[1,1]
	v_pk_add_f32 v[220:221], v[220:221], v[200:201] op_sel:[0,1] op_sel_hi:[1,1]
	v_pk_add_f32 v[222:223], v[222:223], v[200:201] op_sel:[0,1] op_sel_hi:[1,1]
	v_rcp_f32_e32 v216, v216
	v_rcp_f32_e32 v217, v217
	v_rcp_f32_e32 v218, v218
	v_rcp_f32_e32 v219, v219
	v_rcp_f32_e32 v220, v220
	v_rcp_f32_e32 v221, v221
	v_rcp_f32_e32 v222, v222
	v_rcp_f32_e32 v223, v223
	v_cvt_pk_bf16_f32 v224, v216, v217
	v_cvt_pk_bf16_f32 v225, v218, v219
	v_cvt_pk_bf16_f32 v226, v220, v221
	v_cvt_pk_bf16_f32 v227, v222, v223
	v_add_u32_e32 v8, 0xb0, v198
	v_mad_i64_i32 v[8:9], s[36:37], s0, v8, 0
	v_lshl_add_u64 v[8:9], v[8:9], 1, v[164:165]
	global_store_dwordx4 v[8:9], v[224:227], off
	s_cmp_gt_i32 s61, 1
	s_mov_b64 s[36:37], -1
	s_mov_b64 s[36:37], 0
	s_andn2_b64 vcc, exec, s[36:37]
	s_andn2_b64 vcc, exec, s[10:11]
	s_mov_b64 s[10:11], -1
	v_pk_fma_f32 v[204:205], v[40:41], v[50:51], v[56:57] op_sel:[0,1,0]
	v_pk_fma_f32 v[206:207], v[42:43], v[50:51], v[58:59] op_sel:[0,1,0]
	v_pk_fma_f32 v[208:209], v[32:33], v[50:51], v[44:45] op_sel:[0,1,0]
	v_pk_fma_f32 v[210:211], v[34:35], v[50:51], v[46:47] op_sel:[0,1,0]
	v_pk_fma_f32 v[204:205], v[4:5], v[50:51], v[204:205] op_sel_hi:[1,0,1]
	v_pk_fma_f32 v[206:207], v[6:7], v[50:51], v[206:207] op_sel_hi:[1,0,1]
	v_pk_fma_f32 v[208:209], v[0:1], v[50:51], v[208:209] op_sel_hi:[1,0,1]
	v_pk_fma_f32 v[210:211], v[2:3], v[50:51], v[210:211] op_sel_hi:[1,0,1]
	v_pk_mul_f32 v[216:217], v[204:205], v[200:201] op_sel_hi:[1,0]
	v_pk_mul_f32 v[218:219], v[206:207], v[200:201] op_sel_hi:[1,0]
	v_pk_mul_f32 v[220:221], v[208:209], v[200:201] op_sel_hi:[1,0]
	v_pk_mul_f32 v[222:223], v[210:211], v[200:201] op_sel_hi:[1,0]
	v_exp_f32_e32 v216, v216
	v_exp_f32_e32 v217, v217
	v_exp_f32_e32 v218, v218
	v_exp_f32_e32 v219, v219
	v_exp_f32_e32 v220, v220
	v_exp_f32_e32 v221, v221
	v_exp_f32_e32 v222, v222
	v_exp_f32_e32 v223, v223
	v_pk_add_f32 v[216:217], v[216:217], v[200:201] op_sel:[0,1] op_sel_hi:[1,1]
	v_pk_add_f32 v[218:219], v[218:219], v[200:201] op_sel:[0,1] op_sel_hi:[1,1]
	v_pk_add_f32 v[220:221], v[220:221], v[200:201] op_sel:[0,1] op_sel_hi:[1,1]
	v_pk_add_f32 v[222:223], v[222:223], v[200:201] op_sel:[0,1] op_sel_hi:[1,1]
	v_rcp_f32_e32 v216, v216
	v_rcp_f32_e32 v217, v217
	v_rcp_f32_e32 v218, v218
	v_rcp_f32_e32 v219, v219
	v_rcp_f32_e32 v220, v220
	v_rcp_f32_e32 v221, v221
	v_rcp_f32_e32 v222, v222
	v_rcp_f32_e32 v223, v223
	v_cvt_pk_bf16_f32 v228, v216, v217
	v_cvt_pk_bf16_f32 v229, v218, v219
	v_cvt_pk_bf16_f32 v230, v220, v221
	v_cvt_pk_bf16_f32 v231, v222, v223
	global_store_dwordx4 v[8:9], v[228:231], off offset:256

.LBB0_2795:
	s_cmp_lg_u32 s40, 2
	s_cselect_b64 s[46:47], -1, 0
	s_cmp_lt_u32 s40, 6
	s_cselect_b64 s[52:53], -1, 0
	s_and_b64 s[46:47], s[46:47], s[52:53]
	s_cmp_gt_u32 s40, 11
	s_cselect_b32 s0, 2, 0
	s_and_b64 s[46:47], s[46:47], exec
	s_cselect_b32 s0, 1, s0
	s_cmp_gt_i32 s40, 1
	s_cselect_b32 s23, s0, 1
	s_cmp_gt_i32 s23, 1
	s_cbranch_scc1 .Le1m2_26
	s_cmp_eq_u32 s23, 1
	s_cbranch_scc1 .Le1m1_26
	s_cmp_eq_u32 s36, s61
	s_movk_i32 s0, 0x200
	s_cselect_b32 s0, s0, 0x300
	s_cmp_lg_u32 s36, s60
	v_mov_b32_e32 v44, v192
	v_mov_b32_e32 v198, v193
	s_cselect_b32 s0, s0, 0x100
	s_cmp_lg_u32 s36, s19
	s_cselect_b32 s0, s0, 0
	v_lshl_add_u32 v45, v198, 5, s73
	v_add_u32_e32 v199, s68, v44
	ds_read_b128 v[68:71], v45
	ds_read_b128 v[60:63], v45 offset:16
	ds_read_b128 v[72:75], v45 offset:256
	ds_read_b128 v[64:67], v45 offset:272
	ds_read_b128 v[40:43], v45 offset:128
	ds_read_b128 v[32:35], v45 offset:144
	v_add_u32_e32 v44, s0, v199
	v_lshl_add_u32 v48, v44, 3, v197
	ds_read2_b64 v[172:175], v48 offset1:16
	ds_read_b128 v[56:59], v45 offset:384
	ds_read_b128 v[44:47], v45 offset:400
	ds_read2_b64 v[136:139], v48 offset0:32 offset1:48
	ds_read2_b64 v[100:103], v48 offset0:128 offset1:144
	ds_read2_b64 v[48:51], v48 offset0:160 offset1:176
	s_waitcnt lgkmcnt(0)
	s_cmp_gt_i32 s23, 1
	s_mov_b64 s[46:47], -1
	s_andn2_b64 vcc, exec, s[46:47]
	s_cmp_eq_u32 s23, 1
	s_add_i32 s0, s48, 0xfffff400
	s_lshl_b64 s[46:47], s[0:1], 1
	s_add_u32 s0, s56, s46
	s_addc_u32 s25, s57, s47
	s_ashr_i32 s49, s48, 31
	s_lshl_b64 s[46:47], s[48:49], 1
	s_add_u32 s37, s42, s46
	s_addc_u32 s46, s43, s47
	s_cmp_lt_i32 s40, 12
	s_cselect_b32 s0, s37, s0
	v_pk_fma_f32 v[200:201], v[68:69], v[172:173], v[72:73] op_sel:[0,1,0]
	v_pk_fma_f32 v[204:205], v[70:71], v[172:173], v[74:75] op_sel:[0,1,0]
	v_pk_fma_f32 v[206:207], v[60:61], v[172:173], v[64:65] op_sel:[0,1,0]
	v_pk_fma_f32 v[208:209], v[62:63], v[172:173], v[66:67] op_sel:[0,1,0]
	v_pk_fma_f32 v[200:201], v[168:169], v[172:173], v[200:201] op_sel_hi:[1,0,1]
	v_pk_fma_f32 v[204:205], v[170:171], v[172:173], v[204:205] op_sel_hi:[1,0,1]
	v_pk_fma_f32 v[206:207], v[164:165], v[172:173], v[206:207] op_sel_hi:[1,0,1]
	v_pk_fma_f32 v[208:209], v[166:167], v[172:173], v[208:209] op_sel_hi:[1,0,1]
	v_cvt_pk_bf16_f32 v216, v200, v201
	v_cvt_pk_bf16_f32 v217, v204, v205
	v_cvt_pk_bf16_f32 v218, v206, v207
	v_cvt_pk_bf16_f32 v219, v208, v209
	v_lshl_add_u32 v164, v198, 3, s69
	s_cselect_b32 s25, s46, s25
	v_mov_b32_e32 v166, s0
	s_movk_i32 s0, 0xc00
	v_mov_b32_e32 v167, s25
	s_cselect_b32 s0, s0, 0x800
	v_ashrrev_i32_e32 v165, 31, v164
	v_lshl_add_u32 v198, s36, 8, v199
	v_lshl_add_u64 v[164:165], v[164:165], 1, v[166:167]
	v_mad_i64_i32 v[166:167], s[36:37], s0, v198, 0
	v_lshl_add_u64 v[166:167], v[166:167], 1, v[164:165]
	s_cmp_gt_i32 s23, 1
	s_mov_b64 s[36:37], -1
	global_store_dwordx4 v[166:167], v[216:219], off
	s_andn2_b64 vcc, exec, s[36:37]
	s_cmp_eq_u32 s23, 1
	v_pk_fma_f32 v[200:201], v[40:41], v[172:173], v[56:57] op_sel:[0,1,0]
	v_pk_fma_f32 v[204:205], v[42:43], v[172:173], v[58:59] op_sel:[0,1,0]
	v_pk_fma_f32 v[206:207], v[32:33], v[172:173], v[44:45] op_sel:[0,1,0]
	v_pk_fma_f32 v[208:209], v[34:35], v[172:173], v[46:47] op_sel:[0,1,0]
	v_pk_fma_f32 v[200:201], v[160:161], v[172:173], v[200:201] op_sel_hi:[1,0,1]
	v_pk_fma_f32 v[204:205], v[162:163], v[172:173], v[204:205] op_sel_hi:[1,0,1]
	v_pk_fma_f32 v[206:207], v[156:157], v[172:173], v[206:207] op_sel_hi:[1,0,1]
	v_pk_fma_f32 v[208:209], v[158:159], v[172:173], v[208:209] op_sel_hi:[1,0,1]
	v_cvt_pk_bf16_f32 v220, v200, v201
	v_cvt_pk_bf16_f32 v221, v204, v205
	v_cvt_pk_bf16_f32 v222, v206, v207
	v_cvt_pk_bf16_f32 v223, v208, v209
	global_store_dwordx4 v[166:167], v[220:223], off offset:256
	s_cmp_gt_i32 s23, 1
	s_mov_b64 s[36:37], -1
	s_andn2_b64 vcc, exec, s[36:37]
	s_cmp_eq_u32 s23, 1
	v_pk_fma_f32 v[200:201], v[68:69], v[174:175], v[72:73] op_sel:[0,1,0]
	v_pk_fma_f32 v[204:205], v[70:71], v[174:175], v[74:75] op_sel:[0,1,0]
	v_pk_fma_f32 v[206:207], v[60:61], v[174:175], v[64:65] op_sel:[0,1,0]
	v_pk_fma_f32 v[208:209], v[62:63], v[174:175], v[66:67] op_sel:[0,1,0]
	v_pk_fma_f32 v[200:201], v[152:153], v[174:175], v[200:201] op_sel_hi:[1,0,1]
	v_pk_fma_f32 v[204:205], v[154:155], v[174:175], v[204:205] op_sel_hi:[1,0,1]
	v_pk_fma_f32 v[206:207], v[148:149], v[174:175], v[206:207] op_sel_hi:[1,0,1]
	v_pk_fma_f32 v[208:209], v[150:151], v[174:175], v[208:209] op_sel_hi:[1,0,1]
	v_cvt_pk_bf16_f32 v224, v200, v201
	v_cvt_pk_bf16_f32 v225, v204, v205
	v_cvt_pk_bf16_f32 v226, v206, v207
	v_cvt_pk_bf16_f32 v227, v208, v209
	v_add_u32_e32 v148, 16, v198
	v_mad_i64_i32 v[148:149], s[36:37], s0, v148, 0
	v_lshl_add_u64 v[148:149], v[148:149], 1, v[164:165]
	global_store_dwordx4 v[148:149], v[224:227], off
	s_cmp_gt_i32 s23, 1
	s_mov_b64 s[36:37], -1
	s_andn2_b64 vcc, exec, s[36:37]
	s_cmp_eq_u32 s23, 1
	v_pk_fma_f32 v[200:201], v[40:41], v[174:175], v[56:57] op_sel:[0,1,0]
	v_pk_fma_f32 v[204:205], v[42:43], v[174:175], v[58:59] op_sel:[0,1,0]
	v_pk_fma_f32 v[206:207], v[32:33], v[174:175], v[44:45] op_sel:[0,1,0]
	v_pk_fma_f32 v[208:209], v[34:35], v[174:175], v[46:47] op_sel:[0,1,0]
	v_pk_fma_f32 v[200:201], v[144:145], v[174:175], v[200:201] op_sel_hi:[1,0,1]
	v_pk_fma_f32 v[204:205], v[146:147], v[174:175], v[204:205] op_sel_hi:[1,0,1]
	v_pk_fma_f32 v[206:207], v[140:141], v[174:175], v[206:207] op_sel_hi:[1,0,1]
	v_pk_fma_f32 v[208:209], v[142:143], v[174:175], v[208:209] op_sel_hi:[1,0,1]
	v_cvt_pk_bf16_f32 v228, v200, v201
	v_cvt_pk_bf16_f32 v229, v204, v205
	v_cvt_pk_bf16_f32 v230, v206, v207
	v_cvt_pk_bf16_f32 v231, v208, v209
	global_store_dwordx4 v[148:149], v[228:231], off offset:256
	s_cmp_gt_i32 s23, 1
	s_mov_b64 s[36:37], -1
	s_andn2_b64 vcc, exec, s[36:37]
	s_cmp_eq_u32 s23, 1
	v_pk_fma_f32 v[200:201], v[68:69], v[136:137], v[72:73] op_sel:[0,1,0]
	v_pk_fma_f32 v[204:205], v[70:71], v[136:137], v[74:75] op_sel:[0,1,0]
	v_pk_fma_f32 v[206:207], v[60:61], v[136:137], v[64:65] op_sel:[0,1,0]
	v_pk_fma_f32 v[208:209], v[62:63], v[136:137], v[66:67] op_sel:[0,1,0]
	v_pk_fma_f32 v[200:201], v[132:133], v[136:137], v[200:201] op_sel_hi:[1,0,1]
	v_pk_fma_f32 v[204:205], v[134:135], v[136:137], v[204:205] op_sel_hi:[1,0,1]
	v_pk_fma_f32 v[206:207], v[128:129], v[136:137], v[206:207] op_sel_hi:[1,0,1]
	v_pk_fma_f32 v[208:209], v[130:131], v[136:137], v[208:209] op_sel_hi:[1,0,1]
	v_cvt_pk_bf16_f32 v232, v200, v201
	v_cvt_pk_bf16_f32 v233, v204, v205
	v_cvt_pk_bf16_f32 v234, v206, v207
	v_cvt_pk_bf16_f32 v235, v208, v209
	v_add_u32_e32 v128, 32, v198
	v_mad_i64_i32 v[128:129], s[36:37], s0, v128, 0
	v_lshl_add_u64 v[128:129], v[128:129], 1, v[164:165]
	s_cmp_gt_i32 s23, 1
	s_mov_b64 s[36:37], -1
	global_store_dwordx4 v[128:129], v[232:235], off
	s_andn2_b64 vcc, exec, s[36:37]
	s_cmp_eq_u32 s23, 1
	v_pk_fma_f32 v[200:201], v[40:41], v[136:137], v[56:57] op_sel:[0,1,0]
	v_pk_fma_f32 v[204:205], v[42:43], v[136:137], v[58:59] op_sel:[0,1,0]
	v_pk_fma_f32 v[206:207], v[32:33], v[136:137], v[44:45] op_sel:[0,1,0]
	v_pk_fma_f32 v[208:209], v[34:35], v[136:137], v[46:47] op_sel:[0,1,0]
	v_pk_fma_f32 v[200:201], v[124:125], v[136:137], v[200:201] op_sel_hi:[1,0,1]
	v_pk_fma_f32 v[204:205], v[126:127], v[136:137], v[204:205] op_sel_hi:[1,0,1]
	v_pk_fma_f32 v[206:207], v[120:121], v[136:137], v[206:207] op_sel_hi:[1,0,1]
	v_pk_fma_f32 v[208:209], v[122:123], v[136:137], v[208:209] op_sel_hi:[1,0,1]
	v_cvt_pk_bf16_f32 v236, v200, v201
	v_cvt_pk_bf16_f32 v237, v204, v205
	v_cvt_pk_bf16_f32 v238, v206, v207
	v_cvt_pk_bf16_f32 v239, v208, v209
	global_store_dwordx4 v[128:129], v[236:239], off offset:256
	s_cmp_gt_i32 s23, 1
	s_mov_b64 s[36:37], -1
	s_andn2_b64 vcc, exec, s[36:37]
	s_cmp_eq_u32 s23, 1
	v_pk_fma_f32 v[200:201], v[68:69], v[138:139], v[72:73] op_sel:[0,1,0]
	v_pk_fma_f32 v[204:205], v[70:71], v[138:139], v[74:75] op_sel:[0,1,0]
	v_pk_fma_f32 v[206:207], v[60:61], v[138:139], v[64:65] op_sel:[0,1,0]
	v_pk_fma_f32 v[208:209], v[62:63], v[138:139], v[66:67] op_sel:[0,1,0]
	v_pk_fma_f32 v[200:201], v[116:117], v[138:139], v[200:201] op_sel_hi:[1,0,1]
	v_pk_fma_f32 v[204:205], v[118:119], v[138:139], v[204:205] op_sel_hi:[1,0,1]
	v_pk_fma_f32 v[206:207], v[112:113], v[138:139], v[206:207] op_sel_hi:[1,0,1]
	v_pk_fma_f32 v[208:209], v[114:115], v[138:139], v[208:209] op_sel_hi:[1,0,1]
	v_cvt_pk_bf16_f32 v240, v200, v201
	v_cvt_pk_bf16_f32 v241, v204, v205
	v_cvt_pk_bf16_f32 v242, v206, v207
	v_cvt_pk_bf16_f32 v243, v208, v209
	v_add_u32_e32 v112, 48, v198
	v_mad_i64_i32 v[112:113], s[36:37], s0, v112, 0
	v_lshl_add_u64 v[112:113], v[112:113], 1, v[164:165]
	global_store_dwordx4 v[112:113], v[240:243], off
	s_cmp_gt_i32 s23, 1
	s_mov_b64 s[36:37], -1
	s_andn2_b64 vcc, exec, s[36:37]
	s_cmp_eq_u32 s23, 1
	v_pk_fma_f32 v[200:201], v[40:41], v[138:139], v[56:57] op_sel:[0,1,0]
	v_pk_fma_f32 v[204:205], v[42:43], v[138:139], v[58:59] op_sel:[0,1,0]
	v_pk_fma_f32 v[206:207], v[32:33], v[138:139], v[44:45] op_sel:[0,1,0]
	v_pk_fma_f32 v[208:209], v[34:35], v[138:139], v[46:47] op_sel:[0,1,0]
	v_pk_fma_f32 v[200:201], v[108:109], v[138:139], v[200:201] op_sel_hi:[1,0,1]
	v_pk_fma_f32 v[204:205], v[110:111], v[138:139], v[204:205] op_sel_hi:[1,0,1]
	v_pk_fma_f32 v[206:207], v[104:105], v[138:139], v[206:207] op_sel_hi:[1,0,1]
	v_pk_fma_f32 v[208:209], v[106:107], v[138:139], v[208:209] op_sel_hi:[1,0,1]
	v_cvt_pk_bf16_f32 v244, v200, v201
	v_cvt_pk_bf16_f32 v245, v204, v205
	v_cvt_pk_bf16_f32 v246, v206, v207
	v_cvt_pk_bf16_f32 v247, v208, v209
	global_store_dwordx4 v[112:113], v[244:247], off offset:256
	s_cmp_gt_i32 s23, 1
	s_mov_b64 s[36:37], -1
	s_andn2_b64 vcc, exec, s[36:37]
	s_cmp_eq_u32 s23, 1
	v_pk_fma_f32 v[200:201], v[68:69], v[100:101], v[72:73] op_sel:[0,1,0]
	v_pk_fma_f32 v[204:205], v[70:71], v[100:101], v[74:75] op_sel:[0,1,0]
	v_pk_fma_f32 v[206:207], v[60:61], v[100:101], v[64:65] op_sel:[0,1,0]
	v_pk_fma_f32 v[208:209], v[62:63], v[100:101], v[66:67] op_sel:[0,1,0]
	v_pk_fma_f32 v[200:201], v[96:97], v[100:101], v[200:201] op_sel_hi:[1,0,1]
	v_pk_fma_f32 v[204:205], v[98:99], v[100:101], v[204:205] op_sel_hi:[1,0,1]
	v_pk_fma_f32 v[206:207], v[92:93], v[100:101], v[206:207] op_sel_hi:[1,0,1]
	v_pk_fma_f32 v[208:209], v[94:95], v[100:101], v[208:209] op_sel_hi:[1,0,1]
	v_cvt_pk_bf16_f32 v248, v200, v201
	v_cvt_pk_bf16_f32 v249, v204, v205
	v_cvt_pk_bf16_f32 v250, v206, v207
	v_cvt_pk_bf16_f32 v251, v208, v209
	v_add_u32_e32 v92, 0x80, v198
	v_mad_i64_i32 v[92:93], s[36:37], s0, v92, 0
	v_lshl_add_u64 v[92:93], v[92:93], 1, v[164:165]
	s_cmp_gt_i32 s23, 1
	s_mov_b64 s[36:37], -1
	global_store_dwordx4 v[92:93], v[248:251], off
	s_andn2_b64 vcc, exec, s[36:37]
	s_cmp_eq_u32 s23, 1
	v_pk_fma_f32 v[200:201], v[40:41], v[100:101], v[56:57] op_sel:[0,1,0]
	v_pk_fma_f32 v[204:205], v[42:43], v[100:101], v[58:59] op_sel:[0,1,0]
	v_pk_fma_f32 v[206:207], v[32:33], v[100:101], v[44:45] op_sel:[0,1,0]
	v_pk_fma_f32 v[208:209], v[34:35], v[100:101], v[46:47] op_sel:[0,1,0]
	v_pk_fma_f32 v[200:201], v[88:89], v[100:101], v[200:201] op_sel_hi:[1,0,1]
	v_pk_fma_f32 v[204:205], v[90:91], v[100:101], v[204:205] op_sel_hi:[1,0,1]
	v_pk_fma_f32 v[206:207], v[84:85], v[100:101], v[206:207] op_sel_hi:[1,0,1]
	v_pk_fma_f32 v[208:209], v[86:87], v[100:101], v[208:209] op_sel_hi:[1,0,1]
	v_cvt_pk_bf16_f32 v216, v200, v201
	v_cvt_pk_bf16_f32 v217, v204, v205
	v_cvt_pk_bf16_f32 v218, v206, v207
	v_cvt_pk_bf16_f32 v219, v208, v209
	global_store_dwordx4 v[92:93], v[216:219], off offset:256
	s_cmp_gt_i32 s23, 1
	s_mov_b64 s[36:37], -1
	s_andn2_b64 vcc, exec, s[36:37]
	s_cmp_eq_u32 s23, 1
	v_pk_fma_f32 v[200:201], v[68:69], v[102:103], v[72:73] op_sel:[0,1,0]
	v_pk_fma_f32 v[204:205], v[70:71], v[102:103], v[74:75] op_sel:[0,1,0]
	v_pk_fma_f32 v[206:207], v[60:61], v[102:103], v[64:65] op_sel:[0,1,0]
	v_pk_fma_f32 v[208:209], v[62:63], v[102:103], v[66:67] op_sel:[0,1,0]
	v_pk_fma_f32 v[200:201], v[80:81], v[102:103], v[200:201] op_sel_hi:[1,0,1]
	v_pk_fma_f32 v[204:205], v[82:83], v[102:103], v[204:205] op_sel_hi:[1,0,1]
	v_pk_fma_f32 v[206:207], v[76:77], v[102:103], v[206:207] op_sel_hi:[1,0,1]
	v_pk_fma_f32 v[208:209], v[78:79], v[102:103], v[208:209] op_sel_hi:[1,0,1]
	v_cvt_pk_bf16_f32 v220, v200, v201
	v_cvt_pk_bf16_f32 v221, v204, v205
	v_cvt_pk_bf16_f32 v222, v206, v207
	v_cvt_pk_bf16_f32 v223, v208, v209
	v_add_u32_e32 v76, 0x90, v198
	v_mad_i64_i32 v[76:77], s[36:37], s0, v76, 0
	v_lshl_add_u64 v[76:77], v[76:77], 1, v[164:165]
	global_store_dwordx4 v[76:77], v[220:223], off
	s_cmp_gt_i32 s23, 1
	s_mov_b64 s[36:37], -1
	s_andn2_b64 vcc, exec, s[36:37]
	s_cmp_eq_u32 s23, 1
	v_pk_fma_f32 v[200:201], v[40:41], v[102:103], v[56:57] op_sel:[0,1,0]
	v_pk_fma_f32 v[204:205], v[42:43], v[102:103], v[58:59] op_sel:[0,1,0]
	v_pk_fma_f32 v[206:207], v[32:33], v[102:103], v[44:45] op_sel:[0,1,0]
	v_pk_fma_f32 v[208:209], v[34:35], v[102:103], v[46:47] op_sel:[0,1,0]
	v_pk_fma_f32 v[200:201], v[52:53], v[102:103], v[200:201] op_sel_hi:[1,0,1]
	v_pk_fma_f32 v[204:205], v[54:55], v[102:103], v[204:205] op_sel_hi:[1,0,1]
	v_pk_fma_f32 v[206:207], v[36:37], v[102:103], v[206:207] op_sel_hi:[1,0,1]
	v_pk_fma_f32 v[208:209], v[38:39], v[102:103], v[208:209] op_sel_hi:[1,0,1]
	v_cvt_pk_bf16_f32 v224, v200, v201
	v_cvt_pk_bf16_f32 v225, v204, v205
	v_cvt_pk_bf16_f32 v226, v206, v207
	v_cvt_pk_bf16_f32 v227, v208, v209
	global_store_dwordx4 v[76:77], v[224:227], off offset:256
	s_cmp_gt_i32 s23, 1
	s_mov_b64 s[36:37], -1
	s_andn2_b64 vcc, exec, s[36:37]
	s_cmp_eq_u32 s23, 1
	v_pk_fma_f32 v[200:201], v[68:69], v[48:49], v[72:73] op_sel:[0,1,0]
	v_pk_fma_f32 v[204:205], v[70:71], v[48:49], v[74:75] op_sel:[0,1,0]
	v_pk_fma_f32 v[206:207], v[60:61], v[48:49], v[64:65] op_sel:[0,1,0]
	v_pk_fma_f32 v[208:209], v[62:63], v[48:49], v[66:67] op_sel:[0,1,0]
	v_pk_fma_f32 v[200:201], v[28:29], v[48:49], v[200:201] op_sel_hi:[1,0,1]
	v_pk_fma_f32 v[204:205], v[30:31], v[48:49], v[204:205] op_sel_hi:[1,0,1]
	v_pk_fma_f32 v[206:207], v[24:25], v[48:49], v[206:207] op_sel_hi:[1,0,1]
	v_pk_fma_f32 v[208:209], v[26:27], v[48:49], v[208:209] op_sel_hi:[1,0,1]
	v_cvt_pk_bf16_f32 v228, v200, v201
	v_cvt_pk_bf16_f32 v229, v204, v205
	v_cvt_pk_bf16_f32 v230, v206, v207
	v_cvt_pk_bf16_f32 v231, v208, v209
	v_add_u32_e32 v24, 0xa0, v198
	v_mad_i64_i32 v[24:25], s[36:37], s0, v24, 0
	v_lshl_add_u64 v[24:25], v[24:25], 1, v[164:165]
	s_cmp_gt_i32 s23, 1
	s_mov_b64 s[36:37], -1
	global_store_dwordx4 v[24:25], v[228:231], off
	s_andn2_b64 vcc, exec, s[36:37]
	s_cmp_eq_u32 s23, 1
	v_pk_fma_f32 v[200:201], v[40:41], v[48:49], v[56:57] op_sel:[0,1,0]
	v_pk_fma_f32 v[204:205], v[42:43], v[48:49], v[58:59] op_sel:[0,1,0]
	v_pk_fma_f32 v[206:207], v[32:33], v[48:49], v[44:45] op_sel:[0,1,0]
	v_pk_fma_f32 v[208:209], v[34:35], v[48:49], v[46:47] op_sel:[0,1,0]
	v_pk_fma_f32 v[200:201], v[20:21], v[48:49], v[200:201] op_sel_hi:[1,0,1]
	v_pk_fma_f32 v[204:205], v[22:23], v[48:49], v[204:205] op_sel_hi:[1,0,1]
	v_pk_fma_f32 v[206:207], v[16:17], v[48:49], v[206:207] op_sel_hi:[1,0,1]
	v_pk_fma_f32 v[208:209], v[18:19], v[48:49], v[208:209] op_sel_hi:[1,0,1]
	v_cvt_pk_bf16_f32 v232, v200, v201
	v_cvt_pk_bf16_f32 v233, v204, v205
	v_cvt_pk_bf16_f32 v234, v206, v207
	v_cvt_pk_bf16_f32 v235, v208, v209
	global_store_dwordx4 v[24:25], v[232:235], off offset:256
	s_cmp_gt_i32 s23, 1
	s_mov_b64 s[36:37], -1
	s_andn2_b64 vcc, exec, s[36:37]
	s_cmp_eq_u32 s23, 1
	v_pk_fma_f32 v[200:201], v[68:69], v[50:51], v[72:73] op_sel:[0,1,0]
	v_pk_fma_f32 v[204:205], v[70:71], v[50:51], v[74:75] op_sel:[0,1,0]
	v_pk_fma_f32 v[206:207], v[60:61], v[50:51], v[64:65] op_sel:[0,1,0]
	v_pk_fma_f32 v[208:209], v[62:63], v[50:51], v[66:67] op_sel:[0,1,0]
	v_pk_fma_f32 v[200:201], v[12:13], v[50:51], v[200:201] op_sel_hi:[1,0,1]
	v_pk_fma_f32 v[204:205], v[14:15], v[50:51], v[204:205] op_sel_hi:[1,0,1]
	v_pk_fma_f32 v[206:207], v[8:9], v[50:51], v[206:207] op_sel_hi:[1,0,1]
	v_pk_fma_f32 v[208:209], v[10:11], v[50:51], v[208:209] op_sel_hi:[1,0,1]
	v_cvt_pk_bf16_f32 v236, v200, v201
	v_cvt_pk_bf16_f32 v237, v204, v205
	v_cvt_pk_bf16_f32 v238, v206, v207
	v_cvt_pk_bf16_f32 v239, v208, v209
	v_add_u32_e32 v8, 0xb0, v198
	v_mad_i64_i32 v[8:9], s[36:37], s0, v8, 0
	v_lshl_add_u64 v[8:9], v[8:9], 1, v[164:165]
	global_store_dwordx4 v[8:9], v[236:239], off
	s_cmp_gt_i32 s23, 1
	s_mov_b64 s[36:37], -1
	s_andn2_b64 vcc, exec, s[36:37]
	s_cmp_eq_u32 s23, 1
	s_andn2_b64 vcc, exec, s[10:11]
	s_mov_b64 s[10:11], -1
	v_pk_fma_f32 v[200:201], v[40:41], v[50:51], v[56:57] op_sel:[0,1,0]
	v_pk_fma_f32 v[204:205], v[42:43], v[50:51], v[58:59] op_sel:[0,1,0]
	v_pk_fma_f32 v[206:207], v[32:33], v[50:51], v[44:45] op_sel:[0,1,0]
	v_pk_fma_f32 v[208:209], v[34:35], v[50:51], v[46:47] op_sel:[0,1,0]
	v_pk_fma_f32 v[200:201], v[4:5], v[50:51], v[200:201] op_sel_hi:[1,0,1]
	v_pk_fma_f32 v[204:205], v[6:7], v[50:51], v[204:205] op_sel_hi:[1,0,1]
	v_pk_fma_f32 v[206:207], v[0:1], v[50:51], v[206:207] op_sel_hi:[1,0,1]
	v_pk_fma_f32 v[208:209], v[2:3], v[50:51], v[208:209] op_sel_hi:[1,0,1]
	v_cvt_pk_bf16_f32 v240, v200, v201
	v_cvt_pk_bf16_f32 v241, v204, v205
	v_cvt_pk_bf16_f32 v242, v206, v207
	v_cvt_pk_bf16_f32 v243, v208, v209
	global_store_dwordx4 v[8:9], v[240:243], off offset:256
	s_branch .Le1end_26
.Le1m1_26:
	s_cmp_eq_u32 s36, s61
	s_movk_i32 s0, 0x200
	s_cselect_b32 s0, s0, 0x300
	s_cmp_lg_u32 s36, s60
	v_mov_b32_e32 v44, v192
	v_mov_b32_e32 v198, v193
	s_cselect_b32 s0, s0, 0x100
	s_cmp_lg_u32 s36, s19
	s_cselect_b32 s0, s0, 0
	v_lshl_add_u32 v45, v198, 5, s73
	v_add_u32_e32 v199, s68, v44
	ds_read_b128 v[68:71], v45
	ds_read_b128 v[60:63], v45 offset:16
	ds_read_b128 v[72:75], v45 offset:256
	ds_read_b128 v[64:67], v45 offset:272
	ds_read_b128 v[40:43], v45 offset:128
	ds_read_b128 v[32:35], v45 offset:144
	v_add_u32_e32 v44, s0, v199
	v_lshl_add_u32 v48, v44, 3, v197
	ds_read2_b64 v[172:175], v48 offset1:16
	ds_read_b128 v[56:59], v45 offset:384
	ds_read_b128 v[44:47], v45 offset:400
	ds_read2_b64 v[136:139], v48 offset0:32 offset1:48
	ds_read2_b64 v[100:103], v48 offset0:128 offset1:144
	ds_read2_b64 v[48:51], v48 offset0:160 offset1:176
	s_waitcnt lgkmcnt(0)
	s_cmp_gt_i32 s23, 1
	s_mov_b64 s[46:47], -1
	s_andn2_b64 vcc, exec, s[46:47]
	s_cmp_eq_u32 s23, 1
	s_add_i32 s0, s48, 0xfffff400
	s_lshl_b64 s[46:47], s[0:1], 1
	s_add_u32 s0, s56, s46
	s_addc_u32 s25, s57, s47
	s_ashr_i32 s49, s48, 31
	s_lshl_b64 s[46:47], s[48:49], 1
	s_add_u32 s37, s42, s46
	s_addc_u32 s46, s43, s47
	s_cmp_lt_i32 s40, 12
	s_cselect_b32 s0, s37, s0
	v_pk_fma_f32 v[200:201], v[68:69], v[172:173], v[72:73] op_sel:[0,1,0]
	v_pk_fma_f32 v[204:205], v[70:71], v[172:173], v[74:75] op_sel:[0,1,0]
	v_pk_fma_f32 v[206:207], v[60:61], v[172:173], v[64:65] op_sel:[0,1,0]
	v_pk_fma_f32 v[208:209], v[62:63], v[172:173], v[66:67] op_sel:[0,1,0]
	v_pk_fma_f32 v[200:201], v[168:169], v[172:173], v[200:201] op_sel_hi:[1,0,1]
	v_pk_fma_f32 v[204:205], v[170:171], v[172:173], v[204:205] op_sel_hi:[1,0,1]
	v_pk_fma_f32 v[206:207], v[164:165], v[172:173], v[206:207] op_sel_hi:[1,0,1]
	v_pk_fma_f32 v[208:209], v[166:167], v[172:173], v[208:209] op_sel_hi:[1,0,1]
	v_pk_mul_f32 v[200:201], v[200:201], s[18:19] op_sel_hi:[1,0]
	v_pk_mul_f32 v[204:205], v[204:205], s[18:19] op_sel_hi:[1,0]
	v_pk_mul_f32 v[206:207], v[206:207], s[18:19] op_sel_hi:[1,0]
	v_pk_mul_f32 v[208:209], v[208:209], s[18:19] op_sel_hi:[1,0]
	v_cvt_pk_bf16_f32 v216, v200, v201
	v_cvt_pk_bf16_f32 v217, v204, v205
	v_cvt_pk_bf16_f32 v218, v206, v207
	v_cvt_pk_bf16_f32 v219, v208, v209
	v_lshl_add_u32 v164, v198, 3, s69
	s_cselect_b32 s25, s46, s25
	v_mov_b32_e32 v166, s0
	s_movk_i32 s0, 0xc00
	v_mov_b32_e32 v167, s25
	s_cselect_b32 s0, s0, 0x800
	v_ashrrev_i32_e32 v165, 31, v164
	v_lshl_add_u32 v198, s36, 8, v199
	v_lshl_add_u64 v[164:165], v[164:165], 1, v[166:167]
	v_mad_i64_i32 v[166:167], s[36:37], s0, v198, 0
	v_lshl_add_u64 v[166:167], v[166:167], 1, v[164:165]
	s_cmp_gt_i32 s23, 1
	s_mov_b64 s[36:37], -1
	global_store_dwordx4 v[166:167], v[216:219], off
	s_andn2_b64 vcc, exec, s[36:37]
	s_cmp_eq_u32 s23, 1
	v_pk_fma_f32 v[200:201], v[40:41], v[172:173], v[56:57] op_sel:[0,1,0]
	v_pk_fma_f32 v[204:205], v[42:43], v[172:173], v[58:59] op_sel:[0,1,0]
	v_pk_fma_f32 v[206:207], v[32:33], v[172:173], v[44:45] op_sel:[0,1,0]
	v_pk_fma_f32 v[208:209], v[34:35], v[172:173], v[46:47] op_sel:[0,1,0]
	v_pk_fma_f32 v[200:201], v[160:161], v[172:173], v[200:201] op_sel_hi:[1,0,1]
	v_pk_fma_f32 v[204:205], v[162:163], v[172:173], v[204:205] op_sel_hi:[1,0,1]
	v_pk_fma_f32 v[206:207], v[156:157], v[172:173], v[206:207] op_sel_hi:[1,0,1]
	v_pk_fma_f32 v[208:209], v[158:159], v[172:173], v[208:209] op_sel_hi:[1,0,1]
	v_pk_mul_f32 v[200:201], v[200:201], s[18:19] op_sel_hi:[1,0]
	v_pk_mul_f32 v[204:205], v[204:205], s[18:19] op_sel_hi:[1,0]
	v_pk_mul_f32 v[206:207], v[206:207], s[18:19] op_sel_hi:[1,0]
	v_pk_mul_f32 v[208:209], v[208:209], s[18:19] op_sel_hi:[1,0]
	v_cvt_pk_bf16_f32 v220, v200, v201
	v_cvt_pk_bf16_f32 v221, v204, v205
	v_cvt_pk_bf16_f32 v222, v206, v207
	v_cvt_pk_bf16_f32 v223, v208, v209
	global_store_dwordx4 v[166:167], v[220:223], off offset:256
	s_cmp_gt_i32 s23, 1
	s_mov_b64 s[36:37], -1
	s_andn2_b64 vcc, exec, s[36:37]
	s_cmp_eq_u32 s23, 1
	v_pk_fma_f32 v[200:201], v[68:69], v[174:175], v[72:73] op_sel:[0,1,0]
	v_pk_fma_f32 v[204:205], v[70:71], v[174:175], v[74:75] op_sel:[0,1,0]
	v_pk_fma_f32 v[206:207], v[60:61], v[174:175], v[64:65] op_sel:[0,1,0]
	v_pk_fma_f32 v[208:209], v[62:63], v[174:175], v[66:67] op_sel:[0,1,0]
	v_pk_fma_f32 v[200:201], v[152:153], v[174:175], v[200:201] op_sel_hi:[1,0,1]
	v_pk_fma_f32 v[204:205], v[154:155], v[174:175], v[204:205] op_sel_hi:[1,0,1]
	v_pk_fma_f32 v[206:207], v[148:149], v[174:175], v[206:207] op_sel_hi:[1,0,1]
	v_pk_fma_f32 v[208:209], v[150:151], v[174:175], v[208:209] op_sel_hi:[1,0,1]
	v_pk_mul_f32 v[200:201], v[200:201], s[18:19] op_sel_hi:[1,0]
	v_pk_mul_f32 v[204:205], v[204:205], s[18:19] op_sel_hi:[1,0]
	v_pk_mul_f32 v[206:207], v[206:207], s[18:19] op_sel_hi:[1,0]
	v_pk_mul_f32 v[208:209], v[208:209], s[18:19] op_sel_hi:[1,0]
	v_cvt_pk_bf16_f32 v224, v200, v201
	v_cvt_pk_bf16_f32 v225, v204, v205
	v_cvt_pk_bf16_f32 v226, v206, v207
	v_cvt_pk_bf16_f32 v227, v208, v209
	v_add_u32_e32 v148, 16, v198
	v_mad_i64_i32 v[148:149], s[36:37], s0, v148, 0
	v_lshl_add_u64 v[148:149], v[148:149], 1, v[164:165]
	global_store_dwordx4 v[148:149], v[224:227], off
	s_cmp_gt_i32 s23, 1
	s_mov_b64 s[36:37], -1
	s_andn2_b64 vcc, exec, s[36:37]
	s_cmp_eq_u32 s23, 1
	v_pk_fma_f32 v[200:201], v[40:41], v[174:175], v[56:57] op_sel:[0,1,0]
	v_pk_fma_f32 v[204:205], v[42:43], v[174:175], v[58:59] op_sel:[0,1,0]
	v_pk_fma_f32 v[206:207], v[32:33], v[174:175], v[44:45] op_sel:[0,1,0]
	v_pk_fma_f32 v[208:209], v[34:35], v[174:175], v[46:47] op_sel:[0,1,0]
	v_pk_fma_f32 v[200:201], v[144:145], v[174:175], v[200:201] op_sel_hi:[1,0,1]
	v_pk_fma_f32 v[204:205], v[146:147], v[174:175], v[204:205] op_sel_hi:[1,0,1]
	v_pk_fma_f32 v[206:207], v[140:141], v[174:175], v[206:207] op_sel_hi:[1,0,1]
	v_pk_fma_f32 v[208:209], v[142:143], v[174:175], v[208:209] op_sel_hi:[1,0,1]
	v_pk_mul_f32 v[200:201], v[200:201], s[18:19] op_sel_hi:[1,0]
	v_pk_mul_f32 v[204:205], v[204:205], s[18:19] op_sel_hi:[1,0]
	v_pk_mul_f32 v[206:207], v[206:207], s[18:19] op_sel_hi:[1,0]
	v_pk_mul_f32 v[208:209], v[208:209], s[18:19] op_sel_hi:[1,0]
	v_cvt_pk_bf16_f32 v228, v200, v201
	v_cvt_pk_bf16_f32 v229, v204, v205
	v_cvt_pk_bf16_f32 v230, v206, v207
	v_cvt_pk_bf16_f32 v231, v208, v209
	global_store_dwordx4 v[148:149], v[228:231], off offset:256
	s_cmp_gt_i32 s23, 1
	s_mov_b64 s[36:37], -1
	s_andn2_b64 vcc, exec, s[36:37]
	s_cmp_eq_u32 s23, 1
	v_pk_fma_f32 v[200:201], v[68:69], v[136:137], v[72:73] op_sel:[0,1,0]
	v_pk_fma_f32 v[204:205], v[70:71], v[136:137], v[74:75] op_sel:[0,1,0]
	v_pk_fma_f32 v[206:207], v[60:61], v[136:137], v[64:65] op_sel:[0,1,0]
	v_pk_fma_f32 v[208:209], v[62:63], v[136:137], v[66:67] op_sel:[0,1,0]
	v_pk_fma_f32 v[200:201], v[132:133], v[136:137], v[200:201] op_sel_hi:[1,0,1]
	v_pk_fma_f32 v[204:205], v[134:135], v[136:137], v[204:205] op_sel_hi:[1,0,1]
	v_pk_fma_f32 v[206:207], v[128:129], v[136:137], v[206:207] op_sel_hi:[1,0,1]
	v_pk_fma_f32 v[208:209], v[130:131], v[136:137], v[208:209] op_sel_hi:[1,0,1]
	v_pk_mul_f32 v[200:201], v[200:201], s[18:19] op_sel_hi:[1,0]
	v_pk_mul_f32 v[204:205], v[204:205], s[18:19] op_sel_hi:[1,0]
	v_pk_mul_f32 v[206:207], v[206:207], s[18:19] op_sel_hi:[1,0]
	v_pk_mul_f32 v[208:209], v[208:209], s[18:19] op_sel_hi:[1,0]
	v_cvt_pk_bf16_f32 v232, v200, v201
	v_cvt_pk_bf16_f32 v233, v204, v205
	v_cvt_pk_bf16_f32 v234, v206, v207
	v_cvt_pk_bf16_f32 v235, v208, v209
	v_add_u32_e32 v128, 32, v198
	v_mad_i64_i32 v[128:129], s[36:37], s0, v128, 0
	v_lshl_add_u64 v[128:129], v[128:129], 1, v[164:165]
	s_cmp_gt_i32 s23, 1
	s_mov_b64 s[36:37], -1
	global_store_dwordx4 v[128:129], v[232:235], off
	s_andn2_b64 vcc, exec, s[36:37]
	s_cmp_eq_u32 s23, 1
	v_pk_fma_f32 v[200:201], v[40:41], v[136:137], v[56:57] op_sel:[0,1,0]
	v_pk_fma_f32 v[204:205], v[42:43], v[136:137], v[58:59] op_sel:[0,1,0]
	v_pk_fma_f32 v[206:207], v[32:33], v[136:137], v[44:45] op_sel:[0,1,0]
	v_pk_fma_f32 v[208:209], v[34:35], v[136:137], v[46:47] op_sel:[0,1,0]
	v_pk_fma_f32 v[200:201], v[124:125], v[136:137], v[200:201] op_sel_hi:[1,0,1]
	v_pk_fma_f32 v[204:205], v[126:127], v[136:137], v[204:205] op_sel_hi:[1,0,1]
	v_pk_fma_f32 v[206:207], v[120:121], v[136:137], v[206:207] op_sel_hi:[1,0,1]
	v_pk_fma_f32 v[208:209], v[122:123], v[136:137], v[208:209] op_sel_hi:[1,0,1]
	v_pk_mul_f32 v[200:201], v[200:201], s[18:19] op_sel_hi:[1,0]
	v_pk_mul_f32 v[204:205], v[204:205], s[18:19] op_sel_hi:[1,0]
	v_pk_mul_f32 v[206:207], v[206:207], s[18:19] op_sel_hi:[1,0]
	v_pk_mul_f32 v[208:209], v[208:209], s[18:19] op_sel_hi:[1,0]
	v_cvt_pk_bf16_f32 v236, v200, v201
	v_cvt_pk_bf16_f32 v237, v204, v205
	v_cvt_pk_bf16_f32 v238, v206, v207
	v_cvt_pk_bf16_f32 v239, v208, v209
	global_store_dwordx4 v[128:129], v[236:239], off offset:256
	s_cmp_gt_i32 s23, 1
	s_mov_b64 s[36:37], -1
	s_andn2_b64 vcc, exec, s[36:37]
	s_cmp_eq_u32 s23, 1
	v_pk_fma_f32 v[200:201], v[68:69], v[138:139], v[72:73] op_sel:[0,1,0]
	v_pk_fma_f32 v[204:205], v[70:71], v[138:139], v[74:75] op_sel:[0,1,0]
	v_pk_fma_f32 v[206:207], v[60:61], v[138:139], v[64:65] op_sel:[0,1,0]
	v_pk_fma_f32 v[208:209], v[62:63], v[138:139], v[66:67] op_sel:[0,1,0]
	v_pk_fma_f32 v[200:201], v[116:117], v[138:139], v[200:201] op_sel_hi:[1,0,1]
	v_pk_fma_f32 v[204:205], v[118:119], v[138:139], v[204:205] op_sel_hi:[1,0,1]
	v_pk_fma_f32 v[206:207], v[112:113], v[138:139], v[206:207] op_sel_hi:[1,0,1]
	v_pk_fma_f32 v[208:209], v[114:115], v[138:139], v[208:209] op_sel_hi:[1,0,1]
	v_pk_mul_f32 v[200:201], v[200:201], s[18:19] op_sel_hi:[1,0]
	v_pk_mul_f32 v[204:205], v[204:205], s[18:19] op_sel_hi:[1,0]
	v_pk_mul_f32 v[206:207], v[206:207], s[18:19] op_sel_hi:[1,0]
	v_pk_mul_f32 v[208:209], v[208:209], s[18:19] op_sel_hi:[1,0]
	v_cvt_pk_bf16_f32 v240, v200, v201
	v_cvt_pk_bf16_f32 v241, v204, v205
	v_cvt_pk_bf16_f32 v242, v206, v207
	v_cvt_pk_bf16_f32 v243, v208, v209
	v_add_u32_e32 v112, 48, v198
	v_mad_i64_i32 v[112:113], s[36:37], s0, v112, 0
	v_lshl_add_u64 v[112:113], v[112:113], 1, v[164:165]
	global_store_dwordx4 v[112:113], v[240:243], off
	s_cmp_gt_i32 s23, 1
	s_mov_b64 s[36:37], -1
	s_andn2_b64 vcc, exec, s[36:37]
	s_cmp_eq_u32 s23, 1
	v_pk_fma_f32 v[200:201], v[40:41], v[138:139], v[56:57] op_sel:[0,1,0]
	v_pk_fma_f32 v[204:205], v[42:43], v[138:139], v[58:59] op_sel:[0,1,0]
	v_pk_fma_f32 v[206:207], v[32:33], v[138:139], v[44:45] op_sel:[0,1,0]
	v_pk_fma_f32 v[208:209], v[34:35], v[138:139], v[46:47] op_sel:[0,1,0]
	v_pk_fma_f32 v[200:201], v[108:109], v[138:139], v[200:201] op_sel_hi:[1,0,1]
	v_pk_fma_f32 v[204:205], v[110:111], v[138:139], v[204:205] op_sel_hi:[1,0,1]
	v_pk_fma_f32 v[206:207], v[104:105], v[138:139], v[206:207] op_sel_hi:[1,0,1]
	v_pk_fma_f32 v[208:209], v[106:107], v[138:139], v[208:209] op_sel_hi:[1,0,1]
	v_pk_mul_f32 v[200:201], v[200:201], s[18:19] op_sel_hi:[1,0]
	v_pk_mul_f32 v[204:205], v[204:205], s[18:19] op_sel_hi:[1,0]
	v_pk_mul_f32 v[206:207], v[206:207], s[18:19] op_sel_hi:[1,0]
	v_pk_mul_f32 v[208:209], v[208:209], s[18:19] op_sel_hi:[1,0]
	v_cvt_pk_bf16_f32 v244, v200, v201
	v_cvt_pk_bf16_f32 v245, v204, v205
	v_cvt_pk_bf16_f32 v246, v206, v207
	v_cvt_pk_bf16_f32 v247, v208, v209
	global_store_dwordx4 v[112:113], v[244:247], off offset:256
	s_cmp_gt_i32 s23, 1
	s_mov_b64 s[36:37], -1
	s_andn2_b64 vcc, exec, s[36:37]
	s_cmp_eq_u32 s23, 1
	v_pk_fma_f32 v[200:201], v[68:69], v[100:101], v[72:73] op_sel:[0,1,0]
	v_pk_fma_f32 v[204:205], v[70:71], v[100:101], v[74:75] op_sel:[0,1,0]
	v_pk_fma_f32 v[206:207], v[60:61], v[100:101], v[64:65] op_sel:[0,1,0]
	v_pk_fma_f32 v[208:209], v[62:63], v[100:101], v[66:67] op_sel:[0,1,0]
	v_pk_fma_f32 v[200:201], v[96:97], v[100:101], v[200:201] op_sel_hi:[1,0,1]
	v_pk_fma_f32 v[204:205], v[98:99], v[100:101], v[204:205] op_sel_hi:[1,0,1]
	v_pk_fma_f32 v[206:207], v[92:93], v[100:101], v[206:207] op_sel_hi:[1,0,1]
	v_pk_fma_f32 v[208:209], v[94:95], v[100:101], v[208:209] op_sel_hi:[1,0,1]
	v_pk_mul_f32 v[200:201], v[200:201], s[18:19] op_sel_hi:[1,0]
	v_pk_mul_f32 v[204:205], v[204:205], s[18:19] op_sel_hi:[1,0]
	v_pk_mul_f32 v[206:207], v[206:207], s[18:19] op_sel_hi:[1,0]
	v_pk_mul_f32 v[208:209], v[208:209], s[18:19] op_sel_hi:[1,0]
	v_cvt_pk_bf16_f32 v248, v200, v201
	v_cvt_pk_bf16_f32 v249, v204, v205
	v_cvt_pk_bf16_f32 v250, v206, v207
	v_cvt_pk_bf16_f32 v251, v208, v209
	v_add_u32_e32 v92, 0x80, v198
	v_mad_i64_i32 v[92:93], s[36:37], s0, v92, 0
	v_lshl_add_u64 v[92:93], v[92:93], 1, v[164:165]
	s_cmp_gt_i32 s23, 1
	s_mov_b64 s[36:37], -1
	global_store_dwordx4 v[92:93], v[248:251], off
	s_andn2_b64 vcc, exec, s[36:37]
	s_cmp_eq_u32 s23, 1
	v_pk_fma_f32 v[200:201], v[40:41], v[100:101], v[56:57] op_sel:[0,1,0]
	v_pk_fma_f32 v[204:205], v[42:43], v[100:101], v[58:59] op_sel:[0,1,0]
	v_pk_fma_f32 v[206:207], v[32:33], v[100:101], v[44:45] op_sel:[0,1,0]
	v_pk_fma_f32 v[208:209], v[34:35], v[100:101], v[46:47] op_sel:[0,1,0]
	v_pk_fma_f32 v[200:201], v[88:89], v[100:101], v[200:201] op_sel_hi:[1,0,1]
	v_pk_fma_f32 v[204:205], v[90:91], v[100:101], v[204:205] op_sel_hi:[1,0,1]
	v_pk_fma_f32 v[206:207], v[84:85], v[100:101], v[206:207] op_sel_hi:[1,0,1]
	v_pk_fma_f32 v[208:209], v[86:87], v[100:101], v[208:209] op_sel_hi:[1,0,1]
	v_pk_mul_f32 v[200:201], v[200:201], s[18:19] op_sel_hi:[1,0]
	v_pk_mul_f32 v[204:205], v[204:205], s[18:19] op_sel_hi:[1,0]
	v_pk_mul_f32 v[206:207], v[206:207], s[18:19] op_sel_hi:[1,0]
	v_pk_mul_f32 v[208:209], v[208:209], s[18:19] op_sel_hi:[1,0]
	v_cvt_pk_bf16_f32 v216, v200, v201
	v_cvt_pk_bf16_f32 v217, v204, v205
	v_cvt_pk_bf16_f32 v218, v206, v207
	v_cvt_pk_bf16_f32 v219, v208, v209
	global_store_dwordx4 v[92:93], v[216:219], off offset:256
	s_cmp_gt_i32 s23, 1
	s_mov_b64 s[36:37], -1
	s_andn2_b64 vcc, exec, s[36:37]
	s_cmp_eq_u32 s23, 1
	v_pk_fma_f32 v[200:201], v[68:69], v[102:103], v[72:73] op_sel:[0,1,0]
	v_pk_fma_f32 v[204:205], v[70:71], v[102:103], v[74:75] op_sel:[0,1,0]
	v_pk_fma_f32 v[206:207], v[60:61], v[102:103], v[64:65] op_sel:[0,1,0]
	v_pk_fma_f32 v[208:209], v[62:63], v[102:103], v[66:67] op_sel:[0,1,0]
	v_pk_fma_f32 v[200:201], v[80:81], v[102:103], v[200:201] op_sel_hi:[1,0,1]
	v_pk_fma_f32 v[204:205], v[82:83], v[102:103], v[204:205] op_sel_hi:[1,0,1]
	v_pk_fma_f32 v[206:207], v[76:77], v[102:103], v[206:207] op_sel_hi:[1,0,1]
	v_pk_fma_f32 v[208:209], v[78:79], v[102:103], v[208:209] op_sel_hi:[1,0,1]
	v_pk_mul_f32 v[200:201], v[200:201], s[18:19] op_sel_hi:[1,0]
	v_pk_mul_f32 v[204:205], v[204:205], s[18:19] op_sel_hi:[1,0]
	v_pk_mul_f32 v[206:207], v[206:207], s[18:19] op_sel_hi:[1,0]
	v_pk_mul_f32 v[208:209], v[208:209], s[18:19] op_sel_hi:[1,0]
	v_cvt_pk_bf16_f32 v220, v200, v201
	v_cvt_pk_bf16_f32 v221, v204, v205
	v_cvt_pk_bf16_f32 v222, v206, v207
	v_cvt_pk_bf16_f32 v223, v208, v209
	v_add_u32_e32 v76, 0x90, v198
	v_mad_i64_i32 v[76:77], s[36:37], s0, v76, 0
	v_lshl_add_u64 v[76:77], v[76:77], 1, v[164:165]
	global_store_dwordx4 v[76:77], v[220:223], off
	s_cmp_gt_i32 s23, 1
	s_mov_b64 s[36:37], -1
	s_andn2_b64 vcc, exec, s[36:37]
	s_cmp_eq_u32 s23, 1
	v_pk_fma_f32 v[200:201], v[40:41], v[102:103], v[56:57] op_sel:[0,1,0]
	v_pk_fma_f32 v[204:205], v[42:43], v[102:103], v[58:59] op_sel:[0,1,0]
	v_pk_fma_f32 v[206:207], v[32:33], v[102:103], v[44:45] op_sel:[0,1,0]
	v_pk_fma_f32 v[208:209], v[34:35], v[102:103], v[46:47] op_sel:[0,1,0]
	v_pk_fma_f32 v[200:201], v[52:53], v[102:103], v[200:201] op_sel_hi:[1,0,1]
	v_pk_fma_f32 v[204:205], v[54:55], v[102:103], v[204:205] op_sel_hi:[1,0,1]
	v_pk_fma_f32 v[206:207], v[36:37], v[102:103], v[206:207] op_sel_hi:[1,0,1]
	v_pk_fma_f32 v[208:209], v[38:39], v[102:103], v[208:209] op_sel_hi:[1,0,1]
	v_pk_mul_f32 v[200:201], v[200:201], s[18:19] op_sel_hi:[1,0]
	v_pk_mul_f32 v[204:205], v[204:205], s[18:19] op_sel_hi:[1,0]
	v_pk_mul_f32 v[206:207], v[206:207], s[18:19] op_sel_hi:[1,0]
	v_pk_mul_f32 v[208:209], v[208:209], s[18:19] op_sel_hi:[1,0]
	v_cvt_pk_bf16_f32 v224, v200, v201
	v_cvt_pk_bf16_f32 v225, v204, v205
	v_cvt_pk_bf16_f32 v226, v206, v207
	v_cvt_pk_bf16_f32 v227, v208, v209
	global_store_dwordx4 v[76:77], v[224:227], off offset:256
	s_cmp_gt_i32 s23, 1
	s_mov_b64 s[36:37], -1
	s_andn2_b64 vcc, exec, s[36:37]
	s_cmp_eq_u32 s23, 1
	v_pk_fma_f32 v[200:201], v[68:69], v[48:49], v[72:73] op_sel:[0,1,0]
	v_pk_fma_f32 v[204:205], v[70:71], v[48:49], v[74:75] op_sel:[0,1,0]
	v_pk_fma_f32 v[206:207], v[60:61], v[48:49], v[64:65] op_sel:[0,1,0]
	v_pk_fma_f32 v[208:209], v[62:63], v[48:49], v[66:67] op_sel:[0,1,0]
	v_pk_fma_f32 v[200:201], v[28:29], v[48:49], v[200:201] op_sel_hi:[1,0,1]
	v_pk_fma_f32 v[204:205], v[30:31], v[48:49], v[204:205] op_sel_hi:[1,0,1]
	v_pk_fma_f32 v[206:207], v[24:25], v[48:49], v[206:207] op_sel_hi:[1,0,1]
	v_pk_fma_f32 v[208:209], v[26:27], v[48:49], v[208:209] op_sel_hi:[1,0,1]
	v_pk_mul_f32 v[200:201], v[200:201], s[18:19] op_sel_hi:[1,0]
	v_pk_mul_f32 v[204:205], v[204:205], s[18:19] op_sel_hi:[1,0]
	v_pk_mul_f32 v[206:207], v[206:207], s[18:19] op_sel_hi:[1,0]
	v_pk_mul_f32 v[208:209], v[208:209], s[18:19] op_sel_hi:[1,0]
	v_cvt_pk_bf16_f32 v228, v200, v201
	v_cvt_pk_bf16_f32 v229, v204, v205
	v_cvt_pk_bf16_f32 v230, v206, v207
	v_cvt_pk_bf16_f32 v231, v208, v209
	v_add_u32_e32 v24, 0xa0, v198
	v_mad_i64_i32 v[24:25], s[36:37], s0, v24, 0
	v_lshl_add_u64 v[24:25], v[24:25], 1, v[164:165]
	s_cmp_gt_i32 s23, 1
	s_mov_b64 s[36:37], -1
	global_store_dwordx4 v[24:25], v[228:231], off
	s_andn2_b64 vcc, exec, s[36:37]
	s_cmp_eq_u32 s23, 1
	v_pk_fma_f32 v[200:201], v[40:41], v[48:49], v[56:57] op_sel:[0,1,0]
	v_pk_fma_f32 v[204:205], v[42:43], v[48:49], v[58:59] op_sel:[0,1,0]
	v_pk_fma_f32 v[206:207], v[32:33], v[48:49], v[44:45] op_sel:[0,1,0]
	v_pk_fma_f32 v[208:209], v[34:35], v[48:49], v[46:47] op_sel:[0,1,0]
	v_pk_fma_f32 v[200:201], v[20:21], v[48:49], v[200:201] op_sel_hi:[1,0,1]
	v_pk_fma_f32 v[204:205], v[22:23], v[48:49], v[204:205] op_sel_hi:[1,0,1]
	v_pk_fma_f32 v[206:207], v[16:17], v[48:49], v[206:207] op_sel_hi:[1,0,1]
	v_pk_fma_f32 v[208:209], v[18:19], v[48:49], v[208:209] op_sel_hi:[1,0,1]
	v_pk_mul_f32 v[200:201], v[200:201], s[18:19] op_sel_hi:[1,0]
	v_pk_mul_f32 v[204:205], v[204:205], s[18:19] op_sel_hi:[1,0]
	v_pk_mul_f32 v[206:207], v[206:207], s[18:19] op_sel_hi:[1,0]
	v_pk_mul_f32 v[208:209], v[208:209], s[18:19] op_sel_hi:[1,0]
	v_cvt_pk_bf16_f32 v232, v200, v201
	v_cvt_pk_bf16_f32 v233, v204, v205
	v_cvt_pk_bf16_f32 v234, v206, v207
	v_cvt_pk_bf16_f32 v235, v208, v209
	global_store_dwordx4 v[24:25], v[232:235], off offset:256
	s_cmp_gt_i32 s23, 1
	s_mov_b64 s[36:37], -1
	s_andn2_b64 vcc, exec, s[36:37]
	s_cmp_eq_u32 s23, 1
	v_pk_fma_f32 v[200:201], v[68:69], v[50:51], v[72:73] op_sel:[0,1,0]
	v_pk_fma_f32 v[204:205], v[70:71], v[50:51], v[74:75] op_sel:[0,1,0]
	v_pk_fma_f32 v[206:207], v[60:61], v[50:51], v[64:65] op_sel:[0,1,0]
	v_pk_fma_f32 v[208:209], v[62:63], v[50:51], v[66:67] op_sel:[0,1,0]
	v_pk_fma_f32 v[200:201], v[12:13], v[50:51], v[200:201] op_sel_hi:[1,0,1]
	v_pk_fma_f32 v[204:205], v[14:15], v[50:51], v[204:205] op_sel_hi:[1,0,1]
	v_pk_fma_f32 v[206:207], v[8:9], v[50:51], v[206:207] op_sel_hi:[1,0,1]
	v_pk_fma_f32 v[208:209], v[10:11], v[50:51], v[208:209] op_sel_hi:[1,0,1]
	v_pk_mul_f32 v[200:201], v[200:201], s[18:19] op_sel_hi:[1,0]
	v_pk_mul_f32 v[204:205], v[204:205], s[18:19] op_sel_hi:[1,0]
	v_pk_mul_f32 v[206:207], v[206:207], s[18:19] op_sel_hi:[1,0]
	v_pk_mul_f32 v[208:209], v[208:209], s[18:19] op_sel_hi:[1,0]
	v_cvt_pk_bf16_f32 v236, v200, v201
	v_cvt_pk_bf16_f32 v237, v204, v205
	v_cvt_pk_bf16_f32 v238, v206, v207
	v_cvt_pk_bf16_f32 v239, v208, v209
	v_add_u32_e32 v8, 0xb0, v198
	v_mad_i64_i32 v[8:9], s[36:37], s0, v8, 0
	v_lshl_add_u64 v[8:9], v[8:9], 1, v[164:165]
	global_store_dwordx4 v[8:9], v[236:239], off
	s_cmp_gt_i32 s23, 1
	s_mov_b64 s[36:37], -1
	s_andn2_b64 vcc, exec, s[36:37]
	s_cmp_eq_u32 s23, 1
	s_andn2_b64 vcc, exec, s[10:11]
	s_mov_b64 s[10:11], -1
	v_pk_fma_f32 v[200:201], v[40:41], v[50:51], v[56:57] op_sel:[0,1,0]
	v_pk_fma_f32 v[204:205], v[42:43], v[50:51], v[58:59] op_sel:[0,1,0]
	v_pk_fma_f32 v[206:207], v[32:33], v[50:51], v[44:45] op_sel:[0,1,0]
	v_pk_fma_f32 v[208:209], v[34:35], v[50:51], v[46:47] op_sel:[0,1,0]
	v_pk_fma_f32 v[200:201], v[4:5], v[50:51], v[200:201] op_sel_hi:[1,0,1]
	v_pk_fma_f32 v[204:205], v[6:7], v[50:51], v[204:205] op_sel_hi:[1,0,1]
	v_pk_fma_f32 v[206:207], v[0:1], v[50:51], v[206:207] op_sel_hi:[1,0,1]
	v_pk_fma_f32 v[208:209], v[2:3], v[50:51], v[208:209] op_sel_hi:[1,0,1]
	v_pk_mul_f32 v[200:201], v[200:201], s[18:19] op_sel_hi:[1,0]
	v_pk_mul_f32 v[204:205], v[204:205], s[18:19] op_sel_hi:[1,0]
	v_pk_mul_f32 v[206:207], v[206:207], s[18:19] op_sel_hi:[1,0]
	v_pk_mul_f32 v[208:209], v[208:209], s[18:19] op_sel_hi:[1,0]
	v_cvt_pk_bf16_f32 v240, v200, v201
	v_cvt_pk_bf16_f32 v241, v204, v205
	v_cvt_pk_bf16_f32 v242, v206, v207
	v_cvt_pk_bf16_f32 v243, v208, v209
	global_store_dwordx4 v[8:9], v[240:243], off offset:256
	s_branch .Le1end_26
.Le1m2_26:
	v_mov_b32_e32 v200, 0xbfb8aa3b
	v_mov_b32_e32 v201, 1.0
	s_cmp_eq_u32 s36, s61
	s_movk_i32 s0, 0x200
	s_cselect_b32 s0, s0, 0x300
	s_cmp_lg_u32 s36, s60
	v_mov_b32_e32 v44, v192
	v_mov_b32_e32 v198, v193
	s_cselect_b32 s0, s0, 0x100
	s_cmp_lg_u32 s36, s19
	s_cselect_b32 s0, s0, 0
	v_lshl_add_u32 v45, v198, 5, s73
	v_add_u32_e32 v199, s68, v44
	ds_read_b128 v[68:71], v45
	ds_read_b128 v[60:63], v45 offset:16
	ds_read_b128 v[72:75], v45 offset:256
	ds_read_b128 v[64:67], v45 offset:272
	ds_read_b128 v[40:43], v45 offset:128
	ds_read_b128 v[32:35], v45 offset:144
	v_add_u32_e32 v44, s0, v199
	v_lshl_add_u32 v48, v44, 3, v197
	ds_read2_b64 v[172:175], v48 offset1:16
	ds_read_b128 v[56:59], v45 offset:384
	ds_read_b128 v[44:47], v45 offset:400
	ds_read2_b64 v[136:139], v48 offset0:32 offset1:48
	ds_read2_b64 v[100:103], v48 offset0:128 offset1:144
	ds_read2_b64 v[48:51], v48 offset0:160 offset1:176
	s_waitcnt lgkmcnt(0)
	s_cmp_gt_i32 s23, 1
	s_mov_b64 s[46:47], -1
	s_mov_b64 s[46:47], 0
	s_andn2_b64 vcc, exec, s[46:47]
	s_add_i32 s0, s48, 0xfffff400
	s_lshl_b64 s[46:47], s[0:1], 1
	s_add_u32 s0, s56, s46
	s_addc_u32 s25, s57, s47
	s_ashr_i32 s49, s48, 31
	s_lshl_b64 s[46:47], s[48:49], 1
	s_add_u32 s37, s42, s46
	s_addc_u32 s46, s43, s47
	s_cmp_lt_i32 s40, 12
	s_cselect_b32 s0, s37, s0
	v_pk_fma_f32 v[204:205], v[68:69], v[172:173], v[72:73] op_sel:[0,1,0]
	v_pk_fma_f32 v[206:207], v[70:71], v[172:173], v[74:75] op_sel:[0,1,0]
	v_pk_fma_f32 v[208:209], v[60:61], v[172:173], v[64:65] op_sel:[0,1,0]
	v_pk_fma_f32 v[210:211], v[62:63], v[172:173], v[66:67] op_sel:[0,1,0]
	v_pk_fma_f32 v[204:205], v[168:169], v[172:173], v[204:205] op_sel_hi:[1,0,1]
	v_pk_fma_f32 v[206:207], v[170:171], v[172:173], v[206:207] op_sel_hi:[1,0,1]
	v_pk_fma_f32 v[208:209], v[164:165], v[172:173], v[208:209] op_sel_hi:[1,0,1]
	v_pk_fma_f32 v[210:211], v[166:167], v[172:173], v[210:211] op_sel_hi:[1,0,1]
	v_pk_mul_f32 v[216:217], v[204:205], v[200:201] op_sel_hi:[1,0]
	v_pk_mul_f32 v[218:219], v[206:207], v[200:201] op_sel_hi:[1,0]
	v_pk_mul_f32 v[220:221], v[208:209], v[200:201] op_sel_hi:[1,0]
	v_pk_mul_f32 v[222:223], v[210:211], v[200:201] op_sel_hi:[1,0]
	v_exp_f32_e32 v216, v216
	v_exp_f32_e32 v217, v217
	v_exp_f32_e32 v218, v218
	v_exp_f32_e32 v219, v219
	v_exp_f32_e32 v220, v220
	v_exp_f32_e32 v221, v221
	v_exp_f32_e32 v222, v222
	v_exp_f32_e32 v223, v223
	v_pk_add_f32 v[216:217], v[216:217], v[200:201] op_sel:[0,1] op_sel_hi:[1,1]
	v_pk_add_f32 v[218:219], v[218:219], v[200:201] op_sel:[0,1] op_sel_hi:[1,1]
	v_pk_add_f32 v[220:221], v[220:221], v[200:201] op_sel:[0,1] op_sel_hi:[1,1]
	v_pk_add_f32 v[222:223], v[222:223], v[200:201] op_sel:[0,1] op_sel_hi:[1,1]
	v_rcp_f32_e32 v216, v216
	v_rcp_f32_e32 v217, v217
	v_rcp_f32_e32 v218, v218
	v_rcp_f32_e32 v219, v219
	v_rcp_f32_e32 v220, v220
	v_rcp_f32_e32 v221, v221
	v_rcp_f32_e32 v222, v222
	v_rcp_f32_e32 v223, v223
	v_cvt_pk_bf16_f32 v224, v216, v217
	v_cvt_pk_bf16_f32 v225, v218, v219
	v_cvt_pk_bf16_f32 v226, v220, v221
	v_cvt_pk_bf16_f32 v227, v222, v223
	v_lshl_add_u32 v164, v198, 3, s69
	s_cselect_b32 s25, s46, s25
	v_mov_b32_e32 v166, s0
	s_movk_i32 s0, 0xc00
	v_mov_b32_e32 v167, s25
	s_cselect_b32 s0, s0, 0x800
	v_ashrrev_i32_e32 v165, 31, v164
	v_lshl_add_u32 v198, s36, 8, v199
	v_lshl_add_u64 v[164:165], v[164:165], 1, v[166:167]
	v_mad_i64_i32 v[166:167], s[36:37], s0, v198, 0
	v_lshl_add_u64 v[166:167], v[166:167], 1, v[164:165]
	s_cmp_gt_i32 s23, 1
	s_mov_b64 s[36:37], -1
	global_store_dwordx4 v[166:167], v[224:227], off
	s_mov_b64 s[36:37], 0
	s_andn2_b64 vcc, exec, s[36:37]
	v_pk_fma_f32 v[204:205], v[40:41], v[172:173], v[56:57] op_sel:[0,1,0]
	v_pk_fma_f32 v[206:207], v[42:43], v[172:173], v[58:59] op_sel:[0,1,0]
	v_pk_fma_f32 v[208:209], v[32:33], v[172:173], v[44:45] op_sel:[0,1,0]
	v_pk_fma_f32 v[210:211], v[34:35], v[172:173], v[46:47] op_sel:[0,1,0]
	v_pk_fma_f32 v[204:205], v[160:161], v[172:173], v[204:205] op_sel_hi:[1,0,1]
	v_pk_fma_f32 v[206:207], v[162:163], v[172:173], v[206:207] op_sel_hi:[1,0,1]
	v_pk_fma_f32 v[208:209], v[156:157], v[172:173], v[208:209] op_sel_hi:[1,0,1]
	v_pk_fma_f32 v[210:211], v[158:159], v[172:173], v[210:211] op_sel_hi:[1,0,1]
	v_pk_mul_f32 v[216:217], v[204:205], v[200:201] op_sel_hi:[1,0]
	v_pk_mul_f32 v[218:219], v[206:207], v[200:201] op_sel_hi:[1,0]
	v_pk_mul_f32 v[220:221], v[208:209], v[200:201] op_sel_hi:[1,0]
	v_pk_mul_f32 v[222:223], v[210:211], v[200:201] op_sel_hi:[1,0]
	v_exp_f32_e32 v216, v216
	v_exp_f32_e32 v217, v217
	v_exp_f32_e32 v218, v218
	v_exp_f32_e32 v219, v219
	v_exp_f32_e32 v220, v220
	v_exp_f32_e32 v221, v221
	v_exp_f32_e32 v222, v222
	v_exp_f32_e32 v223, v223
	v_pk_add_f32 v[216:217], v[216:217], v[200:201] op_sel:[0,1] op_sel_hi:[1,1]
	v_pk_add_f32 v[218:219], v[218:219], v[200:201] op_sel:[0,1] op_sel_hi:[1,1]
	v_pk_add_f32 v[220:221], v[220:221], v[200:201] op_sel:[0,1] op_sel_hi:[1,1]
	v_pk_add_f32 v[222:223], v[222:223], v[200:201] op_sel:[0,1] op_sel_hi:[1,1]
	v_rcp_f32_e32 v216, v216
	v_rcp_f32_e32 v217, v217
	v_rcp_f32_e32 v218, v218
	v_rcp_f32_e32 v219, v219
	v_rcp_f32_e32 v220, v220
	v_rcp_f32_e32 v221, v221
	v_rcp_f32_e32 v222, v222
	v_rcp_f32_e32 v223, v223
	v_cvt_pk_bf16_f32 v228, v216, v217
	v_cvt_pk_bf16_f32 v229, v218, v219
	v_cvt_pk_bf16_f32 v230, v220, v221
	v_cvt_pk_bf16_f32 v231, v222, v223
	global_store_dwordx4 v[166:167], v[228:231], off offset:256
	s_cmp_gt_i32 s23, 1
	s_mov_b64 s[36:37], -1
	s_mov_b64 s[36:37], 0
	s_andn2_b64 vcc, exec, s[36:37]
	v_pk_fma_f32 v[204:205], v[68:69], v[174:175], v[72:73] op_sel:[0,1,0]
	v_pk_fma_f32 v[206:207], v[70:71], v[174:175], v[74:75] op_sel:[0,1,0]
	v_pk_fma_f32 v[208:209], v[60:61], v[174:175], v[64:65] op_sel:[0,1,0]
	v_pk_fma_f32 v[210:211], v[62:63], v[174:175], v[66:67] op_sel:[0,1,0]
	v_pk_fma_f32 v[204:205], v[152:153], v[174:175], v[204:205] op_sel_hi:[1,0,1]
	v_pk_fma_f32 v[206:207], v[154:155], v[174:175], v[206:207] op_sel_hi:[1,0,1]
	v_pk_fma_f32 v[208:209], v[148:149], v[174:175], v[208:209] op_sel_hi:[1,0,1]
	v_pk_fma_f32 v[210:211], v[150:151], v[174:175], v[210:211] op_sel_hi:[1,0,1]
	v_pk_mul_f32 v[216:217], v[204:205], v[200:201] op_sel_hi:[1,0]
	v_pk_mul_f32 v[218:219], v[206:207], v[200:201] op_sel_hi:[1,0]
	v_pk_mul_f32 v[220:221], v[208:209], v[200:201] op_sel_hi:[1,0]
	v_pk_mul_f32 v[222:223], v[210:211], v[200:201] op_sel_hi:[1,0]
	v_exp_f32_e32 v216, v216
	v_exp_f32_e32 v217, v217
	v_exp_f32_e32 v218, v218
	v_exp_f32_e32 v219, v219
	v_exp_f32_e32 v220, v220
	v_exp_f32_e32 v221, v221
	v_exp_f32_e32 v222, v222
	v_exp_f32_e32 v223, v223
	v_pk_add_f32 v[216:217], v[216:217], v[200:201] op_sel:[0,1] op_sel_hi:[1,1]
	v_pk_add_f32 v[218:219], v[218:219], v[200:201] op_sel:[0,1] op_sel_hi:[1,1]
	v_pk_add_f32 v[220:221], v[220:221], v[200:201] op_sel:[0,1] op_sel_hi:[1,1]
	v_pk_add_f32 v[222:223], v[222:223], v[200:201] op_sel:[0,1] op_sel_hi:[1,1]
	v_rcp_f32_e32 v216, v216
	v_rcp_f32_e32 v217, v217
	v_rcp_f32_e32 v218, v218
	v_rcp_f32_e32 v219, v219
	v_rcp_f32_e32 v220, v220
	v_rcp_f32_e32 v221, v221
	v_rcp_f32_e32 v222, v222
	v_rcp_f32_e32 v223, v223
	v_cvt_pk_bf16_f32 v232, v216, v217
	v_cvt_pk_bf16_f32 v233, v218, v219
	v_cvt_pk_bf16_f32 v234, v220, v221
	v_cvt_pk_bf16_f32 v235, v222, v223
	v_add_u32_e32 v148, 16, v198
	v_mad_i64_i32 v[148:149], s[36:37], s0, v148, 0
	v_lshl_add_u64 v[148:149], v[148:149], 1, v[164:165]
	global_store_dwordx4 v[148:149], v[232:235], off
	s_cmp_gt_i32 s23, 1
	s_mov_b64 s[36:37], -1
	s_mov_b64 s[36:37], 0
	s_andn2_b64 vcc, exec, s[36:37]
	v_pk_fma_f32 v[204:205], v[40:41], v[174:175], v[56:57] op_sel:[0,1,0]
	v_pk_fma_f32 v[206:207], v[42:43], v[174:175], v[58:59] op_sel:[0,1,0]
	v_pk_fma_f32 v[208:209], v[32:33], v[174:175], v[44:45] op_sel:[0,1,0]
	v_pk_fma_f32 v[210:211], v[34:35], v[174:175], v[46:47] op_sel:[0,1,0]
	v_pk_fma_f32 v[204:205], v[144:145], v[174:175], v[204:205] op_sel_hi:[1,0,1]
	v_pk_fma_f32 v[206:207], v[146:147], v[174:175], v[206:207] op_sel_hi:[1,0,1]
	v_pk_fma_f32 v[208:209], v[140:141], v[174:175], v[208:209] op_sel_hi:[1,0,1]
	v_pk_fma_f32 v[210:211], v[142:143], v[174:175], v[210:211] op_sel_hi:[1,0,1]
	v_pk_mul_f32 v[216:217], v[204:205], v[200:201] op_sel_hi:[1,0]
	v_pk_mul_f32 v[218:219], v[206:207], v[200:201] op_sel_hi:[1,0]
	v_pk_mul_f32 v[220:221], v[208:209], v[200:201] op_sel_hi:[1,0]
	v_pk_mul_f32 v[222:223], v[210:211], v[200:201] op_sel_hi:[1,0]
	v_exp_f32_e32 v216, v216
	v_exp_f32_e32 v217, v217
	v_exp_f32_e32 v218, v218
	v_exp_f32_e32 v219, v219
	v_exp_f32_e32 v220, v220
	v_exp_f32_e32 v221, v221
	v_exp_f32_e32 v222, v222
	v_exp_f32_e32 v223, v223
	v_pk_add_f32 v[216:217], v[216:217], v[200:201] op_sel:[0,1] op_sel_hi:[1,1]
	v_pk_add_f32 v[218:219], v[218:219], v[200:201] op_sel:[0,1] op_sel_hi:[1,1]
	v_pk_add_f32 v[220:221], v[220:221], v[200:201] op_sel:[0,1] op_sel_hi:[1,1]
	v_pk_add_f32 v[222:223], v[222:223], v[200:201] op_sel:[0,1] op_sel_hi:[1,1]
	v_rcp_f32_e32 v216, v216
	v_rcp_f32_e32 v217, v217
	v_rcp_f32_e32 v218, v218
	v_rcp_f32_e32 v219, v219
	v_rcp_f32_e32 v220, v220
	v_rcp_f32_e32 v221, v221
	v_rcp_f32_e32 v222, v222
	v_rcp_f32_e32 v223, v223
	v_cvt_pk_bf16_f32 v236, v216, v217
	v_cvt_pk_bf16_f32 v237, v218, v219
	v_cvt_pk_bf16_f32 v238, v220, v221
	v_cvt_pk_bf16_f32 v239, v222, v223
	global_store_dwordx4 v[148:149], v[236:239], off offset:256
	s_cmp_gt_i32 s23, 1
	s_mov_b64 s[36:37], -1
	s_mov_b64 s[36:37], 0
	s_andn2_b64 vcc, exec, s[36:37]
	v_pk_fma_f32 v[204:205], v[68:69], v[136:137], v[72:73] op_sel:[0,1,0]
	v_pk_fma_f32 v[206:207], v[70:71], v[136:137], v[74:75] op_sel:[0,1,0]
	v_pk_fma_f32 v[208:209], v[60:61], v[136:137], v[64:65] op_sel:[0,1,0]
	v_pk_fma_f32 v[210:211], v[62:63], v[136:137], v[66:67] op_sel:[0,1,0]
	v_pk_fma_f32 v[204:205], v[132:133], v[136:137], v[204:205] op_sel_hi:[1,0,1]
	v_pk_fma_f32 v[206:207], v[134:135], v[136:137], v[206:207] op_sel_hi:[1,0,1]
	v_pk_fma_f32 v[208:209], v[128:129], v[136:137], v[208:209] op_sel_hi:[1,0,1]
	v_pk_fma_f32 v[210:211], v[130:131], v[136:137], v[210:211] op_sel_hi:[1,0,1]
	v_pk_mul_f32 v[216:217], v[204:205], v[200:201] op_sel_hi:[1,0]
	v_pk_mul_f32 v[218:219], v[206:207], v[200:201] op_sel_hi:[1,0]
	v_pk_mul_f32 v[220:221], v[208:209], v[200:201] op_sel_hi:[1,0]
	v_pk_mul_f32 v[222:223], v[210:211], v[200:201] op_sel_hi:[1,0]
	v_exp_f32_e32 v216, v216
	v_exp_f32_e32 v217, v217
	v_exp_f32_e32 v218, v218
	v_exp_f32_e32 v219, v219
	v_exp_f32_e32 v220, v220
	v_exp_f32_e32 v221, v221
	v_exp_f32_e32 v222, v222
	v_exp_f32_e32 v223, v223
	v_pk_add_f32 v[216:217], v[216:217], v[200:201] op_sel:[0,1] op_sel_hi:[1,1]
	v_pk_add_f32 v[218:219], v[218:219], v[200:201] op_sel:[0,1] op_sel_hi:[1,1]
	v_pk_add_f32 v[220:221], v[220:221], v[200:201] op_sel:[0,1] op_sel_hi:[1,1]
	v_pk_add_f32 v[222:223], v[222:223], v[200:201] op_sel:[0,1] op_sel_hi:[1,1]
	v_rcp_f32_e32 v216, v216
	v_rcp_f32_e32 v217, v217
	v_rcp_f32_e32 v218, v218
	v_rcp_f32_e32 v219, v219
	v_rcp_f32_e32 v220, v220
	v_rcp_f32_e32 v221, v221
	v_rcp_f32_e32 v222, v222
	v_rcp_f32_e32 v223, v223
	v_cvt_pk_bf16_f32 v240, v216, v217
	v_cvt_pk_bf16_f32 v241, v218, v219
	v_cvt_pk_bf16_f32 v242, v220, v221
	v_cvt_pk_bf16_f32 v243, v222, v223
	v_add_u32_e32 v128, 32, v198
	v_mad_i64_i32 v[128:129], s[36:37], s0, v128, 0
	v_lshl_add_u64 v[128:129], v[128:129], 1, v[164:165]
	s_cmp_gt_i32 s23, 1
	s_mov_b64 s[36:37], -1
	global_store_dwordx4 v[128:129], v[240:243], off
	s_mov_b64 s[36:37], 0
	s_andn2_b64 vcc, exec, s[36:37]
	v_pk_fma_f32 v[204:205], v[40:41], v[136:137], v[56:57] op_sel:[0,1,0]
	v_pk_fma_f32 v[206:207], v[42:43], v[136:137], v[58:59] op_sel:[0,1,0]
	v_pk_fma_f32 v[208:209], v[32:33], v[136:137], v[44:45] op_sel:[0,1,0]
	v_pk_fma_f32 v[210:211], v[34:35], v[136:137], v[46:47] op_sel:[0,1,0]
	v_pk_fma_f32 v[204:205], v[124:125], v[136:137], v[204:205] op_sel_hi:[1,0,1]
	v_pk_fma_f32 v[206:207], v[126:127], v[136:137], v[206:207] op_sel_hi:[1,0,1]
	v_pk_fma_f32 v[208:209], v[120:121], v[136:137], v[208:209] op_sel_hi:[1,0,1]
	v_pk_fma_f32 v[210:211], v[122:123], v[136:137], v[210:211] op_sel_hi:[1,0,1]
	v_pk_mul_f32 v[216:217], v[204:205], v[200:201] op_sel_hi:[1,0]
	v_pk_mul_f32 v[218:219], v[206:207], v[200:201] op_sel_hi:[1,0]
	v_pk_mul_f32 v[220:221], v[208:209], v[200:201] op_sel_hi:[1,0]
	v_pk_mul_f32 v[222:223], v[210:211], v[200:201] op_sel_hi:[1,0]
	v_exp_f32_e32 v216, v216
	v_exp_f32_e32 v217, v217
	v_exp_f32_e32 v218, v218
	v_exp_f32_e32 v219, v219
	v_exp_f32_e32 v220, v220
	v_exp_f32_e32 v221, v221
	v_exp_f32_e32 v222, v222
	v_exp_f32_e32 v223, v223
	v_pk_add_f32 v[216:217], v[216:217], v[200:201] op_sel:[0,1] op_sel_hi:[1,1]
	v_pk_add_f32 v[218:219], v[218:219], v[200:201] op_sel:[0,1] op_sel_hi:[1,1]
	v_pk_add_f32 v[220:221], v[220:221], v[200:201] op_sel:[0,1] op_sel_hi:[1,1]
	v_pk_add_f32 v[222:223], v[222:223], v[200:201] op_sel:[0,1] op_sel_hi:[1,1]
	v_rcp_f32_e32 v216, v216
	v_rcp_f32_e32 v217, v217
	v_rcp_f32_e32 v218, v218
	v_rcp_f32_e32 v219, v219
	v_rcp_f32_e32 v220, v220
	v_rcp_f32_e32 v221, v221
	v_rcp_f32_e32 v222, v222
	v_rcp_f32_e32 v223, v223
	v_cvt_pk_bf16_f32 v244, v216, v217
	v_cvt_pk_bf16_f32 v245, v218, v219
	v_cvt_pk_bf16_f32 v246, v220, v221
	v_cvt_pk_bf16_f32 v247, v222, v223
	global_store_dwordx4 v[128:129], v[244:247], off offset:256
	s_cmp_gt_i32 s23, 1
	s_mov_b64 s[36:37], -1
	s_mov_b64 s[36:37], 0
	s_andn2_b64 vcc, exec, s[36:37]
	v_pk_fma_f32 v[204:205], v[68:69], v[138:139], v[72:73] op_sel:[0,1,0]
	v_pk_fma_f32 v[206:207], v[70:71], v[138:139], v[74:75] op_sel:[0,1,0]
	v_pk_fma_f32 v[208:209], v[60:61], v[138:139], v[64:65] op_sel:[0,1,0]
	v_pk_fma_f32 v[210:211], v[62:63], v[138:139], v[66:67] op_sel:[0,1,0]
	v_pk_fma_f32 v[204:205], v[116:117], v[138:139], v[204:205] op_sel_hi:[1,0,1]
	v_pk_fma_f32 v[206:207], v[118:119], v[138:139], v[206:207] op_sel_hi:[1,0,1]
	v_pk_fma_f32 v[208:209], v[112:113], v[138:139], v[208:209] op_sel_hi:[1,0,1]
	v_pk_fma_f32 v[210:211], v[114:115], v[138:139], v[210:211] op_sel_hi:[1,0,1]
	v_pk_mul_f32 v[216:217], v[204:205], v[200:201] op_sel_hi:[1,0]
	v_pk_mul_f32 v[218:219], v[206:207], v[200:201] op_sel_hi:[1,0]
	v_pk_mul_f32 v[220:221], v[208:209], v[200:201] op_sel_hi:[1,0]
	v_pk_mul_f32 v[222:223], v[210:211], v[200:201] op_sel_hi:[1,0]
	v_exp_f32_e32 v216, v216
	v_exp_f32_e32 v217, v217
	v_exp_f32_e32 v218, v218
	v_exp_f32_e32 v219, v219
	v_exp_f32_e32 v220, v220
	v_exp_f32_e32 v221, v221
	v_exp_f32_e32 v222, v222
	v_exp_f32_e32 v223, v223
	v_pk_add_f32 v[216:217], v[216:217], v[200:201] op_sel:[0,1] op_sel_hi:[1,1]
	v_pk_add_f32 v[218:219], v[218:219], v[200:201] op_sel:[0,1] op_sel_hi:[1,1]
	v_pk_add_f32 v[220:221], v[220:221], v[200:201] op_sel:[0,1] op_sel_hi:[1,1]
	v_pk_add_f32 v[222:223], v[222:223], v[200:201] op_sel:[0,1] op_sel_hi:[1,1]
	v_rcp_f32_e32 v216, v216
	v_rcp_f32_e32 v217, v217
	v_rcp_f32_e32 v218, v218
	v_rcp_f32_e32 v219, v219
	v_rcp_f32_e32 v220, v220
	v_rcp_f32_e32 v221, v221
	v_rcp_f32_e32 v222, v222
	v_rcp_f32_e32 v223, v223
	v_cvt_pk_bf16_f32 v248, v216, v217
	v_cvt_pk_bf16_f32 v249, v218, v219
	v_cvt_pk_bf16_f32 v250, v220, v221
	v_cvt_pk_bf16_f32 v251, v222, v223
	v_add_u32_e32 v112, 48, v198
	v_mad_i64_i32 v[112:113], s[36:37], s0, v112, 0
	v_lshl_add_u64 v[112:113], v[112:113], 1, v[164:165]
	global_store_dwordx4 v[112:113], v[248:251], off
	s_cmp_gt_i32 s23, 1
	s_mov_b64 s[36:37], -1
	s_mov_b64 s[36:37], 0
	s_andn2_b64 vcc, exec, s[36:37]
	v_pk_fma_f32 v[204:205], v[40:41], v[138:139], v[56:57] op_sel:[0,1,0]
	v_pk_fma_f32 v[206:207], v[42:43], v[138:139], v[58:59] op_sel:[0,1,0]
	v_pk_fma_f32 v[208:209], v[32:33], v[138:139], v[44:45] op_sel:[0,1,0]
	v_pk_fma_f32 v[210:211], v[34:35], v[138:139], v[46:47] op_sel:[0,1,0]
	v_pk_fma_f32 v[204:205], v[108:109], v[138:139], v[204:205] op_sel_hi:[1,0,1]
	v_pk_fma_f32 v[206:207], v[110:111], v[138:139], v[206:207] op_sel_hi:[1,0,1]
	v_pk_fma_f32 v[208:209], v[104:105], v[138:139], v[208:209] op_sel_hi:[1,0,1]
	v_pk_fma_f32 v[210:211], v[106:107], v[138:139], v[210:211] op_sel_hi:[1,0,1]
	v_pk_mul_f32 v[216:217], v[204:205], v[200:201] op_sel_hi:[1,0]
	v_pk_mul_f32 v[218:219], v[206:207], v[200:201] op_sel_hi:[1,0]
	v_pk_mul_f32 v[220:221], v[208:209], v[200:201] op_sel_hi:[1,0]
	v_pk_mul_f32 v[222:223], v[210:211], v[200:201] op_sel_hi:[1,0]
	v_exp_f32_e32 v216, v216
	v_exp_f32_e32 v217, v217
	v_exp_f32_e32 v218, v218
	v_exp_f32_e32 v219, v219
	v_exp_f32_e32 v220, v220
	v_exp_f32_e32 v221, v221
	v_exp_f32_e32 v222, v222
	v_exp_f32_e32 v223, v223
	v_pk_add_f32 v[216:217], v[216:217], v[200:201] op_sel:[0,1] op_sel_hi:[1,1]
	v_pk_add_f32 v[218:219], v[218:219], v[200:201] op_sel:[0,1] op_sel_hi:[1,1]
	v_pk_add_f32 v[220:221], v[220:221], v[200:201] op_sel:[0,1] op_sel_hi:[1,1]
	v_pk_add_f32 v[222:223], v[222:223], v[200:201] op_sel:[0,1] op_sel_hi:[1,1]
	v_rcp_f32_e32 v216, v216
	v_rcp_f32_e32 v217, v217
	v_rcp_f32_e32 v218, v218
	v_rcp_f32_e32 v219, v219
	v_rcp_f32_e32 v220, v220
	v_rcp_f32_e32 v221, v221
	v_rcp_f32_e32 v222, v222
	v_rcp_f32_e32 v223, v223
	v_cvt_pk_bf16_f32 v224, v216, v217
	v_cvt_pk_bf16_f32 v225, v218, v219
	v_cvt_pk_bf16_f32 v226, v220, v221
	v_cvt_pk_bf16_f32 v227, v222, v223
	global_store_dwordx4 v[112:113], v[224:227], off offset:256
	s_cmp_gt_i32 s23, 1
	s_mov_b64 s[36:37], -1
	s_mov_b64 s[36:37], 0
	s_andn2_b64 vcc, exec, s[36:37]
	v_pk_fma_f32 v[204:205], v[68:69], v[100:101], v[72:73] op_sel:[0,1,0]
	v_pk_fma_f32 v[206:207], v[70:71], v[100:101], v[74:75] op_sel:[0,1,0]
	v_pk_fma_f32 v[208:209], v[60:61], v[100:101], v[64:65] op_sel:[0,1,0]
	v_pk_fma_f32 v[210:211], v[62:63], v[100:101], v[66:67] op_sel:[0,1,0]
	v_pk_fma_f32 v[204:205], v[96:97], v[100:101], v[204:205] op_sel_hi:[1,0,1]
	v_pk_fma_f32 v[206:207], v[98:99], v[100:101], v[206:207] op_sel_hi:[1,0,1]
	v_pk_fma_f32 v[208:209], v[92:93], v[100:101], v[208:209] op_sel_hi:[1,0,1]
	v_pk_fma_f32 v[210:211], v[94:95], v[100:101], v[210:211] op_sel_hi:[1,0,1]
	v_pk_mul_f32 v[216:217], v[204:205], v[200:201] op_sel_hi:[1,0]
	v_pk_mul_f32 v[218:219], v[206:207], v[200:201] op_sel_hi:[1,0]
	v_pk_mul_f32 v[220:221], v[208:209], v[200:201] op_sel_hi:[1,0]
	v_pk_mul_f32 v[222:223], v[210:211], v[200:201] op_sel_hi:[1,0]
	v_exp_f32_e32 v216, v216
	v_exp_f32_e32 v217, v217
	v_exp_f32_e32 v218, v218
	v_exp_f32_e32 v219, v219
	v_exp_f32_e32 v220, v220
	v_exp_f32_e32 v221, v221
	v_exp_f32_e32 v222, v222
	v_exp_f32_e32 v223, v223
	v_pk_add_f32 v[216:217], v[216:217], v[200:201] op_sel:[0,1] op_sel_hi:[1,1]
	v_pk_add_f32 v[218:219], v[218:219], v[200:201] op_sel:[0,1] op_sel_hi:[1,1]
	v_pk_add_f32 v[220:221], v[220:221], v[200:201] op_sel:[0,1] op_sel_hi:[1,1]
	v_pk_add_f32 v[222:223], v[222:223], v[200:201] op_sel:[0,1] op_sel_hi:[1,1]
	v_rcp_f32_e32 v216, v216
	v_rcp_f32_e32 v217, v217
	v_rcp_f32_e32 v218, v218
	v_rcp_f32_e32 v219, v219
	v_rcp_f32_e32 v220, v220
	v_rcp_f32_e32 v221, v221
	v_rcp_f32_e32 v222, v222
	v_rcp_f32_e32 v223, v223
	v_cvt_pk_bf16_f32 v228, v216, v217
	v_cvt_pk_bf16_f32 v229, v218, v219
	v_cvt_pk_bf16_f32 v230, v220, v221
	v_cvt_pk_bf16_f32 v231, v222, v223
	v_add_u32_e32 v92, 0x80, v198
	v_mad_i64_i32 v[92:93], s[36:37], s0, v92, 0
	v_lshl_add_u64 v[92:93], v[92:93], 1, v[164:165]
	s_cmp_gt_i32 s23, 1
	s_mov_b64 s[36:37], -1
	global_store_dwordx4 v[92:93], v[228:231], off
	s_mov_b64 s[36:37], 0
	s_andn2_b64 vcc, exec, s[36:37]
	v_pk_fma_f32 v[204:205], v[40:41], v[100:101], v[56:57] op_sel:[0,1,0]
	v_pk_fma_f32 v[206:207], v[42:43], v[100:101], v[58:59] op_sel:[0,1,0]
	v_pk_fma_f32 v[208:209], v[32:33], v[100:101], v[44:45] op_sel:[0,1,0]
	v_pk_fma_f32 v[210:211], v[34:35], v[100:101], v[46:47] op_sel:[0,1,0]
	v_pk_fma_f32 v[204:205], v[88:89], v[100:101], v[204:205] op_sel_hi:[1,0,1]
	v_pk_fma_f32 v[206:207], v[90:91], v[100:101], v[206:207] op_sel_hi:[1,0,1]
	v_pk_fma_f32 v[208:209], v[84:85], v[100:101], v[208:209] op_sel_hi:[1,0,1]
	v_pk_fma_f32 v[210:211], v[86:87], v[100:101], v[210:211] op_sel_hi:[1,0,1]
	v_pk_mul_f32 v[216:217], v[204:205], v[200:201] op_sel_hi:[1,0]
	v_pk_mul_f32 v[218:219], v[206:207], v[200:201] op_sel_hi:[1,0]
	v_pk_mul_f32 v[220:221], v[208:209], v[200:201] op_sel_hi:[1,0]
	v_pk_mul_f32 v[222:223], v[210:211], v[200:201] op_sel_hi:[1,0]
	v_exp_f32_e32 v216, v216
	v_exp_f32_e32 v217, v217
	v_exp_f32_e32 v218, v218
	v_exp_f32_e32 v219, v219
	v_exp_f32_e32 v220, v220
	v_exp_f32_e32 v221, v221
	v_exp_f32_e32 v222, v222
	v_exp_f32_e32 v223, v223
	v_pk_add_f32 v[216:217], v[216:217], v[200:201] op_sel:[0,1] op_sel_hi:[1,1]
	v_pk_add_f32 v[218:219], v[218:219], v[200:201] op_sel:[0,1] op_sel_hi:[1,1]
	v_pk_add_f32 v[220:221], v[220:221], v[200:201] op_sel:[0,1] op_sel_hi:[1,1]
	v_pk_add_f32 v[222:223], v[222:223], v[200:201] op_sel:[0,1] op_sel_hi:[1,1]
	v_rcp_f32_e32 v216, v216
	v_rcp_f32_e32 v217, v217
	v_rcp_f32_e32 v218, v218
	v_rcp_f32_e32 v219, v219
	v_rcp_f32_e32 v220, v220
	v_rcp_f32_e32 v221, v221
	v_rcp_f32_e32 v222, v222
	v_rcp_f32_e32 v223, v223
	v_cvt_pk_bf16_f32 v232, v216, v217
	v_cvt_pk_bf16_f32 v233, v218, v219
	v_cvt_pk_bf16_f32 v234, v220, v221
	v_cvt_pk_bf16_f32 v235, v222, v223
	global_store_dwordx4 v[92:93], v[232:235], off offset:256
	s_cmp_gt_i32 s23, 1
	s_mov_b64 s[36:37], -1
	s_mov_b64 s[36:37], 0
	s_andn2_b64 vcc, exec, s[36:37]
	v_pk_fma_f32 v[204:205], v[68:69], v[102:103], v[72:73] op_sel:[0,1,0]
	v_pk_fma_f32 v[206:207], v[70:71], v[102:103], v[74:75] op_sel:[0,1,0]
	v_pk_fma_f32 v[208:209], v[60:61], v[102:103], v[64:65] op_sel:[0,1,0]
	v_pk_fma_f32 v[210:211], v[62:63], v[102:103], v[66:67] op_sel:[0,1,0]
	v_pk_fma_f32 v[204:205], v[80:81], v[102:103], v[204:205] op_sel_hi:[1,0,1]
	v_pk_fma_f32 v[206:207], v[82:83], v[102:103], v[206:207] op_sel_hi:[1,0,1]
	v_pk_fma_f32 v[208:209], v[76:77], v[102:103], v[208:209] op_sel_hi:[1,0,1]
	v_pk_fma_f32 v[210:211], v[78:79], v[102:103], v[210:211] op_sel_hi:[1,0,1]
	v_pk_mul_f32 v[216:217], v[204:205], v[200:201] op_sel_hi:[1,0]
	v_pk_mul_f32 v[218:219], v[206:207], v[200:201] op_sel_hi:[1,0]
	v_pk_mul_f32 v[220:221], v[208:209], v[200:201] op_sel_hi:[1,0]
	v_pk_mul_f32 v[222:223], v[210:211], v[200:201] op_sel_hi:[1,0]
	v_exp_f32_e32 v216, v216
	v_exp_f32_e32 v217, v217
	v_exp_f32_e32 v218, v218
	v_exp_f32_e32 v219, v219
	v_exp_f32_e32 v220, v220
	v_exp_f32_e32 v221, v221
	v_exp_f32_e32 v222, v222
	v_exp_f32_e32 v223, v223
	v_pk_add_f32 v[216:217], v[216:217], v[200:201] op_sel:[0,1] op_sel_hi:[1,1]
	v_pk_add_f32 v[218:219], v[218:219], v[200:201] op_sel:[0,1] op_sel_hi:[1,1]
	v_pk_add_f32 v[220:221], v[220:221], v[200:201] op_sel:[0,1] op_sel_hi:[1,1]
	v_pk_add_f32 v[222:223], v[222:223], v[200:201] op_sel:[0,1] op_sel_hi:[1,1]
	v_rcp_f32_e32 v216, v216
	v_rcp_f32_e32 v217, v217
	v_rcp_f32_e32 v218, v218
	v_rcp_f32_e32 v219, v219
	v_rcp_f32_e32 v220, v220
	v_rcp_f32_e32 v221, v221
	v_rcp_f32_e32 v222, v222
	v_rcp_f32_e32 v223, v223
	v_cvt_pk_bf16_f32 v236, v216, v217
	v_cvt_pk_bf16_f32 v237, v218, v219
	v_cvt_pk_bf16_f32 v238, v220, v221
	v_cvt_pk_bf16_f32 v239, v222, v223
	v_add_u32_e32 v76, 0x90, v198
	v_mad_i64_i32 v[76:77], s[36:37], s0, v76, 0
	v_lshl_add_u64 v[76:77], v[76:77], 1, v[164:165]
	global_store_dwordx4 v[76:77], v[236:239], off
	s_cmp_gt_i32 s23, 1
	s_mov_b64 s[36:37], -1
	s_mov_b64 s[36:37], 0
	s_andn2_b64 vcc, exec, s[36:37]
	v_pk_fma_f32 v[204:205], v[40:41], v[102:103], v[56:57] op_sel:[0,1,0]
	v_pk_fma_f32 v[206:207], v[42:43], v[102:103], v[58:59] op_sel:[0,1,0]
	v_pk_fma_f32 v[208:209], v[32:33], v[102:103], v[44:45] op_sel:[0,1,0]
	v_pk_fma_f32 v[210:211], v[34:35], v[102:103], v[46:47] op_sel:[0,1,0]
	v_pk_fma_f32 v[204:205], v[52:53], v[102:103], v[204:205] op_sel_hi:[1,0,1]
	v_pk_fma_f32 v[206:207], v[54:55], v[102:103], v[206:207] op_sel_hi:[1,0,1]
	v_pk_fma_f32 v[208:209], v[36:37], v[102:103], v[208:209] op_sel_hi:[1,0,1]
	v_pk_fma_f32 v[210:211], v[38:39], v[102:103], v[210:211] op_sel_hi:[1,0,1]
	v_pk_mul_f32 v[216:217], v[204:205], v[200:201] op_sel_hi:[1,0]
	v_pk_mul_f32 v[218:219], v[206:207], v[200:201] op_sel_hi:[1,0]
	v_pk_mul_f32 v[220:221], v[208:209], v[200:201] op_sel_hi:[1,0]
	v_pk_mul_f32 v[222:223], v[210:211], v[200:201] op_sel_hi:[1,0]
	v_exp_f32_e32 v216, v216
	v_exp_f32_e32 v217, v217
	v_exp_f32_e32 v218, v218
	v_exp_f32_e32 v219, v219
	v_exp_f32_e32 v220, v220
	v_exp_f32_e32 v221, v221
	v_exp_f32_e32 v222, v222
	v_exp_f32_e32 v223, v223
	v_pk_add_f32 v[216:217], v[216:217], v[200:201] op_sel:[0,1] op_sel_hi:[1,1]
	v_pk_add_f32 v[218:219], v[218:219], v[200:201] op_sel:[0,1] op_sel_hi:[1,1]
	v_pk_add_f32 v[220:221], v[220:221], v[200:201] op_sel:[0,1] op_sel_hi:[1,1]
	v_pk_add_f32 v[222:223], v[222:223], v[200:201] op_sel:[0,1] op_sel_hi:[1,1]
	v_rcp_f32_e32 v216, v216
	v_rcp_f32_e32 v217, v217
	v_rcp_f32_e32 v218, v218
	v_rcp_f32_e32 v219, v219
	v_rcp_f32_e32 v220, v220
	v_rcp_f32_e32 v221, v221
	v_rcp_f32_e32 v222, v222
	v_rcp_f32_e32 v223, v223
	v_cvt_pk_bf16_f32 v240, v216, v217
	v_cvt_pk_bf16_f32 v241, v218, v219
	v_cvt_pk_bf16_f32 v242, v220, v221
	v_cvt_pk_bf16_f32 v243, v222, v223
	global_store_dwordx4 v[76:77], v[240:243], off offset:256
	s_cmp_gt_i32 s23, 1
	s_mov_b64 s[36:37], -1
	s_mov_b64 s[36:37], 0
	s_andn2_b64 vcc, exec, s[36:37]
	v_pk_fma_f32 v[204:205], v[68:69], v[48:49], v[72:73] op_sel:[0,1,0]
	v_pk_fma_f32 v[206:207], v[70:71], v[48:49], v[74:75] op_sel:[0,1,0]
	v_pk_fma_f32 v[208:209], v[60:61], v[48:49], v[64:65] op_sel:[0,1,0]
	v_pk_fma_f32 v[210:211], v[62:63], v[48:49], v[66:67] op_sel:[0,1,0]
	v_pk_fma_f32 v[204:205], v[28:29], v[48:49], v[204:205] op_sel_hi:[1,0,1]
	v_pk_fma_f32 v[206:207], v[30:31], v[48:49], v[206:207] op_sel_hi:[1,0,1]
	v_pk_fma_f32 v[208:209], v[24:25], v[48:49], v[208:209] op_sel_hi:[1,0,1]
	v_pk_fma_f32 v[210:211], v[26:27], v[48:49], v[210:211] op_sel_hi:[1,0,1]
	v_pk_mul_f32 v[216:217], v[204:205], v[200:201] op_sel_hi:[1,0]
	v_pk_mul_f32 v[218:219], v[206:207], v[200:201] op_sel_hi:[1,0]
	v_pk_mul_f32 v[220:221], v[208:209], v[200:201] op_sel_hi:[1,0]
	v_pk_mul_f32 v[222:223], v[210:211], v[200:201] op_sel_hi:[1,0]
	v_exp_f32_e32 v216, v216
	v_exp_f32_e32 v217, v217
	v_exp_f32_e32 v218, v218
	v_exp_f32_e32 v219, v219
	v_exp_f32_e32 v220, v220
	v_exp_f32_e32 v221, v221
	v_exp_f32_e32 v222, v222
	v_exp_f32_e32 v223, v223
	v_pk_add_f32 v[216:217], v[216:217], v[200:201] op_sel:[0,1] op_sel_hi:[1,1]
	v_pk_add_f32 v[218:219], v[218:219], v[200:201] op_sel:[0,1] op_sel_hi:[1,1]
	v_pk_add_f32 v[220:221], v[220:221], v[200:201] op_sel:[0,1] op_sel_hi:[1,1]
	v_pk_add_f32 v[222:223], v[222:223], v[200:201] op_sel:[0,1] op_sel_hi:[1,1]
	v_rcp_f32_e32 v216, v216
	v_rcp_f32_e32 v217, v217
	v_rcp_f32_e32 v218, v218
	v_rcp_f32_e32 v219, v219
	v_rcp_f32_e32 v220, v220
	v_rcp_f32_e32 v221, v221
	v_rcp_f32_e32 v222, v222
	v_rcp_f32_e32 v223, v223
	v_cvt_pk_bf16_f32 v244, v216, v217
	v_cvt_pk_bf16_f32 v245, v218, v219
	v_cvt_pk_bf16_f32 v246, v220, v221
	v_cvt_pk_bf16_f32 v247, v222, v223
	v_add_u32_e32 v24, 0xa0, v198
	v_mad_i64_i32 v[24:25], s[36:37], s0, v24, 0
	v_lshl_add_u64 v[24:25], v[24:25], 1, v[164:165]
	s_cmp_gt_i32 s23, 1
	s_mov_b64 s[36:37], -1
	global_store_dwordx4 v[24:25], v[244:247], off
	s_mov_b64 s[36:37], 0
	s_andn2_b64 vcc, exec, s[36:37]
	v_pk_fma_f32 v[204:205], v[40:41], v[48:49], v[56:57] op_sel:[0,1,0]
	v_pk_fma_f32 v[206:207], v[42:43], v[48:49], v[58:59] op_sel:[0,1,0]
	v_pk_fma_f32 v[208:209], v[32:33], v[48:49], v[44:45] op_sel:[0,1,0]
	v_pk_fma_f32 v[210:211], v[34:35], v[48:49], v[46:47] op_sel:[0,1,0]
	v_pk_fma_f32 v[204:205], v[20:21], v[48:49], v[204:205] op_sel_hi:[1,0,1]
	v_pk_fma_f32 v[206:207], v[22:23], v[48:49], v[206:207] op_sel_hi:[1,0,1]
	v_pk_fma_f32 v[208:209], v[16:17], v[48:49], v[208:209] op_sel_hi:[1,0,1]
	v_pk_fma_f32 v[210:211], v[18:19], v[48:49], v[210:211] op_sel_hi:[1,0,1]
	v_pk_mul_f32 v[216:217], v[204:205], v[200:201] op_sel_hi:[1,0]
	v_pk_mul_f32 v[218:219], v[206:207], v[200:201] op_sel_hi:[1,0]
	v_pk_mul_f32 v[220:221], v[208:209], v[200:201] op_sel_hi:[1,0]
	v_pk_mul_f32 v[222:223], v[210:211], v[200:201] op_sel_hi:[1,0]
	v_exp_f32_e32 v216, v216
	v_exp_f32_e32 v217, v217
	v_exp_f32_e32 v218, v218
	v_exp_f32_e32 v219, v219
	v_exp_f32_e32 v220, v220
	v_exp_f32_e32 v221, v221
	v_exp_f32_e32 v222, v222
	v_exp_f32_e32 v223, v223
	v_pk_add_f32 v[216:217], v[216:217], v[200:201] op_sel:[0,1] op_sel_hi:[1,1]
	v_pk_add_f32 v[218:219], v[218:219], v[200:201] op_sel:[0,1] op_sel_hi:[1,1]
	v_pk_add_f32 v[220:221], v[220:221], v[200:201] op_sel:[0,1] op_sel_hi:[1,1]
	v_pk_add_f32 v[222:223], v[222:223], v[200:201] op_sel:[0,1] op_sel_hi:[1,1]
	v_rcp_f32_e32 v216, v216
	v_rcp_f32_e32 v217, v217
	v_rcp_f32_e32 v218, v218
	v_rcp_f32_e32 v219, v219
	v_rcp_f32_e32 v220, v220
	v_rcp_f32_e32 v221, v221
	v_rcp_f32_e32 v222, v222
	v_rcp_f32_e32 v223, v223
	v_cvt_pk_bf16_f32 v248, v216, v217
	v_cvt_pk_bf16_f32 v249, v218, v219
	v_cvt_pk_bf16_f32 v250, v220, v221
	v_cvt_pk_bf16_f32 v251, v222, v223
	global_store_dwordx4 v[24:25], v[248:251], off offset:256
	s_cmp_gt_i32 s23, 1
	s_mov_b64 s[36:37], -1
	s_mov_b64 s[36:37], 0
	s_andn2_b64 vcc, exec, s[36:37]
	v_pk_fma_f32 v[204:205], v[68:69], v[50:51], v[72:73] op_sel:[0,1,0]
	v_pk_fma_f32 v[206:207], v[70:71], v[50:51], v[74:75] op_sel:[0,1,0]
	v_pk_fma_f32 v[208:209], v[60:61], v[50:51], v[64:65] op_sel:[0,1,0]
	v_pk_fma_f32 v[210:211], v[62:63], v[50:51], v[66:67] op_sel:[0,1,0]
	v_pk_fma_f32 v[204:205], v[12:13], v[50:51], v[204:205] op_sel_hi:[1,0,1]
	v_pk_fma_f32 v[206:207], v[14:15], v[50:51], v[206:207] op_sel_hi:[1,0,1]
	v_pk_fma_f32 v[208:209], v[8:9], v[50:51], v[208:209] op_sel_hi:[1,0,1]
	v_pk_fma_f32 v[210:211], v[10:11], v[50:51], v[210:211] op_sel_hi:[1,0,1]
	v_pk_mul_f32 v[216:217], v[204:205], v[200:201] op_sel_hi:[1,0]
	v_pk_mul_f32 v[218:219], v[206:207], v[200:201] op_sel_hi:[1,0]
	v_pk_mul_f32 v[220:221], v[208:209], v[200:201] op_sel_hi:[1,0]
	v_pk_mul_f32 v[222:223], v[210:211], v[200:201] op_sel_hi:[1,0]
	v_exp_f32_e32 v216, v216
	v_exp_f32_e32 v217, v217
	v_exp_f32_e32 v218, v218
	v_exp_f32_e32 v219, v219
	v_exp_f32_e32 v220, v220
	v_exp_f32_e32 v221, v221
	v_exp_f32_e32 v222, v222
	v_exp_f32_e32 v223, v223
	v_pk_add_f32 v[216:217], v[216:217], v[200:201] op_sel:[0,1] op_sel_hi:[1,1]
	v_pk_add_f32 v[218:219], v[218:219], v[200:201] op_sel:[0,1] op_sel_hi:[1,1]
	v_pk_add_f32 v[220:221], v[220:221], v[200:201] op_sel:[0,1] op_sel_hi:[1,1]
	v_pk_add_f32 v[222:223], v[222:223], v[200:201] op_sel:[0,1] op_sel_hi:[1,1]
	v_rcp_f32_e32 v216, v216
	v_rcp_f32_e32 v217, v217
	v_rcp_f32_e32 v218, v218
	v_rcp_f32_e32 v219, v219
	v_rcp_f32_e32 v220, v220
	v_rcp_f32_e32 v221, v221
	v_rcp_f32_e32 v222, v222
	v_rcp_f32_e32 v223, v223
	v_cvt_pk_bf16_f32 v224, v216, v217
	v_cvt_pk_bf16_f32 v225, v218, v219
	v_cvt_pk_bf16_f32 v226, v220, v221
	v_cvt_pk_bf16_f32 v227, v222, v223
	v_add_u32_e32 v8, 0xb0, v198
	v_mad_i64_i32 v[8:9], s[36:37], s0, v8, 0
	v_lshl_add_u64 v[8:9], v[8:9], 1, v[164:165]
	global_store_dwordx4 v[8:9], v[224:227], off
	s_cmp_gt_i32 s23, 1
	s_mov_b64 s[36:37], -1
	s_mov_b64 s[36:37], 0
	s_andn2_b64 vcc, exec, s[36:37]
	s_andn2_b64 vcc, exec, s[10:11]
	s_mov_b64 s[10:11], -1
	v_pk_fma_f32 v[204:205], v[40:41], v[50:51], v[56:57] op_sel:[0,1,0]
	v_pk_fma_f32 v[206:207], v[42:43], v[50:51], v[58:59] op_sel:[0,1,0]
	v_pk_fma_f32 v[208:209], v[32:33], v[50:51], v[44:45] op_sel:[0,1,0]
	v_pk_fma_f32 v[210:211], v[34:35], v[50:51], v[46:47] op_sel:[0,1,0]
	v_pk_fma_f32 v[204:205], v[4:5], v[50:51], v[204:205] op_sel_hi:[1,0,1]
	v_pk_fma_f32 v[206:207], v[6:7], v[50:51], v[206:207] op_sel_hi:[1,0,1]
	v_pk_fma_f32 v[208:209], v[0:1], v[50:51], v[208:209] op_sel_hi:[1,0,1]
	v_pk_fma_f32 v[210:211], v[2:3], v[50:51], v[210:211] op_sel_hi:[1,0,1]
	v_pk_mul_f32 v[216:217], v[204:205], v[200:201] op_sel_hi:[1,0]
	v_pk_mul_f32 v[218:219], v[206:207], v[200:201] op_sel_hi:[1,0]
	v_pk_mul_f32 v[220:221], v[208:209], v[200:201] op_sel_hi:[1,0]
	v_pk_mul_f32 v[222:223], v[210:211], v[200:201] op_sel_hi:[1,0]
	v_exp_f32_e32 v216, v216
	v_exp_f32_e32 v217, v217
	v_exp_f32_e32 v218, v218
	v_exp_f32_e32 v219, v219
	v_exp_f32_e32 v220, v220
	v_exp_f32_e32 v221, v221
	v_exp_f32_e32 v222, v222
	v_exp_f32_e32 v223, v223
	v_pk_add_f32 v[216:217], v[216:217], v[200:201] op_sel:[0,1] op_sel_hi:[1,1]
	v_pk_add_f32 v[218:219], v[218:219], v[200:201] op_sel:[0,1] op_sel_hi:[1,1]
	v_pk_add_f32 v[220:221], v[220:221], v[200:201] op_sel:[0,1] op_sel_hi:[1,1]
	v_pk_add_f32 v[222:223], v[222:223], v[200:201] op_sel:[0,1] op_sel_hi:[1,1]
	v_rcp_f32_e32 v216, v216
	v_rcp_f32_e32 v217, v217
	v_rcp_f32_e32 v218, v218
	v_rcp_f32_e32 v219, v219
	v_rcp_f32_e32 v220, v220
	v_rcp_f32_e32 v221, v221
	v_rcp_f32_e32 v222, v222
	v_rcp_f32_e32 v223, v223
	v_cvt_pk_bf16_f32 v228, v216, v217
	v_cvt_pk_bf16_f32 v229, v218, v219
	v_cvt_pk_bf16_f32 v230, v220, v221
	v_cvt_pk_bf16_f32 v231, v222, v223
	global_store_dwordx4 v[8:9], v[228:231], off offset:256
